# phases 3,8: third register staging set (loads 3 k-tiles ahead)
# baseline (speedup 1.0000x reference)
.LBB0_300:
	s_and_b32 s12, s17, 0x1ffffc0
	s_lshl_b32 s14, s17, 3
	s_and_b32 s14, s14, 56
	s_or_b32 s12, s12, s3
	s_or_b32 s12, s12, s14
	s_lshl_b32 s12, s12, 7
	s_lshl_b64 s[26:27], s[12:13], 11
	v_lshl_add_u64 v[74:75], v[70:71], 0, s[26:27]
	v_add_co_u32_e32 v78, vcc, s20, v74
	s_lshl_b32 s14, s17, 4
	s_nop 0
	v_addc_co_u32_e32 v79, vcc, 0, v75, vcc
	v_add_co_u32_e32 v80, vcc, s21, v74
	s_and_b32 s14, s14, 0x380
	s_nop 0
	v_addc_co_u32_e32 v81, vcc, 0, v75, vcc
	v_add_co_u32_e32 v82, vcc, s22, v74
	s_lshl_b32 s12, s14, 11
	s_nop 0
	v_addc_co_u32_e32 v83, vcc, 0, v75, vcc
	v_lshl_add_u64 v[76:77], v[72:73], 0, s[12:13]
	global_load_dwordx4 v[2:5], v[74:75], off
	global_load_dwordx4 v[6:9], v[78:79], off
	global_load_dwordx4 v[10:13], v[80:81], off
	global_load_dwordx4 v[14:17], v[82:83], off
	global_load_dwordx4 v[18:21], v[76:77], off
	v_add_co_u32_e32 v84, vcc, s20, v76
	s_nop 1
	v_addc_co_u32_e32 v85, vcc, 0, v77, vcc
	v_add_co_u32_e32 v86, vcc, s21, v76
	global_load_dwordx4 v[22:25], v[84:85], off
	s_nop 0
	v_addc_co_u32_e32 v87, vcc, 0, v77, vcc
	global_load_dwordx4 v[26:29], v[86:87], off
	v_add_co_u32_e32 v88, vcc, s22, v76
	s_nop 1
	v_addc_co_u32_e32 v89, vcc, 0, v77, vcc
	global_load_dwordx4 v[30:33], v[88:89], off
	global_load_dwordx4 v[112:115], v[74:75], off offset:128
	global_load_dwordx4 v[116:119], v[76:77], off offset:128
	global_load_dwordx4 v[120:123], v[78:79], off offset:128
	global_load_dwordx4 v[124:127], v[80:81], off offset:128
	global_load_dwordx4 v[128:131], v[82:83], off offset:128
	global_load_dwordx4 v[132:135], v[84:85], off offset:128
	global_load_dwordx4 v[136:139], v[86:87], off offset:128
	global_load_dwordx4 v[140:143], v[88:89], off offset:128
	s_waitcnt vmcnt(15)
	ds_write_b128 v90, v[2:5]
	s_waitcnt vmcnt(11)
	ds_write_b128 v90, v[18:21] offset:36864
	ds_write_b128 v90, v[6:9] offset:4608
	ds_write_b128 v90, v[10:13] offset:9216
	ds_write_b128 v90, v[14:17] offset:13824
	s_waitcnt vmcnt(10)
	ds_write_b128 v90, v[22:25] offset:41472
	s_waitcnt vmcnt(9)
	ds_write_b128 v90, v[26:29] offset:46080
	s_waitcnt vmcnt(8)
	ds_write_b128 v90, v[30:33] offset:50688
	s_waitcnt lgkmcnt(0)
	s_barrier
	global_load_dwordx4 v[152:155], v[78:79], off offset:256
	global_load_dwordx4 v[156:159], v[80:81], off offset:256
	global_load_dwordx4 v[144:147], v[74:75], off offset:256
	global_load_dwordx4 v[148:151], v[76:77], off offset:256
	global_load_dwordx4 v[160:163], v[82:83], off offset:256
	global_load_dwordx4 v[164:167], v[84:85], off offset:256
	global_load_dwordx4 v[168:171], v[86:87], off offset:256
	global_load_dwordx4 v[172:175], v[88:89], off offset:256
	global_load_dwordx4 v[212:215], v[78:79], off offset:384
	global_load_dwordx4 v[216:219], v[80:81], off offset:384
	global_load_dwordx4 v[204:207], v[74:75], off offset:384
	global_load_dwordx4 v[208:211], v[76:77], off offset:384
	global_load_dwordx4 v[220:223], v[82:83], off offset:384
	global_load_dwordx4 v[224:227], v[84:85], off offset:384
	global_load_dwordx4 v[228:231], v[86:87], off offset:384
	global_load_dwordx4 v[232:235], v[88:89], off offset:384
	ds_read_b128 v[18:21], v66
	ds_read_b128 v[34:37], v67 offset:36864
	ds_read_b128 v[176:179], v66 offset:32
	ds_read_b128 v[180:183], v67 offset:36896
	ds_read_b128 v[50:53], v67 offset:41472
	ds_read_b128 v[184:187], v67 offset:41504
	ds_read_b128 v[54:57], v66 offset:4608
	ds_read_b128 v[188:191], v66 offset:4640
	s_waitcnt lgkmcnt(6)
	v_mfma_f32_32x32x16_bf16 v[2:17], v[18:21], v[34:37], 0
	s_waitcnt lgkmcnt(3)
	v_mfma_f32_32x32x16_bf16 v[18:33], v[18:21], v[50:53], 0
	s_waitcnt lgkmcnt(1)
	v_mfma_f32_32x32x16_bf16 v[34:49], v[54:57], v[34:37], 0
	v_mfma_f32_32x32x16_bf16 v[50:65], v[54:57], v[50:53], 0
	v_mfma_f32_32x32x16_bf16 v[2:17], v[176:179], v[180:183], v[2:17]
	v_mfma_f32_32x32x16_bf16 v[18:33], v[176:179], v[184:187], v[18:33]
	s_waitcnt lgkmcnt(0)
	v_mfma_f32_32x32x16_bf16 v[34:49], v[188:191], v[180:183], v[34:49]
	v_mfma_f32_32x32x16_bf16 v[50:65], v[188:191], v[184:187], v[50:65]
	ds_read_b128 v[176:179], v66 offset:64
	ds_read_b128 v[180:183], v67 offset:36928
	ds_read_b128 v[184:187], v66 offset:96
	ds_read_b128 v[188:191], v67 offset:36960
	ds_read_b128 v[192:195], v67 offset:41536
	ds_read_b128 v[196:199], v67 offset:41568
	s_waitcnt lgkmcnt(4)
	v_mfma_f32_32x32x16_bf16 v[2:17], v[176:179], v[180:183], v[2:17]
	s_waitcnt lgkmcnt(1)
	v_mfma_f32_32x32x16_bf16 v[18:33], v[176:179], v[192:195], v[18:33]
	ds_read_b128 v[176:179], v66 offset:4672
	ds_read_b128 v[200:203], v66 offset:4704
	s_waitcnt vmcnt(16)
	ds_write_b128 v90, v[112:115] offset:18432
	ds_write_b128 v90, v[120:123] offset:23040
	ds_write_b128 v90, v[124:127] offset:27648
	ds_write_b128 v90, v[128:131] offset:32256
	ds_write_b128 v90, v[116:119] offset:55296
	ds_write_b128 v90, v[132:135] offset:59904
	ds_write_b128 v90, v[136:139] offset:64512
	ds_write_b128 v91, v[140:143] offset:32256
	global_load_dwordx4 v[120:123], v[78:79], off offset:512
	global_load_dwordx4 v[124:127], v[80:81], off offset:512
	global_load_dwordx4 v[112:115], v[74:75], off offset:512
	global_load_dwordx4 v[116:119], v[76:77], off offset:512
	global_load_dwordx4 v[128:131], v[82:83], off offset:512
	global_load_dwordx4 v[132:135], v[84:85], off offset:512
	global_load_dwordx4 v[136:139], v[86:87], off offset:512
	global_load_dwordx4 v[140:143], v[88:89], off offset:512
	s_waitcnt lgkmcnt(0)
	s_barrier
	v_mfma_f32_32x32x16_bf16 v[34:49], v[176:179], v[180:183], v[34:49]
	v_mfma_f32_32x32x16_bf16 v[50:65], v[176:179], v[192:195], v[50:65]
	v_mfma_f32_32x32x16_bf16 v[2:17], v[184:187], v[188:191], v[2:17]
	v_mfma_f32_32x32x16_bf16 v[18:33], v[184:187], v[196:199], v[18:33]
	v_mfma_f32_32x32x16_bf16 v[34:49], v[200:203], v[188:191], v[34:49]
	v_mfma_f32_32x32x16_bf16 v[50:65], v[200:203], v[196:199], v[50:65]
	ds_read_b128 v[176:179], v66 offset:18432
	ds_read_b128 v[180:183], v67 offset:55296
	ds_read_b128 v[184:187], v66 offset:18464
	ds_read_b128 v[188:191], v67 offset:55328
	ds_read_b128 v[192:195], v67 offset:59904
	ds_read_b128 v[196:199], v67 offset:59936
	s_waitcnt lgkmcnt(4)
	v_mfma_f32_32x32x16_bf16 v[2:17], v[176:179], v[180:183], v[2:17]
	s_waitcnt lgkmcnt(1)
	v_mfma_f32_32x32x16_bf16 v[18:33], v[176:179], v[192:195], v[18:33]
	ds_read_b128 v[176:179], v66 offset:23040
	ds_read_b128 v[200:203], v66 offset:23072
	s_waitcnt lgkmcnt(1)
	v_mfma_f32_32x32x16_bf16 v[34:49], v[176:179], v[180:183], v[34:49]
	v_mfma_f32_32x32x16_bf16 v[50:65], v[176:179], v[192:195], v[50:65]
	v_mfma_f32_32x32x16_bf16 v[2:17], v[184:187], v[188:191], v[2:17]
	v_mfma_f32_32x32x16_bf16 v[18:33], v[184:187], v[196:199], v[18:33]
	s_waitcnt lgkmcnt(0)
	v_mfma_f32_32x32x16_bf16 v[34:49], v[200:203], v[188:191], v[34:49]
	ds_read_b128 v[176:179], v66 offset:18496
	ds_read_b128 v[180:183], v67 offset:55360
	ds_read_b128 v[184:187], v66 offset:18528
	ds_read_b128 v[188:191], v67 offset:55392
	v_mfma_f32_32x32x16_bf16 v[50:65], v[200:203], v[196:199], v[50:65]
	ds_read_b128 v[192:195], v67 offset:59968
	ds_read_b128 v[196:199], v67 offset:60000
	s_waitcnt lgkmcnt(4)
	v_mfma_f32_32x32x16_bf16 v[2:17], v[176:179], v[180:183], v[2:17]
	s_waitcnt lgkmcnt(1)
	v_mfma_f32_32x32x16_bf16 v[18:33], v[176:179], v[192:195], v[18:33]
	ds_read_b128 v[176:179], v66 offset:23104
	ds_read_b128 v[200:203], v66 offset:23136
	s_waitcnt vmcnt(16)
	ds_write_b128 v90, v[144:147]
	ds_write_b128 v90, v[152:155] offset:4608
	ds_write_b128 v90, v[156:159] offset:9216
	ds_write_b128 v90, v[160:163] offset:13824
	ds_write_b128 v90, v[148:151] offset:36864
	ds_write_b128 v90, v[164:167] offset:41472
	ds_write_b128 v90, v[168:171] offset:46080
	ds_write_b128 v90, v[172:175] offset:50688
	global_load_dwordx4 v[152:155], v[78:79], off offset:640
	global_load_dwordx4 v[156:159], v[80:81], off offset:640
	global_load_dwordx4 v[144:147], v[74:75], off offset:640
	global_load_dwordx4 v[148:151], v[76:77], off offset:640
	global_load_dwordx4 v[160:163], v[82:83], off offset:640
	global_load_dwordx4 v[164:167], v[84:85], off offset:640
	global_load_dwordx4 v[168:171], v[86:87], off offset:640
	global_load_dwordx4 v[172:175], v[88:89], off offset:640
	s_waitcnt lgkmcnt(0)
	s_barrier
	v_mfma_f32_32x32x16_bf16 v[34:49], v[176:179], v[180:183], v[34:49]
	v_mfma_f32_32x32x16_bf16 v[50:65], v[176:179], v[192:195], v[50:65]
	v_mfma_f32_32x32x16_bf16 v[2:17], v[184:187], v[188:191], v[2:17]
	v_mfma_f32_32x32x16_bf16 v[18:33], v[184:187], v[196:199], v[18:33]
	v_mfma_f32_32x32x16_bf16 v[34:49], v[200:203], v[188:191], v[34:49]
	v_mfma_f32_32x32x16_bf16 v[50:65], v[200:203], v[196:199], v[50:65]
	ds_read_b128 v[176:179], v66
	ds_read_b128 v[180:183], v67 offset:36864
	ds_read_b128 v[184:187], v66 offset:32
	ds_read_b128 v[188:191], v67 offset:36896
	ds_read_b128 v[192:195], v67 offset:41472
	ds_read_b128 v[196:199], v67 offset:41504
	s_waitcnt lgkmcnt(4)
	v_mfma_f32_32x32x16_bf16 v[2:17], v[176:179], v[180:183], v[2:17]
	s_waitcnt lgkmcnt(1)
	v_mfma_f32_32x32x16_bf16 v[18:33], v[176:179], v[192:195], v[18:33]
	ds_read_b128 v[176:179], v66 offset:4608
	ds_read_b128 v[200:203], v66 offset:4640
	s_waitcnt lgkmcnt(1)
	v_mfma_f32_32x32x16_bf16 v[34:49], v[176:179], v[180:183], v[34:49]
	v_mfma_f32_32x32x16_bf16 v[50:65], v[176:179], v[192:195], v[50:65]
	v_mfma_f32_32x32x16_bf16 v[2:17], v[184:187], v[188:191], v[2:17]
	v_mfma_f32_32x32x16_bf16 v[18:33], v[184:187], v[196:199], v[18:33]
	s_waitcnt lgkmcnt(0)
	v_mfma_f32_32x32x16_bf16 v[34:49], v[200:203], v[188:191], v[34:49]
	ds_read_b128 v[176:179], v66 offset:64
	ds_read_b128 v[180:183], v67 offset:36928
	ds_read_b128 v[184:187], v66 offset:96
	ds_read_b128 v[188:191], v67 offset:36960
	v_mfma_f32_32x32x16_bf16 v[50:65], v[200:203], v[196:199], v[50:65]
	ds_read_b128 v[192:195], v67 offset:41536
	ds_read_b128 v[196:199], v67 offset:41568
	s_waitcnt lgkmcnt(4)
	v_mfma_f32_32x32x16_bf16 v[2:17], v[176:179], v[180:183], v[2:17]
	s_waitcnt lgkmcnt(1)
	v_mfma_f32_32x32x16_bf16 v[18:33], v[176:179], v[192:195], v[18:33]
	ds_read_b128 v[176:179], v66 offset:4672
	ds_read_b128 v[200:203], v66 offset:4704
	s_waitcnt vmcnt(16)
	ds_write_b128 v90, v[204:207] offset:18432
	ds_write_b128 v90, v[212:215] offset:23040
	ds_write_b128 v90, v[216:219] offset:27648
	ds_write_b128 v90, v[220:223] offset:32256
	ds_write_b128 v90, v[208:211] offset:55296
	ds_write_b128 v90, v[224:227] offset:59904
	ds_write_b128 v90, v[228:231] offset:64512
	ds_write_b128 v91, v[232:235] offset:32256
	global_load_dwordx4 v[212:215], v[78:79], off offset:768
	global_load_dwordx4 v[216:219], v[80:81], off offset:768
	global_load_dwordx4 v[204:207], v[74:75], off offset:768
	global_load_dwordx4 v[208:211], v[76:77], off offset:768
	global_load_dwordx4 v[220:223], v[82:83], off offset:768
	global_load_dwordx4 v[224:227], v[84:85], off offset:768
	global_load_dwordx4 v[228:231], v[86:87], off offset:768
	global_load_dwordx4 v[232:235], v[88:89], off offset:768
	s_waitcnt lgkmcnt(0)
	s_barrier
	v_mfma_f32_32x32x16_bf16 v[34:49], v[176:179], v[180:183], v[34:49]
	v_mfma_f32_32x32x16_bf16 v[50:65], v[176:179], v[192:195], v[50:65]
	v_mfma_f32_32x32x16_bf16 v[2:17], v[184:187], v[188:191], v[2:17]
	v_mfma_f32_32x32x16_bf16 v[18:33], v[184:187], v[196:199], v[18:33]
	v_mfma_f32_32x32x16_bf16 v[34:49], v[200:203], v[188:191], v[34:49]
	v_mfma_f32_32x32x16_bf16 v[50:65], v[200:203], v[196:199], v[50:65]
	ds_read_b128 v[176:179], v66 offset:18432
	ds_read_b128 v[180:183], v67 offset:55296
	ds_read_b128 v[184:187], v66 offset:18464
	ds_read_b128 v[188:191], v67 offset:55328
	ds_read_b128 v[192:195], v67 offset:59904
	ds_read_b128 v[196:199], v67 offset:59936
	s_waitcnt lgkmcnt(4)
	v_mfma_f32_32x32x16_bf16 v[2:17], v[176:179], v[180:183], v[2:17]
	s_waitcnt lgkmcnt(1)
	v_mfma_f32_32x32x16_bf16 v[18:33], v[176:179], v[192:195], v[18:33]
	ds_read_b128 v[176:179], v66 offset:23040
	ds_read_b128 v[200:203], v66 offset:23072
	s_waitcnt lgkmcnt(1)
	v_mfma_f32_32x32x16_bf16 v[34:49], v[176:179], v[180:183], v[34:49]
	v_mfma_f32_32x32x16_bf16 v[50:65], v[176:179], v[192:195], v[50:65]
	v_mfma_f32_32x32x16_bf16 v[2:17], v[184:187], v[188:191], v[2:17]
	v_mfma_f32_32x32x16_bf16 v[18:33], v[184:187], v[196:199], v[18:33]
	s_waitcnt lgkmcnt(0)
	v_mfma_f32_32x32x16_bf16 v[34:49], v[200:203], v[188:191], v[34:49]
	ds_read_b128 v[176:179], v66 offset:18496
	ds_read_b128 v[180:183], v67 offset:55360
	ds_read_b128 v[184:187], v66 offset:18528
	ds_read_b128 v[188:191], v67 offset:55392
	v_mfma_f32_32x32x16_bf16 v[50:65], v[200:203], v[196:199], v[50:65]
	ds_read_b128 v[192:195], v67 offset:59968
	ds_read_b128 v[196:199], v67 offset:60000
	s_waitcnt lgkmcnt(4)
	v_mfma_f32_32x32x16_bf16 v[2:17], v[176:179], v[180:183], v[2:17]
	s_waitcnt lgkmcnt(1)
	v_mfma_f32_32x32x16_bf16 v[18:33], v[176:179], v[192:195], v[18:33]
	ds_read_b128 v[176:179], v66 offset:23104
	ds_read_b128 v[200:203], v66 offset:23136
	s_waitcnt vmcnt(16)
	ds_write_b128 v90, v[112:115]
	ds_write_b128 v90, v[120:123] offset:4608
	ds_write_b128 v90, v[124:127] offset:9216
	ds_write_b128 v90, v[128:131] offset:13824
	ds_write_b128 v90, v[116:119] offset:36864
	ds_write_b128 v90, v[132:135] offset:41472
	ds_write_b128 v90, v[136:139] offset:46080
	ds_write_b128 v90, v[140:143] offset:50688
	global_load_dwordx4 v[120:123], v[78:79], off offset:896
	global_load_dwordx4 v[124:127], v[80:81], off offset:896
	global_load_dwordx4 v[112:115], v[74:75], off offset:896
	global_load_dwordx4 v[116:119], v[76:77], off offset:896
	global_load_dwordx4 v[128:131], v[82:83], off offset:896
	global_load_dwordx4 v[132:135], v[84:85], off offset:896
	global_load_dwordx4 v[136:139], v[86:87], off offset:896
	global_load_dwordx4 v[140:143], v[88:89], off offset:896
	s_waitcnt lgkmcnt(0)
	s_barrier
	v_mfma_f32_32x32x16_bf16 v[34:49], v[176:179], v[180:183], v[34:49]
	v_mfma_f32_32x32x16_bf16 v[50:65], v[176:179], v[192:195], v[50:65]
	v_mfma_f32_32x32x16_bf16 v[2:17], v[184:187], v[188:191], v[2:17]
	v_mfma_f32_32x32x16_bf16 v[18:33], v[184:187], v[196:199], v[18:33]
	v_mfma_f32_32x32x16_bf16 v[34:49], v[200:203], v[188:191], v[34:49]
	v_mfma_f32_32x32x16_bf16 v[50:65], v[200:203], v[196:199], v[50:65]
	ds_read_b128 v[176:179], v66
	ds_read_b128 v[180:183], v67 offset:36864
	ds_read_b128 v[184:187], v66 offset:32
	ds_read_b128 v[188:191], v67 offset:36896
	ds_read_b128 v[192:195], v67 offset:41472
	ds_read_b128 v[196:199], v67 offset:41504
	s_waitcnt lgkmcnt(4)
	v_mfma_f32_32x32x16_bf16 v[2:17], v[176:179], v[180:183], v[2:17]
	s_waitcnt lgkmcnt(1)
	v_mfma_f32_32x32x16_bf16 v[18:33], v[176:179], v[192:195], v[18:33]
	ds_read_b128 v[176:179], v66 offset:4608
	ds_read_b128 v[200:203], v66 offset:4640
	s_waitcnt lgkmcnt(1)
	v_mfma_f32_32x32x16_bf16 v[34:49], v[176:179], v[180:183], v[34:49]
	v_mfma_f32_32x32x16_bf16 v[50:65], v[176:179], v[192:195], v[50:65]
	v_mfma_f32_32x32x16_bf16 v[2:17], v[184:187], v[188:191], v[2:17]
	v_mfma_f32_32x32x16_bf16 v[18:33], v[184:187], v[196:199], v[18:33]
	s_waitcnt lgkmcnt(0)
	v_mfma_f32_32x32x16_bf16 v[34:49], v[200:203], v[188:191], v[34:49]
	ds_read_b128 v[176:179], v66 offset:64
	ds_read_b128 v[180:183], v67 offset:36928
	ds_read_b128 v[184:187], v66 offset:96
	ds_read_b128 v[188:191], v67 offset:36960
	v_mfma_f32_32x32x16_bf16 v[50:65], v[200:203], v[196:199], v[50:65]
	ds_read_b128 v[192:195], v67 offset:41536
	ds_read_b128 v[196:199], v67 offset:41568
	s_waitcnt lgkmcnt(4)
	v_mfma_f32_32x32x16_bf16 v[2:17], v[176:179], v[180:183], v[2:17]
	s_waitcnt lgkmcnt(1)
	v_mfma_f32_32x32x16_bf16 v[18:33], v[176:179], v[192:195], v[18:33]
	ds_read_b128 v[176:179], v66 offset:4672
	ds_read_b128 v[200:203], v66 offset:4704
	s_waitcnt vmcnt(16)
	ds_write_b128 v90, v[144:147] offset:18432
	ds_write_b128 v90, v[152:155] offset:23040
	ds_write_b128 v90, v[156:159] offset:27648
	ds_write_b128 v90, v[160:163] offset:32256
	ds_write_b128 v90, v[148:151] offset:55296
	ds_write_b128 v90, v[164:167] offset:59904
	ds_write_b128 v90, v[168:171] offset:64512
	ds_write_b128 v91, v[172:175] offset:32256
	global_load_dwordx4 v[152:155], v[78:79], off offset:1024
	global_load_dwordx4 v[156:159], v[80:81], off offset:1024
	global_load_dwordx4 v[144:147], v[74:75], off offset:1024
	global_load_dwordx4 v[148:151], v[76:77], off offset:1024
	global_load_dwordx4 v[160:163], v[82:83], off offset:1024
	global_load_dwordx4 v[164:167], v[84:85], off offset:1024
	global_load_dwordx4 v[168:171], v[86:87], off offset:1024
	global_load_dwordx4 v[172:175], v[88:89], off offset:1024
	s_waitcnt lgkmcnt(0)
	s_barrier
	v_mfma_f32_32x32x16_bf16 v[34:49], v[176:179], v[180:183], v[34:49]
	v_mfma_f32_32x32x16_bf16 v[50:65], v[176:179], v[192:195], v[50:65]
	v_mfma_f32_32x32x16_bf16 v[2:17], v[184:187], v[188:191], v[2:17]
	v_mfma_f32_32x32x16_bf16 v[18:33], v[184:187], v[196:199], v[18:33]
	v_mfma_f32_32x32x16_bf16 v[34:49], v[200:203], v[188:191], v[34:49]
	v_mfma_f32_32x32x16_bf16 v[50:65], v[200:203], v[196:199], v[50:65]
	ds_read_b128 v[176:179], v66 offset:18432
	ds_read_b128 v[180:183], v67 offset:55296
	ds_read_b128 v[184:187], v66 offset:18464
	ds_read_b128 v[188:191], v67 offset:55328
	ds_read_b128 v[192:195], v67 offset:59904
	ds_read_b128 v[196:199], v67 offset:59936
	s_waitcnt lgkmcnt(4)
	v_mfma_f32_32x32x16_bf16 v[2:17], v[176:179], v[180:183], v[2:17]
	s_waitcnt lgkmcnt(1)
	v_mfma_f32_32x32x16_bf16 v[18:33], v[176:179], v[192:195], v[18:33]
	ds_read_b128 v[176:179], v66 offset:23040
	ds_read_b128 v[200:203], v66 offset:23072
	s_waitcnt lgkmcnt(1)
	v_mfma_f32_32x32x16_bf16 v[34:49], v[176:179], v[180:183], v[34:49]
	v_mfma_f32_32x32x16_bf16 v[50:65], v[176:179], v[192:195], v[50:65]
	v_mfma_f32_32x32x16_bf16 v[2:17], v[184:187], v[188:191], v[2:17]
	v_mfma_f32_32x32x16_bf16 v[18:33], v[184:187], v[196:199], v[18:33]
	s_waitcnt lgkmcnt(0)
	v_mfma_f32_32x32x16_bf16 v[34:49], v[200:203], v[188:191], v[34:49]
	ds_read_b128 v[176:179], v66 offset:18496
	ds_read_b128 v[180:183], v67 offset:55360
	ds_read_b128 v[184:187], v66 offset:18528
	ds_read_b128 v[188:191], v67 offset:55392
	v_mfma_f32_32x32x16_bf16 v[50:65], v[200:203], v[196:199], v[50:65]
	ds_read_b128 v[192:195], v67 offset:59968
	ds_read_b128 v[196:199], v67 offset:60000
	s_waitcnt lgkmcnt(4)
	v_mfma_f32_32x32x16_bf16 v[2:17], v[176:179], v[180:183], v[2:17]
	s_waitcnt lgkmcnt(1)
	v_mfma_f32_32x32x16_bf16 v[18:33], v[176:179], v[192:195], v[18:33]
	ds_read_b128 v[176:179], v66 offset:23104
	ds_read_b128 v[200:203], v66 offset:23136
	s_waitcnt vmcnt(16)
	ds_write_b128 v90, v[204:207]
	ds_write_b128 v90, v[212:215] offset:4608
	ds_write_b128 v90, v[216:219] offset:9216
	ds_write_b128 v90, v[220:223] offset:13824
	ds_write_b128 v90, v[208:211] offset:36864
	ds_write_b128 v90, v[224:227] offset:41472
	ds_write_b128 v90, v[228:231] offset:46080
	ds_write_b128 v90, v[232:235] offset:50688
	global_load_dwordx4 v[212:215], v[78:79], off offset:1152
	global_load_dwordx4 v[216:219], v[80:81], off offset:1152
	global_load_dwordx4 v[204:207], v[74:75], off offset:1152
	global_load_dwordx4 v[208:211], v[76:77], off offset:1152
	global_load_dwordx4 v[220:223], v[82:83], off offset:1152
	global_load_dwordx4 v[224:227], v[84:85], off offset:1152
	global_load_dwordx4 v[228:231], v[86:87], off offset:1152
	global_load_dwordx4 v[232:235], v[88:89], off offset:1152
	s_waitcnt lgkmcnt(0)
	s_barrier
	v_mfma_f32_32x32x16_bf16 v[34:49], v[176:179], v[180:183], v[34:49]
	v_mfma_f32_32x32x16_bf16 v[50:65], v[176:179], v[192:195], v[50:65]
	v_mfma_f32_32x32x16_bf16 v[2:17], v[184:187], v[188:191], v[2:17]
	v_mfma_f32_32x32x16_bf16 v[18:33], v[184:187], v[196:199], v[18:33]
	v_mfma_f32_32x32x16_bf16 v[34:49], v[200:203], v[188:191], v[34:49]
	v_mfma_f32_32x32x16_bf16 v[50:65], v[200:203], v[196:199], v[50:65]
	ds_read_b128 v[176:179], v66
	ds_read_b128 v[180:183], v67 offset:36864
	ds_read_b128 v[184:187], v66 offset:32
	ds_read_b128 v[188:191], v67 offset:36896
	ds_read_b128 v[192:195], v67 offset:41472
	ds_read_b128 v[196:199], v67 offset:41504
	s_waitcnt lgkmcnt(4)
	v_mfma_f32_32x32x16_bf16 v[2:17], v[176:179], v[180:183], v[2:17]
	s_waitcnt lgkmcnt(1)
	v_mfma_f32_32x32x16_bf16 v[18:33], v[176:179], v[192:195], v[18:33]
	ds_read_b128 v[176:179], v66 offset:4608
	ds_read_b128 v[200:203], v66 offset:4640
	s_waitcnt lgkmcnt(1)
	v_mfma_f32_32x32x16_bf16 v[34:49], v[176:179], v[180:183], v[34:49]
	v_mfma_f32_32x32x16_bf16 v[50:65], v[176:179], v[192:195], v[50:65]
	v_mfma_f32_32x32x16_bf16 v[2:17], v[184:187], v[188:191], v[2:17]
	v_mfma_f32_32x32x16_bf16 v[18:33], v[184:187], v[196:199], v[18:33]
	s_waitcnt lgkmcnt(0)
	v_mfma_f32_32x32x16_bf16 v[34:49], v[200:203], v[188:191], v[34:49]
	ds_read_b128 v[176:179], v66 offset:64
	ds_read_b128 v[180:183], v67 offset:36928
	ds_read_b128 v[184:187], v66 offset:96
	ds_read_b128 v[188:191], v67 offset:36960
	v_mfma_f32_32x32x16_bf16 v[50:65], v[200:203], v[196:199], v[50:65]
	ds_read_b128 v[192:195], v67 offset:41536
	ds_read_b128 v[196:199], v67 offset:41568
	s_waitcnt lgkmcnt(4)
	v_mfma_f32_32x32x16_bf16 v[2:17], v[176:179], v[180:183], v[2:17]
	s_waitcnt lgkmcnt(1)
	v_mfma_f32_32x32x16_bf16 v[18:33], v[176:179], v[192:195], v[18:33]
	ds_read_b128 v[176:179], v66 offset:4672
	ds_read_b128 v[200:203], v66 offset:4704
	s_waitcnt vmcnt(16)
	ds_write_b128 v90, v[112:115] offset:18432
	ds_write_b128 v90, v[120:123] offset:23040
	ds_write_b128 v90, v[124:127] offset:27648
	ds_write_b128 v90, v[128:131] offset:32256
	ds_write_b128 v90, v[116:119] offset:55296
	ds_write_b128 v90, v[132:135] offset:59904
	ds_write_b128 v90, v[136:139] offset:64512
	ds_write_b128 v91, v[140:143] offset:32256
	global_load_dwordx4 v[120:123], v[78:79], off offset:1280
	global_load_dwordx4 v[124:127], v[80:81], off offset:1280
	global_load_dwordx4 v[112:115], v[74:75], off offset:1280
	global_load_dwordx4 v[116:119], v[76:77], off offset:1280
	global_load_dwordx4 v[128:131], v[82:83], off offset:1280
	global_load_dwordx4 v[132:135], v[84:85], off offset:1280
	global_load_dwordx4 v[136:139], v[86:87], off offset:1280
	global_load_dwordx4 v[140:143], v[88:89], off offset:1280
	s_waitcnt lgkmcnt(0)
	s_barrier
	v_mfma_f32_32x32x16_bf16 v[34:49], v[176:179], v[180:183], v[34:49]
	v_mfma_f32_32x32x16_bf16 v[50:65], v[176:179], v[192:195], v[50:65]
	v_mfma_f32_32x32x16_bf16 v[2:17], v[184:187], v[188:191], v[2:17]
	v_mfma_f32_32x32x16_bf16 v[18:33], v[184:187], v[196:199], v[18:33]
	v_mfma_f32_32x32x16_bf16 v[34:49], v[200:203], v[188:191], v[34:49]
	v_mfma_f32_32x32x16_bf16 v[50:65], v[200:203], v[196:199], v[50:65]
	ds_read_b128 v[176:179], v66 offset:18432
	ds_read_b128 v[180:183], v67 offset:55296
	ds_read_b128 v[184:187], v66 offset:18464
	ds_read_b128 v[188:191], v67 offset:55328
	ds_read_b128 v[192:195], v67 offset:59904
	ds_read_b128 v[196:199], v67 offset:59936
	s_waitcnt lgkmcnt(4)
	v_mfma_f32_32x32x16_bf16 v[2:17], v[176:179], v[180:183], v[2:17]
	s_waitcnt lgkmcnt(1)
	v_mfma_f32_32x32x16_bf16 v[18:33], v[176:179], v[192:195], v[18:33]
	ds_read_b128 v[176:179], v66 offset:23040
	ds_read_b128 v[200:203], v66 offset:23072
	s_waitcnt lgkmcnt(1)
	v_mfma_f32_32x32x16_bf16 v[34:49], v[176:179], v[180:183], v[34:49]
	v_mfma_f32_32x32x16_bf16 v[50:65], v[176:179], v[192:195], v[50:65]
	v_mfma_f32_32x32x16_bf16 v[2:17], v[184:187], v[188:191], v[2:17]
	v_mfma_f32_32x32x16_bf16 v[18:33], v[184:187], v[196:199], v[18:33]
	s_waitcnt lgkmcnt(0)
	v_mfma_f32_32x32x16_bf16 v[34:49], v[200:203], v[188:191], v[34:49]
	ds_read_b128 v[176:179], v66 offset:18496
	ds_read_b128 v[180:183], v67 offset:55360
	ds_read_b128 v[184:187], v66 offset:18528
	ds_read_b128 v[188:191], v67 offset:55392
	v_mfma_f32_32x32x16_bf16 v[50:65], v[200:203], v[196:199], v[50:65]
	ds_read_b128 v[192:195], v67 offset:59968
	ds_read_b128 v[196:199], v67 offset:60000
	s_waitcnt lgkmcnt(4)
	v_mfma_f32_32x32x16_bf16 v[2:17], v[176:179], v[180:183], v[2:17]
	s_waitcnt lgkmcnt(1)
	v_mfma_f32_32x32x16_bf16 v[18:33], v[176:179], v[192:195], v[18:33]
	ds_read_b128 v[176:179], v66 offset:23104
	ds_read_b128 v[200:203], v66 offset:23136
	s_waitcnt vmcnt(16)
	ds_write_b128 v90, v[144:147]
	ds_write_b128 v90, v[152:155] offset:4608
	ds_write_b128 v90, v[156:159] offset:9216
	ds_write_b128 v90, v[160:163] offset:13824
	ds_write_b128 v90, v[148:151] offset:36864
	ds_write_b128 v90, v[164:167] offset:41472
	ds_write_b128 v90, v[168:171] offset:46080
	ds_write_b128 v90, v[172:175] offset:50688
	global_load_dwordx4 v[152:155], v[78:79], off offset:1408
	global_load_dwordx4 v[156:159], v[80:81], off offset:1408
	global_load_dwordx4 v[144:147], v[74:75], off offset:1408
	global_load_dwordx4 v[148:151], v[76:77], off offset:1408
	global_load_dwordx4 v[160:163], v[82:83], off offset:1408
	global_load_dwordx4 v[164:167], v[84:85], off offset:1408
	global_load_dwordx4 v[168:171], v[86:87], off offset:1408
	global_load_dwordx4 v[172:175], v[88:89], off offset:1408
	s_waitcnt lgkmcnt(0)
	s_barrier
	v_mfma_f32_32x32x16_bf16 v[34:49], v[176:179], v[180:183], v[34:49]
	v_mfma_f32_32x32x16_bf16 v[50:65], v[176:179], v[192:195], v[50:65]
	v_mfma_f32_32x32x16_bf16 v[2:17], v[184:187], v[188:191], v[2:17]
	v_mfma_f32_32x32x16_bf16 v[18:33], v[184:187], v[196:199], v[18:33]
	v_mfma_f32_32x32x16_bf16 v[34:49], v[200:203], v[188:191], v[34:49]
	v_mfma_f32_32x32x16_bf16 v[50:65], v[200:203], v[196:199], v[50:65]
	ds_read_b128 v[176:179], v66
	ds_read_b128 v[180:183], v67 offset:36864
	ds_read_b128 v[184:187], v66 offset:32
	ds_read_b128 v[188:191], v67 offset:36896
	ds_read_b128 v[192:195], v67 offset:41472
	ds_read_b128 v[196:199], v67 offset:41504
	s_waitcnt lgkmcnt(4)
	v_mfma_f32_32x32x16_bf16 v[2:17], v[176:179], v[180:183], v[2:17]
	s_waitcnt lgkmcnt(1)
	v_mfma_f32_32x32x16_bf16 v[18:33], v[176:179], v[192:195], v[18:33]
	ds_read_b128 v[176:179], v66 offset:4608
	ds_read_b128 v[200:203], v66 offset:4640
	s_waitcnt lgkmcnt(1)
	v_mfma_f32_32x32x16_bf16 v[34:49], v[176:179], v[180:183], v[34:49]
	v_mfma_f32_32x32x16_bf16 v[50:65], v[176:179], v[192:195], v[50:65]
	v_mfma_f32_32x32x16_bf16 v[2:17], v[184:187], v[188:191], v[2:17]
	v_mfma_f32_32x32x16_bf16 v[18:33], v[184:187], v[196:199], v[18:33]
	s_waitcnt lgkmcnt(0)
	v_mfma_f32_32x32x16_bf16 v[34:49], v[200:203], v[188:191], v[34:49]
	ds_read_b128 v[176:179], v66 offset:64
	ds_read_b128 v[180:183], v67 offset:36928
	ds_read_b128 v[184:187], v66 offset:96
	ds_read_b128 v[188:191], v67 offset:36960
	v_mfma_f32_32x32x16_bf16 v[50:65], v[200:203], v[196:199], v[50:65]
	ds_read_b128 v[192:195], v67 offset:41536
	ds_read_b128 v[196:199], v67 offset:41568
	s_waitcnt lgkmcnt(4)
	v_mfma_f32_32x32x16_bf16 v[2:17], v[176:179], v[180:183], v[2:17]
	s_waitcnt lgkmcnt(1)
	v_mfma_f32_32x32x16_bf16 v[18:33], v[176:179], v[192:195], v[18:33]
	ds_read_b128 v[176:179], v66 offset:4672
	ds_read_b128 v[200:203], v66 offset:4704
	s_waitcnt vmcnt(16)
	ds_write_b128 v90, v[204:207] offset:18432
	ds_write_b128 v90, v[212:215] offset:23040
	ds_write_b128 v90, v[216:219] offset:27648
	ds_write_b128 v90, v[220:223] offset:32256
	ds_write_b128 v90, v[208:211] offset:55296
	ds_write_b128 v90, v[224:227] offset:59904
	ds_write_b128 v90, v[228:231] offset:64512
	ds_write_b128 v91, v[232:235] offset:32256
	global_load_dwordx4 v[212:215], v[78:79], off offset:1536
	global_load_dwordx4 v[216:219], v[80:81], off offset:1536
	global_load_dwordx4 v[204:207], v[74:75], off offset:1536
	global_load_dwordx4 v[208:211], v[76:77], off offset:1536
	global_load_dwordx4 v[220:223], v[82:83], off offset:1536
	global_load_dwordx4 v[224:227], v[84:85], off offset:1536
	global_load_dwordx4 v[228:231], v[86:87], off offset:1536
	global_load_dwordx4 v[232:235], v[88:89], off offset:1536
	s_waitcnt lgkmcnt(0)
	s_barrier
	v_mfma_f32_32x32x16_bf16 v[34:49], v[176:179], v[180:183], v[34:49]
	v_mfma_f32_32x32x16_bf16 v[50:65], v[176:179], v[192:195], v[50:65]
	v_mfma_f32_32x32x16_bf16 v[2:17], v[184:187], v[188:191], v[2:17]
	v_mfma_f32_32x32x16_bf16 v[18:33], v[184:187], v[196:199], v[18:33]
	v_mfma_f32_32x32x16_bf16 v[34:49], v[200:203], v[188:191], v[34:49]
	v_mfma_f32_32x32x16_bf16 v[50:65], v[200:203], v[196:199], v[50:65]
	ds_read_b128 v[176:179], v66 offset:18432
	ds_read_b128 v[180:183], v67 offset:55296
	ds_read_b128 v[184:187], v66 offset:18464
	ds_read_b128 v[188:191], v67 offset:55328
	ds_read_b128 v[192:195], v67 offset:59904
	ds_read_b128 v[196:199], v67 offset:59936
	s_waitcnt lgkmcnt(4)
	v_mfma_f32_32x32x16_bf16 v[2:17], v[176:179], v[180:183], v[2:17]
	s_waitcnt lgkmcnt(1)
	v_mfma_f32_32x32x16_bf16 v[18:33], v[176:179], v[192:195], v[18:33]
	ds_read_b128 v[176:179], v66 offset:23040
	ds_read_b128 v[200:203], v66 offset:23072
	s_waitcnt lgkmcnt(1)
	v_mfma_f32_32x32x16_bf16 v[34:49], v[176:179], v[180:183], v[34:49]
	v_mfma_f32_32x32x16_bf16 v[50:65], v[176:179], v[192:195], v[50:65]
	v_mfma_f32_32x32x16_bf16 v[2:17], v[184:187], v[188:191], v[2:17]
	v_mfma_f32_32x32x16_bf16 v[18:33], v[184:187], v[196:199], v[18:33]
	s_waitcnt lgkmcnt(0)
	v_mfma_f32_32x32x16_bf16 v[34:49], v[200:203], v[188:191], v[34:49]
	ds_read_b128 v[176:179], v66 offset:18496
	ds_read_b128 v[180:183], v67 offset:55360
	ds_read_b128 v[184:187], v66 offset:18528
	ds_read_b128 v[188:191], v67 offset:55392
	v_mfma_f32_32x32x16_bf16 v[50:65], v[200:203], v[196:199], v[50:65]
	ds_read_b128 v[192:195], v67 offset:59968
	ds_read_b128 v[196:199], v67 offset:60000
	s_waitcnt lgkmcnt(4)
	v_mfma_f32_32x32x16_bf16 v[2:17], v[176:179], v[180:183], v[2:17]
	s_waitcnt lgkmcnt(1)
	v_mfma_f32_32x32x16_bf16 v[18:33], v[176:179], v[192:195], v[18:33]
	ds_read_b128 v[176:179], v66 offset:23104
	ds_read_b128 v[200:203], v66 offset:23136
	s_waitcnt vmcnt(16)
	ds_write_b128 v90, v[112:115]
	ds_write_b128 v90, v[120:123] offset:4608
	ds_write_b128 v90, v[124:127] offset:9216
	ds_write_b128 v90, v[128:131] offset:13824
	ds_write_b128 v90, v[116:119] offset:36864
	ds_write_b128 v90, v[132:135] offset:41472
	ds_write_b128 v90, v[136:139] offset:46080
	ds_write_b128 v90, v[140:143] offset:50688
	global_load_dwordx4 v[120:123], v[78:79], off offset:1664
	global_load_dwordx4 v[124:127], v[80:81], off offset:1664
	global_load_dwordx4 v[112:115], v[74:75], off offset:1664
	global_load_dwordx4 v[116:119], v[76:77], off offset:1664
	global_load_dwordx4 v[128:131], v[82:83], off offset:1664
	global_load_dwordx4 v[132:135], v[84:85], off offset:1664
	global_load_dwordx4 v[136:139], v[86:87], off offset:1664
	global_load_dwordx4 v[140:143], v[88:89], off offset:1664
	s_waitcnt lgkmcnt(0)
	s_barrier
	v_mfma_f32_32x32x16_bf16 v[34:49], v[176:179], v[180:183], v[34:49]
	v_mfma_f32_32x32x16_bf16 v[50:65], v[176:179], v[192:195], v[50:65]
	v_mfma_f32_32x32x16_bf16 v[2:17], v[184:187], v[188:191], v[2:17]
	v_mfma_f32_32x32x16_bf16 v[18:33], v[184:187], v[196:199], v[18:33]
	v_mfma_f32_32x32x16_bf16 v[34:49], v[200:203], v[188:191], v[34:49]
	v_mfma_f32_32x32x16_bf16 v[50:65], v[200:203], v[196:199], v[50:65]
	ds_read_b128 v[176:179], v66
	ds_read_b128 v[180:183], v67 offset:36864
	ds_read_b128 v[184:187], v66 offset:32
	ds_read_b128 v[188:191], v67 offset:36896
	ds_read_b128 v[192:195], v67 offset:41472
	ds_read_b128 v[196:199], v67 offset:41504
	s_waitcnt lgkmcnt(4)
	v_mfma_f32_32x32x16_bf16 v[2:17], v[176:179], v[180:183], v[2:17]
	s_waitcnt lgkmcnt(1)
	v_mfma_f32_32x32x16_bf16 v[18:33], v[176:179], v[192:195], v[18:33]
	ds_read_b128 v[176:179], v66 offset:4608
	ds_read_b128 v[200:203], v66 offset:4640
	s_waitcnt lgkmcnt(1)
	v_mfma_f32_32x32x16_bf16 v[34:49], v[176:179], v[180:183], v[34:49]
	v_mfma_f32_32x32x16_bf16 v[50:65], v[176:179], v[192:195], v[50:65]
	v_mfma_f32_32x32x16_bf16 v[2:17], v[184:187], v[188:191], v[2:17]
	v_mfma_f32_32x32x16_bf16 v[18:33], v[184:187], v[196:199], v[18:33]
	s_waitcnt lgkmcnt(0)
	v_mfma_f32_32x32x16_bf16 v[34:49], v[200:203], v[188:191], v[34:49]
	ds_read_b128 v[176:179], v66 offset:64
	ds_read_b128 v[180:183], v67 offset:36928
	ds_read_b128 v[184:187], v66 offset:96
	ds_read_b128 v[188:191], v67 offset:36960
	v_mfma_f32_32x32x16_bf16 v[50:65], v[200:203], v[196:199], v[50:65]
	ds_read_b128 v[192:195], v67 offset:41536
	ds_read_b128 v[196:199], v67 offset:41568
	s_waitcnt lgkmcnt(4)
	v_mfma_f32_32x32x16_bf16 v[2:17], v[176:179], v[180:183], v[2:17]
	s_waitcnt lgkmcnt(1)
	v_mfma_f32_32x32x16_bf16 v[18:33], v[176:179], v[192:195], v[18:33]
	ds_read_b128 v[176:179], v66 offset:4672
	ds_read_b128 v[200:203], v66 offset:4704
	s_waitcnt vmcnt(16)
	ds_write_b128 v90, v[144:147] offset:18432
	ds_write_b128 v90, v[152:155] offset:23040
	ds_write_b128 v90, v[156:159] offset:27648
	ds_write_b128 v90, v[160:163] offset:32256
	ds_write_b128 v90, v[148:151] offset:55296
	ds_write_b128 v90, v[164:167] offset:59904
	ds_write_b128 v90, v[168:171] offset:64512
	ds_write_b128 v91, v[172:175] offset:32256
	global_load_dwordx4 v[152:155], v[78:79], off offset:1792
	global_load_dwordx4 v[156:159], v[80:81], off offset:1792
	global_load_dwordx4 v[144:147], v[74:75], off offset:1792
	global_load_dwordx4 v[148:151], v[76:77], off offset:1792
	global_load_dwordx4 v[160:163], v[82:83], off offset:1792
	global_load_dwordx4 v[164:167], v[84:85], off offset:1792
	global_load_dwordx4 v[168:171], v[86:87], off offset:1792
	global_load_dwordx4 v[172:175], v[88:89], off offset:1792
	s_waitcnt lgkmcnt(0)
	s_barrier
	v_mfma_f32_32x32x16_bf16 v[34:49], v[176:179], v[180:183], v[34:49]
	v_mfma_f32_32x32x16_bf16 v[50:65], v[176:179], v[192:195], v[50:65]
	v_mfma_f32_32x32x16_bf16 v[2:17], v[184:187], v[188:191], v[2:17]
	v_mfma_f32_32x32x16_bf16 v[18:33], v[184:187], v[196:199], v[18:33]
	v_mfma_f32_32x32x16_bf16 v[34:49], v[200:203], v[188:191], v[34:49]
	v_mfma_f32_32x32x16_bf16 v[50:65], v[200:203], v[196:199], v[50:65]
	ds_read_b128 v[176:179], v66 offset:18432
	ds_read_b128 v[180:183], v67 offset:55296
	ds_read_b128 v[184:187], v66 offset:18464
	ds_read_b128 v[188:191], v67 offset:55328
	ds_read_b128 v[192:195], v67 offset:59904
	ds_read_b128 v[196:199], v67 offset:59936
	s_waitcnt lgkmcnt(4)
	v_mfma_f32_32x32x16_bf16 v[2:17], v[176:179], v[180:183], v[2:17]
	s_waitcnt lgkmcnt(1)
	v_mfma_f32_32x32x16_bf16 v[18:33], v[176:179], v[192:195], v[18:33]
	ds_read_b128 v[176:179], v66 offset:23040
	ds_read_b128 v[200:203], v66 offset:23072
	s_waitcnt lgkmcnt(1)
	v_mfma_f32_32x32x16_bf16 v[34:49], v[176:179], v[180:183], v[34:49]
	v_mfma_f32_32x32x16_bf16 v[50:65], v[176:179], v[192:195], v[50:65]
	v_mfma_f32_32x32x16_bf16 v[2:17], v[184:187], v[188:191], v[2:17]
	v_mfma_f32_32x32x16_bf16 v[18:33], v[184:187], v[196:199], v[18:33]
	s_waitcnt lgkmcnt(0)
	v_mfma_f32_32x32x16_bf16 v[34:49], v[200:203], v[188:191], v[34:49]
	ds_read_b128 v[176:179], v66 offset:18496
	ds_read_b128 v[180:183], v67 offset:55360
	ds_read_b128 v[184:187], v66 offset:18528
	ds_read_b128 v[188:191], v67 offset:55392
	v_mfma_f32_32x32x16_bf16 v[50:65], v[200:203], v[196:199], v[50:65]
	ds_read_b128 v[192:195], v67 offset:59968
	ds_read_b128 v[196:199], v67 offset:60000
	s_waitcnt lgkmcnt(4)
	v_mfma_f32_32x32x16_bf16 v[2:17], v[176:179], v[180:183], v[2:17]
	s_waitcnt lgkmcnt(1)
	v_mfma_f32_32x32x16_bf16 v[18:33], v[176:179], v[192:195], v[18:33]
	ds_read_b128 v[176:179], v66 offset:23104
	ds_read_b128 v[200:203], v66 offset:23136
	s_waitcnt vmcnt(16)
	ds_write_b128 v90, v[204:207]
	ds_write_b128 v90, v[212:215] offset:4608
	ds_write_b128 v90, v[216:219] offset:9216
	ds_write_b128 v90, v[220:223] offset:13824
	ds_write_b128 v90, v[208:211] offset:36864
	ds_write_b128 v90, v[224:227] offset:41472
	ds_write_b128 v90, v[228:231] offset:46080
	ds_write_b128 v90, v[232:235] offset:50688
	global_load_dwordx4 v[212:215], v[78:79], off offset:1920
	global_load_dwordx4 v[216:219], v[80:81], off offset:1920
	global_load_dwordx4 v[204:207], v[74:75], off offset:1920
	global_load_dwordx4 v[208:211], v[76:77], off offset:1920
	global_load_dwordx4 v[220:223], v[82:83], off offset:1920
	global_load_dwordx4 v[224:227], v[84:85], off offset:1920
	global_load_dwordx4 v[228:231], v[86:87], off offset:1920
	global_load_dwordx4 v[232:235], v[88:89], off offset:1920
	s_waitcnt lgkmcnt(0)
	s_barrier
	v_mfma_f32_32x32x16_bf16 v[34:49], v[176:179], v[180:183], v[34:49]
	v_mfma_f32_32x32x16_bf16 v[50:65], v[176:179], v[192:195], v[50:65]
	v_mfma_f32_32x32x16_bf16 v[2:17], v[184:187], v[188:191], v[2:17]
	v_mfma_f32_32x32x16_bf16 v[18:33], v[184:187], v[196:199], v[18:33]
	v_mfma_f32_32x32x16_bf16 v[34:49], v[200:203], v[188:191], v[34:49]
	v_mfma_f32_32x32x16_bf16 v[50:65], v[200:203], v[196:199], v[50:65]
	ds_read_b128 v[176:179], v66
	ds_read_b128 v[180:183], v67 offset:36864
	ds_read_b128 v[184:187], v66 offset:32
	ds_read_b128 v[188:191], v67 offset:36896
	ds_read_b128 v[192:195], v67 offset:41472
	ds_read_b128 v[196:199], v67 offset:41504
	s_waitcnt lgkmcnt(4)
	v_mfma_f32_32x32x16_bf16 v[2:17], v[176:179], v[180:183], v[2:17]
	s_waitcnt lgkmcnt(1)
	v_mfma_f32_32x32x16_bf16 v[18:33], v[176:179], v[192:195], v[18:33]
	ds_read_b128 v[176:179], v66 offset:4608
	ds_read_b128 v[200:203], v66 offset:4640
	s_waitcnt lgkmcnt(1)
	v_mfma_f32_32x32x16_bf16 v[34:49], v[176:179], v[180:183], v[34:49]
	v_mfma_f32_32x32x16_bf16 v[50:65], v[176:179], v[192:195], v[50:65]
	v_mfma_f32_32x32x16_bf16 v[2:17], v[184:187], v[188:191], v[2:17]
	v_mfma_f32_32x32x16_bf16 v[18:33], v[184:187], v[196:199], v[18:33]
	s_waitcnt lgkmcnt(0)
	v_mfma_f32_32x32x16_bf16 v[34:49], v[200:203], v[188:191], v[34:49]
	ds_read_b128 v[176:179], v66 offset:64
	ds_read_b128 v[180:183], v67 offset:36928
	ds_read_b128 v[184:187], v66 offset:96
	ds_read_b128 v[188:191], v67 offset:36960
	v_mfma_f32_32x32x16_bf16 v[50:65], v[200:203], v[196:199], v[50:65]
	ds_read_b128 v[192:195], v67 offset:41536
	ds_read_b128 v[196:199], v67 offset:41568
	s_waitcnt lgkmcnt(4)
	v_mfma_f32_32x32x16_bf16 v[2:17], v[176:179], v[180:183], v[2:17]
	s_waitcnt lgkmcnt(1)
	v_mfma_f32_32x32x16_bf16 v[18:33], v[176:179], v[192:195], v[18:33]
	ds_read_b128 v[176:179], v66 offset:4672
	ds_read_b128 v[200:203], v66 offset:4704
	s_waitcnt vmcnt(16)
	ds_write_b128 v90, v[112:115] offset:18432
	ds_write_b128 v90, v[120:123] offset:23040
	ds_write_b128 v90, v[124:127] offset:27648
	ds_write_b128 v90, v[128:131] offset:32256
	ds_write_b128 v90, v[116:119] offset:55296
	ds_write_b128 v90, v[132:135] offset:59904
	ds_write_b128 v90, v[136:139] offset:64512
	ds_write_b128 v91, v[140:143] offset:32256
	s_waitcnt lgkmcnt(0)
	s_barrier
	v_mfma_f32_32x32x16_bf16 v[34:49], v[176:179], v[180:183], v[34:49]
	v_mfma_f32_32x32x16_bf16 v[50:65], v[176:179], v[192:195], v[50:65]
	v_mfma_f32_32x32x16_bf16 v[2:17], v[184:187], v[188:191], v[2:17]
	v_mfma_f32_32x32x16_bf16 v[18:33], v[184:187], v[196:199], v[18:33]
	v_mfma_f32_32x32x16_bf16 v[34:49], v[200:203], v[188:191], v[34:49]
	v_mfma_f32_32x32x16_bf16 v[50:65], v[200:203], v[196:199], v[50:65]
	ds_read_b128 v[128:131], v66 offset:18432
	ds_read_b128 v[132:135], v67 offset:55296
	ds_read_b128 v[136:139], v66 offset:18464
	ds_read_b128 v[140:143], v67 offset:55328
	ds_read_b128 v[176:179], v67 offset:59904
	ds_read_b128 v[180:183], v67 offset:59936
	s_waitcnt lgkmcnt(4)
	v_mfma_f32_32x32x16_bf16 v[2:17], v[128:131], v[132:135], v[2:17]
	s_waitcnt lgkmcnt(1)
	v_mfma_f32_32x32x16_bf16 v[18:33], v[128:131], v[176:179], v[18:33]
	ds_read_b128 v[128:131], v66 offset:23040
	ds_read_b128 v[184:187], v66 offset:23072
	s_waitcnt lgkmcnt(1)
	v_mfma_f32_32x32x16_bf16 v[34:49], v[128:131], v[132:135], v[34:49]
	v_mfma_f32_32x32x16_bf16 v[50:65], v[128:131], v[176:179], v[50:65]
	v_mfma_f32_32x32x16_bf16 v[2:17], v[136:139], v[140:143], v[2:17]
	v_mfma_f32_32x32x16_bf16 v[18:33], v[136:139], v[180:183], v[18:33]
	s_waitcnt lgkmcnt(0)
	v_mfma_f32_32x32x16_bf16 v[34:49], v[184:187], v[140:143], v[34:49]
	ds_read_b128 v[128:131], v66 offset:18496
	ds_read_b128 v[132:135], v67 offset:55360
	ds_read_b128 v[136:139], v66 offset:18528
	ds_read_b128 v[140:143], v67 offset:55392
	v_mfma_f32_32x32x16_bf16 v[50:65], v[184:187], v[180:183], v[50:65]
	ds_read_b128 v[176:179], v67 offset:59968
	ds_read_b128 v[180:183], v67 offset:60000
	s_waitcnt lgkmcnt(4)
	v_mfma_f32_32x32x16_bf16 v[2:17], v[128:131], v[132:135], v[2:17]
	s_waitcnt lgkmcnt(1)
	v_mfma_f32_32x32x16_bf16 v[18:33], v[128:131], v[176:179], v[18:33]
	ds_read_b128 v[128:131], v66 offset:23104
	ds_read_b128 v[184:187], v66 offset:23136
	s_waitcnt vmcnt(8)
	ds_write_b128 v90, v[144:147]
	ds_write_b128 v90, v[152:155] offset:4608
	ds_write_b128 v90, v[156:159] offset:9216
	ds_write_b128 v90, v[160:163] offset:13824
	ds_write_b128 v90, v[148:151] offset:36864
	ds_write_b128 v90, v[164:167] offset:41472
	ds_write_b128 v90, v[168:171] offset:46080
	ds_write_b128 v90, v[172:175] offset:50688
	s_waitcnt lgkmcnt(0)
	s_barrier
	v_mfma_f32_32x32x16_bf16 v[34:49], v[128:131], v[132:135], v[34:49]
	v_mfma_f32_32x32x16_bf16 v[50:65], v[128:131], v[176:179], v[50:65]
	v_mfma_f32_32x32x16_bf16 v[2:17], v[136:139], v[140:143], v[2:17]
	v_mfma_f32_32x32x16_bf16 v[18:33], v[136:139], v[180:183], v[18:33]
	v_mfma_f32_32x32x16_bf16 v[34:49], v[184:187], v[140:143], v[34:49]
	v_mfma_f32_32x32x16_bf16 v[50:65], v[184:187], v[180:183], v[50:65]
	ds_read_b128 v[128:131], v66
	ds_read_b128 v[132:135], v67 offset:36864
	ds_read_b128 v[136:139], v66 offset:32
	ds_read_b128 v[140:143], v67 offset:36896
	ds_read_b128 v[144:147], v67 offset:41472
	ds_read_b128 v[148:151], v67 offset:41504
	s_waitcnt lgkmcnt(4)
	v_mfma_f32_32x32x16_bf16 v[2:17], v[128:131], v[132:135], v[2:17]
	s_waitcnt lgkmcnt(1)
	v_mfma_f32_32x32x16_bf16 v[18:33], v[128:131], v[144:147], v[18:33]
	ds_read_b128 v[128:131], v66 offset:4608
	ds_read_b128 v[152:155], v66 offset:4640
	s_waitcnt lgkmcnt(1)
	v_mfma_f32_32x32x16_bf16 v[34:49], v[128:131], v[132:135], v[34:49]
	v_mfma_f32_32x32x16_bf16 v[50:65], v[128:131], v[144:147], v[50:65]
	v_mfma_f32_32x32x16_bf16 v[2:17], v[136:139], v[140:143], v[2:17]
	v_mfma_f32_32x32x16_bf16 v[18:33], v[136:139], v[148:151], v[18:33]
	s_waitcnt lgkmcnt(0)
	v_mfma_f32_32x32x16_bf16 v[34:49], v[152:155], v[140:143], v[34:49]
	ds_read_b128 v[128:131], v66 offset:64
	ds_read_b128 v[132:135], v67 offset:36928
	ds_read_b128 v[136:139], v66 offset:96
	ds_read_b128 v[140:143], v67 offset:36960
	v_mfma_f32_32x32x16_bf16 v[50:65], v[152:155], v[148:151], v[50:65]
	ds_read_b128 v[144:147], v67 offset:41536
	ds_read_b128 v[148:151], v67 offset:41568
	s_waitcnt lgkmcnt(4)
	v_mfma_f32_32x32x16_bf16 v[2:17], v[128:131], v[132:135], v[2:17]
	s_waitcnt lgkmcnt(1)
	v_mfma_f32_32x32x16_bf16 v[18:33], v[128:131], v[144:147], v[18:33]
	ds_read_b128 v[128:131], v66 offset:4672
	ds_read_b128 v[152:155], v66 offset:4704
	s_waitcnt vmcnt(0)
	ds_write_b128 v90, v[204:207] offset:18432
	ds_write_b128 v90, v[212:215] offset:23040
	ds_write_b128 v90, v[216:219] offset:27648
	ds_write_b128 v90, v[220:223] offset:32256
	ds_write_b128 v90, v[208:211] offset:55296
	ds_write_b128 v90, v[224:227] offset:59904
	ds_write_b128 v90, v[228:231] offset:64512
	ds_write_b128 v91, v[232:235] offset:32256
	s_waitcnt lgkmcnt(0)
	s_barrier
	v_mfma_f32_32x32x16_bf16 v[34:49], v[128:131], v[132:135], v[34:49]
	v_mfma_f32_32x32x16_bf16 v[50:65], v[128:131], v[144:147], v[50:65]
	v_mfma_f32_32x32x16_bf16 v[2:17], v[136:139], v[140:143], v[2:17]
	v_mfma_f32_32x32x16_bf16 v[18:33], v[136:139], v[148:151], v[18:33]
	v_mfma_f32_32x32x16_bf16 v[34:49], v[152:155], v[140:143], v[34:49]
	v_mfma_f32_32x32x16_bf16 v[50:65], v[152:155], v[148:151], v[50:65]
	ds_read_b128 v[74:77], v66 offset:18432
	ds_read_b128 v[78:81], v67 offset:55296
	ds_read_b128 v[82:85], v66 offset:18464
	ds_read_b128 v[86:89], v67 offset:55328
	ds_read_b128 v[112:115], v67 offset:59904
	ds_read_b128 v[116:119], v67 offset:59936
	s_and_b64 vcc, exec, s[4:5]
	s_waitcnt lgkmcnt(4)
	v_mfma_f32_32x32x16_bf16 v[2:17], v[74:77], v[78:81], v[2:17]
	s_waitcnt lgkmcnt(1)
	v_mfma_f32_32x32x16_bf16 v[18:33], v[74:77], v[112:115], v[18:33]
	ds_read_b128 v[74:77], v66 offset:23040
	ds_read_b128 v[120:123], v66 offset:23072
	s_waitcnt lgkmcnt(1)
	v_mfma_f32_32x32x16_bf16 v[34:49], v[74:77], v[78:81], v[34:49]
	v_mfma_f32_32x32x16_bf16 v[50:65], v[74:77], v[112:115], v[50:65]
	v_mfma_f32_32x32x16_bf16 v[2:17], v[82:85], v[86:89], v[2:17]
	v_mfma_f32_32x32x16_bf16 v[18:33], v[82:85], v[116:119], v[18:33]
	s_waitcnt lgkmcnt(0)
	v_mfma_f32_32x32x16_bf16 v[34:49], v[120:123], v[86:89], v[34:49]
	ds_read_b128 v[74:77], v66 offset:18496
	ds_read_b128 v[78:81], v67 offset:55360
	ds_read_b128 v[82:85], v66 offset:18528
	ds_read_b128 v[86:89], v67 offset:55392
	v_mfma_f32_32x32x16_bf16 v[50:65], v[120:123], v[116:119], v[50:65]
	ds_read_b128 v[112:115], v67 offset:59968
	ds_read_b128 v[116:119], v67 offset:60000
	s_waitcnt lgkmcnt(4)
	v_mfma_f32_32x32x16_bf16 v[2:17], v[74:77], v[78:81], v[2:17]
	s_waitcnt lgkmcnt(1)
	v_mfma_f32_32x32x16_bf16 v[18:33], v[74:77], v[112:115], v[18:33]
	ds_read_b128 v[74:77], v66 offset:23104
	ds_read_b128 v[120:123], v66 offset:23136
	s_waitcnt lgkmcnt(0)
	s_barrier
	v_mfma_f32_32x32x16_bf16 v[34:49], v[74:77], v[78:81], v[34:49]
	v_mfma_f32_32x32x16_bf16 v[50:65], v[74:77], v[112:115], v[50:65]
	v_mfma_f32_32x32x16_bf16 v[2:17], v[82:85], v[86:89], v[2:17]
	v_mfma_f32_32x32x16_bf16 v[18:33], v[82:85], v[116:119], v[18:33]
	v_mfma_f32_32x32x16_bf16 v[34:49], v[120:123], v[86:89], v[34:49]
	s_nop 10
	ds_write2_b32 v93, v2, v18 offset1:32
	v_mfma_f32_32x32x16_bf16 v[50:65], v[120:123], v[116:119], v[50:65]
	s_nop 11
	ds_write2_b32 v95, v34, v50 offset0:32 offset1:64
	ds_write2_b32 v93, v3, v19 offset0:129 offset1:161
	ds_write2_b32 v95, v35, v51 offset0:161 offset1:193
	ds_write2_b32 v96, v4, v20 offset0:2 offset1:34
	ds_write2_b32 v97, v36, v52 offset0:34 offset1:66
	ds_write2_b32 v96, v5, v21 offset0:131 offset1:163
	ds_write2_b32 v97, v37, v53 offset0:163 offset1:195
	ds_write2_b32 v98, v6, v22 offset0:8 offset1:40
	ds_write2_b32 v99, v38, v54 offset0:40 offset1:72
	ds_write2_b32 v98, v7, v23 offset0:137 offset1:169
	ds_write2_b32 v99, v39, v55 offset0:169 offset1:201
	ds_write2_b32 v100, v8, v24 offset0:10 offset1:42
	ds_write2_b32 v101, v40, v56 offset0:42 offset1:74
	ds_write2_b32 v100, v9, v25 offset0:139 offset1:171
	ds_write2_b32 v101, v41, v57 offset0:171 offset1:203
	ds_write2_b32 v102, v10, v26 offset0:16 offset1:48
	ds_write2_b32 v103, v42, v58 offset0:48 offset1:80
	ds_write2_b32 v102, v11, v27 offset0:145 offset1:177
	ds_write2_b32 v103, v43, v59 offset0:177 offset1:209
	ds_write2_b32 v104, v12, v28 offset0:18 offset1:50
	ds_write2_b32 v105, v44, v60 offset0:50 offset1:82
	ds_write2_b32 v104, v13, v29 offset0:147 offset1:179
	ds_write2_b32 v105, v45, v61 offset0:179 offset1:211
	ds_write2_b32 v106, v14, v30 offset0:24 offset1:56
	ds_write2_b32 v107, v46, v62 offset0:56 offset1:88
	ds_write2_b32 v106, v15, v31 offset0:153 offset1:185
	ds_write2_b32 v107, v47, v63 offset0:185 offset1:217
	ds_write2_b32 v108, v16, v32 offset0:26 offset1:58
	ds_write2_b32 v109, v48, v64 offset0:58 offset1:90
	ds_write2_b32 v108, v17, v33 offset0:155 offset1:187
	ds_write2_b32 v109, v49, v65 offset0:187 offset1:219
	v_or_b32_e32 v6, s14, v92
	v_lshlrev_b32_e32 v68, 2, v6
	s_waitcnt lgkmcnt(0)
	s_barrier
	s_lshl_b32 s12, s17, 7
	s_and_b32 s12, s12, 0xffffe000
	s_lshl_b32 s14, s18, 7
	s_or_b32 s12, s12, s23
	s_and_b32 s14, s14, 0x1c00
	s_or_b32 s12, s14, s12
	v_mov_b32_e32 v2, v6
	v_add_u32_e32 v3, s12, v1
	v_lshlrev_b32_e32 v64, 12, v3
	v_lshl_add_u32 v64, v2, 2, v64
	v_lshlrev_b32_e32 v74, 2, v2
	global_load_dwordx4 v[120:123], v74, s[50:51]
	global_load_dwordx4 v[4:7], v64, s[44:45]
	v_add_u32_e32 v74, 0x8000, v64
	global_load_dwordx4 v[8:11], v74, s[44:45]
	v_add_u32_e32 v65, 0x10000, v64
	global_load_dwordx4 v[12:15], v65, s[44:45]
	v_add_u32_e32 v74, 0x18000, v64
	global_load_dwordx4 v[16:19], v74, s[44:45]
	v_add_u32_e32 v65, 0x20000, v64
	global_load_dwordx4 v[20:23], v65, s[44:45]
	v_add_u32_e32 v74, 0x28000, v64
	global_load_dwordx4 v[24:27], v74, s[44:45]
	v_add_u32_e32 v65, 0x30000, v64
	global_load_dwordx4 v[28:31], v65, s[44:45]
	v_add_u32_e32 v74, 0x38000, v64
	global_load_dwordx4 v[32:35], v74, s[44:45]
	v_add_u32_e32 v65, 0x40000, v64
	global_load_dwordx4 v[36:39], v65, s[44:45]
	v_add_u32_e32 v74, 0x48000, v64
	global_load_dwordx4 v[40:43], v74, s[44:45]
	v_add_u32_e32 v65, 0x50000, v64
	global_load_dwordx4 v[44:47], v65, s[44:45]
	v_add_u32_e32 v74, 0x58000, v64
	global_load_dwordx4 v[48:51], v74, s[44:45]
	v_add_u32_e32 v65, 0x60000, v64
	global_load_dwordx4 v[52:55], v65, s[44:45]
	v_add_u32_e32 v74, 0x68000, v64
	global_load_dwordx4 v[56:59], v74, s[44:45]
	v_add_u32_e32 v65, 0x70000, v64
	global_load_dwordx4 v[60:63], v65, s[44:45]
	v_add_u32_e32 v74, 0x78000, v64
	global_load_dwordx4 v[76:79], v74, s[44:45]
	v_and_b32_e32 v75, 7, v3
	v_mul_u32_u24_e32 v75, 0x204, v75
	v_and_b32_e32 v88, 0x7f, v2
	v_lshl_add_u32 v75, v88, 2, v75
	v_lshlrev_b32_e32 v156, 2, v3
	s_movk_i32 s14, 0x7fff
	v_mov_b32_e32 v157, 1
	ds_read2_b32 v[80:81], v75 offset1:1
	ds_read2_b32 v[82:83], v75 offset0:2 offset1:3
	v_add_u32_e32 v89, 0x1020, v75
	ds_read2_b32 v[84:85], v89 offset1:1
	ds_read2_b32 v[86:87], v89 offset0:2 offset1:3
	v_add_u32_e32 v88, 0x2040, v75
	ds_read2_b32 v[112:113], v88 offset1:1
	ds_read2_b32 v[114:115], v88 offset0:2 offset1:3
	v_add_u32_e32 v89, 0x3060, v75
	ds_read2_b32 v[116:117], v89 offset1:1
	ds_read2_b32 v[118:119], v89 offset0:2 offset1:3
	s_waitcnt vmcnt(15) lgkmcnt(6)
	v_pk_add_f32 v[4:5], v[4:5], v[80:81]
	v_pk_add_f32 v[6:7], v[6:7], v[82:83]
	s_waitcnt vmcnt(14) lgkmcnt(4)
	v_pk_add_f32 v[8:9], v[8:9], v[84:85]
	v_pk_add_f32 v[10:11], v[10:11], v[86:87]
	s_waitcnt vmcnt(13) lgkmcnt(2)
	v_pk_add_f32 v[12:13], v[12:13], v[112:113]
	v_pk_add_f32 v[14:15], v[14:15], v[114:115]
	s_waitcnt vmcnt(12) lgkmcnt(0)
	v_pk_add_f32 v[16:17], v[16:17], v[116:117]
	v_pk_add_f32 v[18:19], v[18:19], v[118:119]
	v_add_u32_e32 v88, 0x4080, v75
	ds_read2_b32 v[80:81], v88 offset1:1
	ds_read2_b32 v[82:83], v88 offset0:2 offset1:3
	v_add_u32_e32 v89, 0x50a0, v75
	ds_read2_b32 v[84:85], v89 offset1:1
	ds_read2_b32 v[86:87], v89 offset0:2 offset1:3
	v_add_u32_e32 v88, 0x60c0, v75
	ds_read2_b32 v[112:113], v88 offset1:1
	ds_read2_b32 v[114:115], v88 offset0:2 offset1:3
	v_add_u32_e32 v89, 0x70e0, v75
	ds_read2_b32 v[116:117], v89 offset1:1
	ds_read2_b32 v[118:119], v89 offset0:2 offset1:3
	global_store_dwordx4 v64, v[4:7], s[80:81]
	v_pk_mul_f32 v[140:141], v[4:5], v[4:5]
	v_pk_mul_f32 v[142:143], v[6:7], v[6:7]
	v_pk_mul_f32 v[144:145], v[4:5], v[120:121]
	v_pk_mul_f32 v[146:147], v[6:7], v[122:123]
	v_lshrrev_b32_e32 v158, 1, v64
	v_add_f32_e32 v124, v140, v141
	v_and_b32_sdwa v148, v144, v157 dst_sel:DWORD dst_unused:UNUSED_PAD src0_sel:WORD_1 src1_sel:DWORD
	v_and_b32_sdwa v149, v145, v157 dst_sel:DWORD dst_unused:UNUSED_PAD src0_sel:WORD_1 src1_sel:DWORD
	v_and_b32_sdwa v150, v146, v157 dst_sel:DWORD dst_unused:UNUSED_PAD src0_sel:WORD_1 src1_sel:DWORD
	v_and_b32_sdwa v151, v147, v157 dst_sel:DWORD dst_unused:UNUSED_PAD src0_sel:WORD_1 src1_sel:DWORD
	v_add_f32_e32 v124, v124, v142
	v_add3_u32 v144, v144, v148, s14
	v_add3_u32 v145, v145, v149, s14
	v_add3_u32 v146, v146, v150, s14
	v_add3_u32 v147, v147, v151, s14
	v_add_f32_e32 v124, v124, v143
	v_and_b32_e32 v145, 0xffff0000, v145
	v_and_b32_e32 v147, 0xffff0000, v147
	s_nop 0
	v_or_b32_sdwa v152, v145, v144 dst_sel:DWORD dst_unused:UNUSED_PAD src0_sel:DWORD src1_sel:WORD_1
	v_or_b32_sdwa v153, v147, v146 dst_sel:DWORD dst_unused:UNUSED_PAD src0_sel:DWORD src1_sel:WORD_1
	global_store_dwordx2 v158, v[152:153], s[92:93]
	v_add_u32_e32 v74, 0x8000, v64
	global_store_dwordx4 v74, v[8:11], s[80:81]
	v_pk_mul_f32 v[140:141], v[8:9], v[8:9]
	v_pk_mul_f32 v[142:143], v[10:11], v[10:11]
	v_pk_mul_f32 v[144:145], v[8:9], v[120:121]
	v_pk_mul_f32 v[146:147], v[10:11], v[122:123]
	v_lshrrev_b32_e32 v159, 1, v74
	v_add_f32_e32 v125, v140, v141
	v_and_b32_sdwa v148, v144, v157 dst_sel:DWORD dst_unused:UNUSED_PAD src0_sel:WORD_1 src1_sel:DWORD
	v_and_b32_sdwa v149, v145, v157 dst_sel:DWORD dst_unused:UNUSED_PAD src0_sel:WORD_1 src1_sel:DWORD
	v_and_b32_sdwa v150, v146, v157 dst_sel:DWORD dst_unused:UNUSED_PAD src0_sel:WORD_1 src1_sel:DWORD
	v_and_b32_sdwa v151, v147, v157 dst_sel:DWORD dst_unused:UNUSED_PAD src0_sel:WORD_1 src1_sel:DWORD
	v_add_f32_e32 v125, v125, v142
	v_add3_u32 v144, v144, v148, s14
	v_add3_u32 v145, v145, v149, s14
	v_add3_u32 v146, v146, v150, s14
	v_add3_u32 v147, v147, v151, s14
	v_add_f32_e32 v125, v125, v143
	v_and_b32_e32 v145, 0xffff0000, v145
	v_and_b32_e32 v147, 0xffff0000, v147
	s_nop 0
	v_or_b32_sdwa v154, v145, v144 dst_sel:DWORD dst_unused:UNUSED_PAD src0_sel:DWORD src1_sel:WORD_1
	v_or_b32_sdwa v155, v147, v146 dst_sel:DWORD dst_unused:UNUSED_PAD src0_sel:DWORD src1_sel:WORD_1
	global_store_dwordx2 v159, v[154:155], s[92:93]
	v_add_u32_e32 v65, 0x10000, v64
	global_store_dwordx4 v65, v[12:15], s[80:81]
	v_pk_mul_f32 v[140:141], v[12:13], v[12:13]
	v_pk_mul_f32 v[142:143], v[14:15], v[14:15]
	v_pk_mul_f32 v[144:145], v[12:13], v[120:121]
	v_pk_mul_f32 v[146:147], v[14:15], v[122:123]
	v_lshrrev_b32_e32 v158, 1, v65
	v_add_f32_e32 v126, v140, v141
	v_and_b32_sdwa v148, v144, v157 dst_sel:DWORD dst_unused:UNUSED_PAD src0_sel:WORD_1 src1_sel:DWORD
	v_and_b32_sdwa v149, v145, v157 dst_sel:DWORD dst_unused:UNUSED_PAD src0_sel:WORD_1 src1_sel:DWORD
	v_and_b32_sdwa v150, v146, v157 dst_sel:DWORD dst_unused:UNUSED_PAD src0_sel:WORD_1 src1_sel:DWORD
	v_and_b32_sdwa v151, v147, v157 dst_sel:DWORD dst_unused:UNUSED_PAD src0_sel:WORD_1 src1_sel:DWORD
	v_add_f32_e32 v126, v126, v142
	v_add3_u32 v144, v144, v148, s14
	v_add3_u32 v145, v145, v149, s14
	v_add3_u32 v146, v146, v150, s14
	v_add3_u32 v147, v147, v151, s14
	v_add_f32_e32 v126, v126, v143
	v_and_b32_e32 v145, 0xffff0000, v145
	v_and_b32_e32 v147, 0xffff0000, v147
	s_nop 0
	v_or_b32_sdwa v152, v145, v144 dst_sel:DWORD dst_unused:UNUSED_PAD src0_sel:DWORD src1_sel:WORD_1
	v_or_b32_sdwa v153, v147, v146 dst_sel:DWORD dst_unused:UNUSED_PAD src0_sel:DWORD src1_sel:WORD_1
	global_store_dwordx2 v158, v[152:153], s[92:93]
	v_add_u32_e32 v74, 0x18000, v64
	global_store_dwordx4 v74, v[16:19], s[80:81]
	v_pk_mul_f32 v[140:141], v[16:17], v[16:17]
	v_pk_mul_f32 v[142:143], v[18:19], v[18:19]
	v_pk_mul_f32 v[144:145], v[16:17], v[120:121]
	v_pk_mul_f32 v[146:147], v[18:19], v[122:123]
	v_lshrrev_b32_e32 v159, 1, v74
	v_add_f32_e32 v127, v140, v141
	v_and_b32_sdwa v148, v144, v157 dst_sel:DWORD dst_unused:UNUSED_PAD src0_sel:WORD_1 src1_sel:DWORD
	v_and_b32_sdwa v149, v145, v157 dst_sel:DWORD dst_unused:UNUSED_PAD src0_sel:WORD_1 src1_sel:DWORD
	v_and_b32_sdwa v150, v146, v157 dst_sel:DWORD dst_unused:UNUSED_PAD src0_sel:WORD_1 src1_sel:DWORD
	v_and_b32_sdwa v151, v147, v157 dst_sel:DWORD dst_unused:UNUSED_PAD src0_sel:WORD_1 src1_sel:DWORD
	v_add_f32_e32 v127, v127, v142
	v_add3_u32 v144, v144, v148, s14
	v_add3_u32 v145, v145, v149, s14
	v_add3_u32 v146, v146, v150, s14
	v_add3_u32 v147, v147, v151, s14
	v_add_f32_e32 v127, v127, v143
	v_and_b32_e32 v145, 0xffff0000, v145
	v_and_b32_e32 v147, 0xffff0000, v147
	s_nop 0
	v_or_b32_sdwa v154, v145, v144 dst_sel:DWORD dst_unused:UNUSED_PAD src0_sel:DWORD src1_sel:WORD_1
	v_or_b32_sdwa v155, v147, v146 dst_sel:DWORD dst_unused:UNUSED_PAD src0_sel:DWORD src1_sel:WORD_1
	global_store_dwordx2 v159, v[154:155], s[92:93]
	s_nop 1
	v_add_f32_dpp v124, v124, v124 quad_perm:[1,0,3,2] row_mask:0xf bank_mask:0xf
	v_add_f32_dpp v125, v125, v125 quad_perm:[1,0,3,2] row_mask:0xf bank_mask:0xf
	v_add_f32_dpp v126, v126, v126 quad_perm:[1,0,3,2] row_mask:0xf bank_mask:0xf
	v_add_f32_dpp v127, v127, v127 quad_perm:[1,0,3,2] row_mask:0xf bank_mask:0xf
	v_add_f32_dpp v124, v124, v124 quad_perm:[2,3,0,1] row_mask:0xf bank_mask:0xf
	v_add_f32_dpp v125, v125, v125 quad_perm:[2,3,0,1] row_mask:0xf bank_mask:0xf
	v_add_f32_dpp v126, v126, v126 quad_perm:[2,3,0,1] row_mask:0xf bank_mask:0xf
	v_add_f32_dpp v127, v127, v127 quad_perm:[2,3,0,1] row_mask:0xf bank_mask:0xf
	v_add_f32_dpp v124, v124, v124 row_half_mirror row_mask:0xf bank_mask:0xf
	v_add_f32_dpp v125, v125, v125 row_half_mirror row_mask:0xf bank_mask:0xf
	v_add_f32_dpp v126, v126, v126 row_half_mirror row_mask:0xf bank_mask:0xf
	v_add_f32_dpp v127, v127, v127 row_half_mirror row_mask:0xf bank_mask:0xf
	v_add_f32_dpp v124, v124, v124 row_mirror row_mask:0xf bank_mask:0xf
	v_add_f32_dpp v125, v125, v125 row_mirror row_mask:0xf bank_mask:0xf
	v_add_f32_dpp v126, v126, v126 row_mirror row_mask:0xf bank_mask:0xf
	v_add_f32_dpp v127, v127, v127 row_mirror row_mask:0xf bank_mask:0xf
	v_add_f32_dpp v124, v124, v124 row_bcast:15 row_mask:0xa bank_mask:0xf
	v_add_f32_dpp v125, v125, v125 row_bcast:15 row_mask:0xa bank_mask:0xf
	v_add_f32_dpp v126, v126, v126 row_bcast:15 row_mask:0xa bank_mask:0xf
	v_add_f32_dpp v127, v127, v127 row_bcast:15 row_mask:0xa bank_mask:0xf
	s_waitcnt vmcnt(19) lgkmcnt(6)
	v_pk_add_f32 v[20:21], v[20:21], v[80:81]
	v_pk_add_f32 v[22:23], v[22:23], v[82:83]
	s_waitcnt vmcnt(18) lgkmcnt(4)
	v_pk_add_f32 v[24:25], v[24:25], v[84:85]
	v_pk_add_f32 v[26:27], v[26:27], v[86:87]
	s_waitcnt vmcnt(17) lgkmcnt(2)
	v_pk_add_f32 v[28:29], v[28:29], v[112:113]
	v_pk_add_f32 v[30:31], v[30:31], v[114:115]
	s_waitcnt vmcnt(16) lgkmcnt(0)
	v_pk_add_f32 v[32:33], v[32:33], v[116:117]
	v_pk_add_f32 v[34:35], v[34:35], v[118:119]
	v_add_u32_e32 v88, 0x8100, v75
	ds_read2_b32 v[80:81], v88 offset1:1
	ds_read2_b32 v[82:83], v88 offset0:2 offset1:3
	v_add_u32_e32 v89, 0x9120, v75
	ds_read2_b32 v[84:85], v89 offset1:1
	ds_read2_b32 v[86:87], v89 offset0:2 offset1:3
	v_add_u32_e32 v88, 0xa140, v75
	ds_read2_b32 v[112:113], v88 offset1:1
	ds_read2_b32 v[114:115], v88 offset0:2 offset1:3
	v_add_u32_e32 v89, 0xb160, v75
	ds_read2_b32 v[116:117], v89 offset1:1
	ds_read2_b32 v[118:119], v89 offset0:2 offset1:3
	v_add_u32_e32 v65, 0x20000, v64
	global_store_dwordx4 v65, v[20:23], s[80:81]
	v_pk_mul_f32 v[140:141], v[20:21], v[20:21]
	v_pk_mul_f32 v[142:143], v[22:23], v[22:23]
	v_pk_mul_f32 v[144:145], v[20:21], v[120:121]
	v_pk_mul_f32 v[146:147], v[22:23], v[122:123]
	v_lshrrev_b32_e32 v158, 1, v65
	v_add_f32_e32 v128, v140, v141
	v_and_b32_sdwa v148, v144, v157 dst_sel:DWORD dst_unused:UNUSED_PAD src0_sel:WORD_1 src1_sel:DWORD
	v_and_b32_sdwa v149, v145, v157 dst_sel:DWORD dst_unused:UNUSED_PAD src0_sel:WORD_1 src1_sel:DWORD
	v_and_b32_sdwa v150, v146, v157 dst_sel:DWORD dst_unused:UNUSED_PAD src0_sel:WORD_1 src1_sel:DWORD
	v_and_b32_sdwa v151, v147, v157 dst_sel:DWORD dst_unused:UNUSED_PAD src0_sel:WORD_1 src1_sel:DWORD
	v_add_f32_e32 v128, v128, v142
	v_add3_u32 v144, v144, v148, s14
	v_add3_u32 v145, v145, v149, s14
	v_add3_u32 v146, v146, v150, s14
	v_add3_u32 v147, v147, v151, s14
	v_add_f32_e32 v128, v128, v143
	v_and_b32_e32 v145, 0xffff0000, v145
	v_and_b32_e32 v147, 0xffff0000, v147
	s_nop 0
	v_or_b32_sdwa v152, v145, v144 dst_sel:DWORD dst_unused:UNUSED_PAD src0_sel:DWORD src1_sel:WORD_1
	v_or_b32_sdwa v153, v147, v146 dst_sel:DWORD dst_unused:UNUSED_PAD src0_sel:DWORD src1_sel:WORD_1
	global_store_dwordx2 v158, v[152:153], s[92:93]
	v_add_u32_e32 v74, 0x28000, v64
	global_store_dwordx4 v74, v[24:27], s[80:81]
	v_pk_mul_f32 v[140:141], v[24:25], v[24:25]
	v_pk_mul_f32 v[142:143], v[26:27], v[26:27]
	v_pk_mul_f32 v[144:145], v[24:25], v[120:121]
	v_pk_mul_f32 v[146:147], v[26:27], v[122:123]
	v_lshrrev_b32_e32 v159, 1, v74
	v_add_f32_e32 v129, v140, v141
	v_and_b32_sdwa v148, v144, v157 dst_sel:DWORD dst_unused:UNUSED_PAD src0_sel:WORD_1 src1_sel:DWORD
	v_and_b32_sdwa v149, v145, v157 dst_sel:DWORD dst_unused:UNUSED_PAD src0_sel:WORD_1 src1_sel:DWORD
	v_and_b32_sdwa v150, v146, v157 dst_sel:DWORD dst_unused:UNUSED_PAD src0_sel:WORD_1 src1_sel:DWORD
	v_and_b32_sdwa v151, v147, v157 dst_sel:DWORD dst_unused:UNUSED_PAD src0_sel:WORD_1 src1_sel:DWORD
	v_add_f32_e32 v129, v129, v142
	v_add3_u32 v144, v144, v148, s14
	v_add3_u32 v145, v145, v149, s14
	v_add3_u32 v146, v146, v150, s14
	v_add3_u32 v147, v147, v151, s14
	v_add_f32_e32 v129, v129, v143
	v_and_b32_e32 v145, 0xffff0000, v145
	v_and_b32_e32 v147, 0xffff0000, v147
	s_nop 0
	v_or_b32_sdwa v154, v145, v144 dst_sel:DWORD dst_unused:UNUSED_PAD src0_sel:DWORD src1_sel:WORD_1
	v_or_b32_sdwa v155, v147, v146 dst_sel:DWORD dst_unused:UNUSED_PAD src0_sel:DWORD src1_sel:WORD_1
	global_store_dwordx2 v159, v[154:155], s[92:93]
	v_add_u32_e32 v65, 0x30000, v64
	global_store_dwordx4 v65, v[28:31], s[80:81]
	v_pk_mul_f32 v[140:141], v[28:29], v[28:29]
	v_pk_mul_f32 v[142:143], v[30:31], v[30:31]
	v_pk_mul_f32 v[144:145], v[28:29], v[120:121]
	v_pk_mul_f32 v[146:147], v[30:31], v[122:123]
	v_lshrrev_b32_e32 v158, 1, v65
	v_add_f32_e32 v130, v140, v141
	v_and_b32_sdwa v148, v144, v157 dst_sel:DWORD dst_unused:UNUSED_PAD src0_sel:WORD_1 src1_sel:DWORD
	v_and_b32_sdwa v149, v145, v157 dst_sel:DWORD dst_unused:UNUSED_PAD src0_sel:WORD_1 src1_sel:DWORD
	v_and_b32_sdwa v150, v146, v157 dst_sel:DWORD dst_unused:UNUSED_PAD src0_sel:WORD_1 src1_sel:DWORD
	v_and_b32_sdwa v151, v147, v157 dst_sel:DWORD dst_unused:UNUSED_PAD src0_sel:WORD_1 src1_sel:DWORD
	v_add_f32_e32 v130, v130, v142
	v_add3_u32 v144, v144, v148, s14
	v_add3_u32 v145, v145, v149, s14
	v_add3_u32 v146, v146, v150, s14
	v_add3_u32 v147, v147, v151, s14
	v_add_f32_e32 v130, v130, v143
	v_and_b32_e32 v145, 0xffff0000, v145
	v_and_b32_e32 v147, 0xffff0000, v147
	s_nop 0
	v_or_b32_sdwa v152, v145, v144 dst_sel:DWORD dst_unused:UNUSED_PAD src0_sel:DWORD src1_sel:WORD_1
	v_or_b32_sdwa v153, v147, v146 dst_sel:DWORD dst_unused:UNUSED_PAD src0_sel:DWORD src1_sel:WORD_1
	global_store_dwordx2 v158, v[152:153], s[92:93]
	v_add_u32_e32 v74, 0x38000, v64
	global_store_dwordx4 v74, v[32:35], s[80:81]
	v_pk_mul_f32 v[140:141], v[32:33], v[32:33]
	v_pk_mul_f32 v[142:143], v[34:35], v[34:35]
	v_pk_mul_f32 v[144:145], v[32:33], v[120:121]
	v_pk_mul_f32 v[146:147], v[34:35], v[122:123]
	v_lshrrev_b32_e32 v159, 1, v74
	v_add_f32_e32 v131, v140, v141
	v_and_b32_sdwa v148, v144, v157 dst_sel:DWORD dst_unused:UNUSED_PAD src0_sel:WORD_1 src1_sel:DWORD
	v_and_b32_sdwa v149, v145, v157 dst_sel:DWORD dst_unused:UNUSED_PAD src0_sel:WORD_1 src1_sel:DWORD
	v_and_b32_sdwa v150, v146, v157 dst_sel:DWORD dst_unused:UNUSED_PAD src0_sel:WORD_1 src1_sel:DWORD
	v_and_b32_sdwa v151, v147, v157 dst_sel:DWORD dst_unused:UNUSED_PAD src0_sel:WORD_1 src1_sel:DWORD
	v_add_f32_e32 v131, v131, v142
	v_add3_u32 v144, v144, v148, s14
	v_add3_u32 v145, v145, v149, s14
	v_add3_u32 v146, v146, v150, s14
	v_add3_u32 v147, v147, v151, s14
	v_add_f32_e32 v131, v131, v143
	v_and_b32_e32 v145, 0xffff0000, v145
	v_and_b32_e32 v147, 0xffff0000, v147
	s_nop 0
	v_or_b32_sdwa v154, v145, v144 dst_sel:DWORD dst_unused:UNUSED_PAD src0_sel:DWORD src1_sel:WORD_1
	v_or_b32_sdwa v155, v147, v146 dst_sel:DWORD dst_unused:UNUSED_PAD src0_sel:DWORD src1_sel:WORD_1
	global_store_dwordx2 v159, v[154:155], s[92:93]
	s_nop 1
	v_add_f32_dpp v128, v128, v128 quad_perm:[1,0,3,2] row_mask:0xf bank_mask:0xf
	v_add_f32_dpp v129, v129, v129 quad_perm:[1,0,3,2] row_mask:0xf bank_mask:0xf
	v_add_f32_dpp v130, v130, v130 quad_perm:[1,0,3,2] row_mask:0xf bank_mask:0xf
	v_add_f32_dpp v131, v131, v131 quad_perm:[1,0,3,2] row_mask:0xf bank_mask:0xf
	v_add_f32_dpp v128, v128, v128 quad_perm:[2,3,0,1] row_mask:0xf bank_mask:0xf
	v_add_f32_dpp v129, v129, v129 quad_perm:[2,3,0,1] row_mask:0xf bank_mask:0xf
	v_add_f32_dpp v130, v130, v130 quad_perm:[2,3,0,1] row_mask:0xf bank_mask:0xf
	v_add_f32_dpp v131, v131, v131 quad_perm:[2,3,0,1] row_mask:0xf bank_mask:0xf
	v_add_f32_dpp v128, v128, v128 row_half_mirror row_mask:0xf bank_mask:0xf
	v_add_f32_dpp v129, v129, v129 row_half_mirror row_mask:0xf bank_mask:0xf
	v_add_f32_dpp v130, v130, v130 row_half_mirror row_mask:0xf bank_mask:0xf
	v_add_f32_dpp v131, v131, v131 row_half_mirror row_mask:0xf bank_mask:0xf
	v_add_f32_dpp v128, v128, v128 row_mirror row_mask:0xf bank_mask:0xf
	v_add_f32_dpp v129, v129, v129 row_mirror row_mask:0xf bank_mask:0xf
	v_add_f32_dpp v130, v130, v130 row_mirror row_mask:0xf bank_mask:0xf
	v_add_f32_dpp v131, v131, v131 row_mirror row_mask:0xf bank_mask:0xf
	v_add_f32_dpp v128, v128, v128 row_bcast:15 row_mask:0xa bank_mask:0xf
	v_add_f32_dpp v129, v129, v129 row_bcast:15 row_mask:0xa bank_mask:0xf
	v_add_f32_dpp v130, v130, v130 row_bcast:15 row_mask:0xa bank_mask:0xf
	v_add_f32_dpp v131, v131, v131 row_bcast:15 row_mask:0xa bank_mask:0xf
	s_waitcnt vmcnt(23) lgkmcnt(6)
	v_pk_add_f32 v[36:37], v[36:37], v[80:81]
	v_pk_add_f32 v[38:39], v[38:39], v[82:83]
	s_waitcnt vmcnt(22) lgkmcnt(4)
	v_pk_add_f32 v[40:41], v[40:41], v[84:85]
	v_pk_add_f32 v[42:43], v[42:43], v[86:87]
	s_waitcnt vmcnt(21) lgkmcnt(2)
	v_pk_add_f32 v[44:45], v[44:45], v[112:113]
	v_pk_add_f32 v[46:47], v[46:47], v[114:115]
	s_waitcnt vmcnt(20) lgkmcnt(0)
	v_pk_add_f32 v[48:49], v[48:49], v[116:117]
	v_pk_add_f32 v[50:51], v[50:51], v[118:119]
	v_add_u32_e32 v88, 0xc180, v75
	ds_read2_b32 v[80:81], v88 offset1:1
	ds_read2_b32 v[82:83], v88 offset0:2 offset1:3
	v_add_u32_e32 v89, 0xd1a0, v75
	ds_read2_b32 v[84:85], v89 offset1:1
	ds_read2_b32 v[86:87], v89 offset0:2 offset1:3
	v_add_u32_e32 v88, 0xe1c0, v75
	ds_read2_b32 v[112:113], v88 offset1:1
	ds_read2_b32 v[114:115], v88 offset0:2 offset1:3
	v_add_u32_e32 v89, 0xf1e0, v75
	ds_read2_b32 v[116:117], v89 offset1:1
	ds_read2_b32 v[118:119], v89 offset0:2 offset1:3
	v_add_u32_e32 v65, 0x40000, v64
	global_store_dwordx4 v65, v[36:39], s[80:81]
	v_pk_mul_f32 v[140:141], v[36:37], v[36:37]
	v_pk_mul_f32 v[142:143], v[38:39], v[38:39]
	v_pk_mul_f32 v[144:145], v[36:37], v[120:121]
	v_pk_mul_f32 v[146:147], v[38:39], v[122:123]
	v_lshrrev_b32_e32 v158, 1, v65
	v_add_f32_e32 v132, v140, v141
	v_and_b32_sdwa v148, v144, v157 dst_sel:DWORD dst_unused:UNUSED_PAD src0_sel:WORD_1 src1_sel:DWORD
	v_and_b32_sdwa v149, v145, v157 dst_sel:DWORD dst_unused:UNUSED_PAD src0_sel:WORD_1 src1_sel:DWORD
	v_and_b32_sdwa v150, v146, v157 dst_sel:DWORD dst_unused:UNUSED_PAD src0_sel:WORD_1 src1_sel:DWORD
	v_and_b32_sdwa v151, v147, v157 dst_sel:DWORD dst_unused:UNUSED_PAD src0_sel:WORD_1 src1_sel:DWORD
	v_add_f32_e32 v132, v132, v142
	v_add3_u32 v144, v144, v148, s14
	v_add3_u32 v145, v145, v149, s14
	v_add3_u32 v146, v146, v150, s14
	v_add3_u32 v147, v147, v151, s14
	v_add_f32_e32 v132, v132, v143
	v_and_b32_e32 v145, 0xffff0000, v145
	v_and_b32_e32 v147, 0xffff0000, v147
	s_nop 0
	v_or_b32_sdwa v152, v145, v144 dst_sel:DWORD dst_unused:UNUSED_PAD src0_sel:DWORD src1_sel:WORD_1
	v_or_b32_sdwa v153, v147, v146 dst_sel:DWORD dst_unused:UNUSED_PAD src0_sel:DWORD src1_sel:WORD_1
	global_store_dwordx2 v158, v[152:153], s[92:93]
	v_add_u32_e32 v74, 0x48000, v64
	global_store_dwordx4 v74, v[40:43], s[80:81]
	v_pk_mul_f32 v[140:141], v[40:41], v[40:41]
	v_pk_mul_f32 v[142:143], v[42:43], v[42:43]
	v_pk_mul_f32 v[144:145], v[40:41], v[120:121]
	v_pk_mul_f32 v[146:147], v[42:43], v[122:123]
	v_lshrrev_b32_e32 v159, 1, v74
	v_add_f32_e32 v133, v140, v141
	v_and_b32_sdwa v148, v144, v157 dst_sel:DWORD dst_unused:UNUSED_PAD src0_sel:WORD_1 src1_sel:DWORD
	v_and_b32_sdwa v149, v145, v157 dst_sel:DWORD dst_unused:UNUSED_PAD src0_sel:WORD_1 src1_sel:DWORD
	v_and_b32_sdwa v150, v146, v157 dst_sel:DWORD dst_unused:UNUSED_PAD src0_sel:WORD_1 src1_sel:DWORD
	v_and_b32_sdwa v151, v147, v157 dst_sel:DWORD dst_unused:UNUSED_PAD src0_sel:WORD_1 src1_sel:DWORD
	v_add_f32_e32 v133, v133, v142
	v_add3_u32 v144, v144, v148, s14
	v_add3_u32 v145, v145, v149, s14
	v_add3_u32 v146, v146, v150, s14
	v_add3_u32 v147, v147, v151, s14
	v_add_f32_e32 v133, v133, v143
	v_and_b32_e32 v145, 0xffff0000, v145
	v_and_b32_e32 v147, 0xffff0000, v147
	s_nop 0
	v_or_b32_sdwa v154, v145, v144 dst_sel:DWORD dst_unused:UNUSED_PAD src0_sel:DWORD src1_sel:WORD_1
	v_or_b32_sdwa v155, v147, v146 dst_sel:DWORD dst_unused:UNUSED_PAD src0_sel:DWORD src1_sel:WORD_1
	global_store_dwordx2 v159, v[154:155], s[92:93]
	v_add_u32_e32 v65, 0x50000, v64
	global_store_dwordx4 v65, v[44:47], s[80:81]
	v_pk_mul_f32 v[140:141], v[44:45], v[44:45]
	v_pk_mul_f32 v[142:143], v[46:47], v[46:47]
	v_pk_mul_f32 v[144:145], v[44:45], v[120:121]
	v_pk_mul_f32 v[146:147], v[46:47], v[122:123]
	v_lshrrev_b32_e32 v158, 1, v65
	v_add_f32_e32 v134, v140, v141
	v_and_b32_sdwa v148, v144, v157 dst_sel:DWORD dst_unused:UNUSED_PAD src0_sel:WORD_1 src1_sel:DWORD
	v_and_b32_sdwa v149, v145, v157 dst_sel:DWORD dst_unused:UNUSED_PAD src0_sel:WORD_1 src1_sel:DWORD
	v_and_b32_sdwa v150, v146, v157 dst_sel:DWORD dst_unused:UNUSED_PAD src0_sel:WORD_1 src1_sel:DWORD
	v_and_b32_sdwa v151, v147, v157 dst_sel:DWORD dst_unused:UNUSED_PAD src0_sel:WORD_1 src1_sel:DWORD
	v_add_f32_e32 v134, v134, v142
	v_add3_u32 v144, v144, v148, s14
	v_add3_u32 v145, v145, v149, s14
	v_add3_u32 v146, v146, v150, s14
	v_add3_u32 v147, v147, v151, s14
	v_add_f32_e32 v134, v134, v143
	v_and_b32_e32 v145, 0xffff0000, v145
	v_and_b32_e32 v147, 0xffff0000, v147
	s_nop 0
	v_or_b32_sdwa v152, v145, v144 dst_sel:DWORD dst_unused:UNUSED_PAD src0_sel:DWORD src1_sel:WORD_1
	v_or_b32_sdwa v153, v147, v146 dst_sel:DWORD dst_unused:UNUSED_PAD src0_sel:DWORD src1_sel:WORD_1
	global_store_dwordx2 v158, v[152:153], s[92:93]
	v_add_u32_e32 v74, 0x58000, v64
	global_store_dwordx4 v74, v[48:51], s[80:81]
	v_pk_mul_f32 v[140:141], v[48:49], v[48:49]
	v_pk_mul_f32 v[142:143], v[50:51], v[50:51]
	v_pk_mul_f32 v[144:145], v[48:49], v[120:121]
	v_pk_mul_f32 v[146:147], v[50:51], v[122:123]
	v_lshrrev_b32_e32 v159, 1, v74
	v_add_f32_e32 v135, v140, v141
	v_and_b32_sdwa v148, v144, v157 dst_sel:DWORD dst_unused:UNUSED_PAD src0_sel:WORD_1 src1_sel:DWORD
	v_and_b32_sdwa v149, v145, v157 dst_sel:DWORD dst_unused:UNUSED_PAD src0_sel:WORD_1 src1_sel:DWORD
	v_and_b32_sdwa v150, v146, v157 dst_sel:DWORD dst_unused:UNUSED_PAD src0_sel:WORD_1 src1_sel:DWORD
	v_and_b32_sdwa v151, v147, v157 dst_sel:DWORD dst_unused:UNUSED_PAD src0_sel:WORD_1 src1_sel:DWORD
	v_add_f32_e32 v135, v135, v142
	v_add3_u32 v144, v144, v148, s14
	v_add3_u32 v145, v145, v149, s14
	v_add3_u32 v146, v146, v150, s14
	v_add3_u32 v147, v147, v151, s14
	v_add_f32_e32 v135, v135, v143
	v_and_b32_e32 v145, 0xffff0000, v145
	v_and_b32_e32 v147, 0xffff0000, v147
	s_nop 0
	v_or_b32_sdwa v154, v145, v144 dst_sel:DWORD dst_unused:UNUSED_PAD src0_sel:DWORD src1_sel:WORD_1
	v_or_b32_sdwa v155, v147, v146 dst_sel:DWORD dst_unused:UNUSED_PAD src0_sel:DWORD src1_sel:WORD_1
	global_store_dwordx2 v159, v[154:155], s[92:93]
	s_nop 1
	v_add_f32_dpp v132, v132, v132 quad_perm:[1,0,3,2] row_mask:0xf bank_mask:0xf
	v_add_f32_dpp v133, v133, v133 quad_perm:[1,0,3,2] row_mask:0xf bank_mask:0xf
	v_add_f32_dpp v134, v134, v134 quad_perm:[1,0,3,2] row_mask:0xf bank_mask:0xf
	v_add_f32_dpp v135, v135, v135 quad_perm:[1,0,3,2] row_mask:0xf bank_mask:0xf
	v_add_f32_dpp v132, v132, v132 quad_perm:[2,3,0,1] row_mask:0xf bank_mask:0xf
	v_add_f32_dpp v133, v133, v133 quad_perm:[2,3,0,1] row_mask:0xf bank_mask:0xf
	v_add_f32_dpp v134, v134, v134 quad_perm:[2,3,0,1] row_mask:0xf bank_mask:0xf
	v_add_f32_dpp v135, v135, v135 quad_perm:[2,3,0,1] row_mask:0xf bank_mask:0xf
	v_add_f32_dpp v132, v132, v132 row_half_mirror row_mask:0xf bank_mask:0xf
	v_add_f32_dpp v133, v133, v133 row_half_mirror row_mask:0xf bank_mask:0xf
	v_add_f32_dpp v134, v134, v134 row_half_mirror row_mask:0xf bank_mask:0xf
	v_add_f32_dpp v135, v135, v135 row_half_mirror row_mask:0xf bank_mask:0xf
	v_add_f32_dpp v132, v132, v132 row_mirror row_mask:0xf bank_mask:0xf
	v_add_f32_dpp v133, v133, v133 row_mirror row_mask:0xf bank_mask:0xf
	v_add_f32_dpp v134, v134, v134 row_mirror row_mask:0xf bank_mask:0xf
	v_add_f32_dpp v135, v135, v135 row_mirror row_mask:0xf bank_mask:0xf
	v_add_f32_dpp v132, v132, v132 row_bcast:15 row_mask:0xa bank_mask:0xf
	v_add_f32_dpp v133, v133, v133 row_bcast:15 row_mask:0xa bank_mask:0xf
	v_add_f32_dpp v134, v134, v134 row_bcast:15 row_mask:0xa bank_mask:0xf
	v_add_f32_dpp v135, v135, v135 row_bcast:15 row_mask:0xa bank_mask:0xf
	s_waitcnt vmcnt(27) lgkmcnt(6)
	v_pk_add_f32 v[52:53], v[52:53], v[80:81]
	v_pk_add_f32 v[54:55], v[54:55], v[82:83]
	s_waitcnt vmcnt(26) lgkmcnt(4)
	v_pk_add_f32 v[56:57], v[56:57], v[84:85]
	v_pk_add_f32 v[58:59], v[58:59], v[86:87]
	s_waitcnt vmcnt(25) lgkmcnt(2)
	v_pk_add_f32 v[60:61], v[60:61], v[112:113]
	v_pk_add_f32 v[62:63], v[62:63], v[114:115]
	s_waitcnt vmcnt(24) lgkmcnt(0)
	v_pk_add_f32 v[76:77], v[76:77], v[116:117]
	v_pk_add_f32 v[78:79], v[78:79], v[118:119]
	v_add_u32_e32 v65, 0x60000, v64
	global_store_dwordx4 v65, v[52:55], s[80:81]
	v_pk_mul_f32 v[140:141], v[52:53], v[52:53]
	v_pk_mul_f32 v[142:143], v[54:55], v[54:55]
	v_pk_mul_f32 v[144:145], v[52:53], v[120:121]
	v_pk_mul_f32 v[146:147], v[54:55], v[122:123]
	v_lshrrev_b32_e32 v158, 1, v65
	v_add_f32_e32 v136, v140, v141
	v_and_b32_sdwa v148, v144, v157 dst_sel:DWORD dst_unused:UNUSED_PAD src0_sel:WORD_1 src1_sel:DWORD
	v_and_b32_sdwa v149, v145, v157 dst_sel:DWORD dst_unused:UNUSED_PAD src0_sel:WORD_1 src1_sel:DWORD
	v_and_b32_sdwa v150, v146, v157 dst_sel:DWORD dst_unused:UNUSED_PAD src0_sel:WORD_1 src1_sel:DWORD
	v_and_b32_sdwa v151, v147, v157 dst_sel:DWORD dst_unused:UNUSED_PAD src0_sel:WORD_1 src1_sel:DWORD
	v_add_f32_e32 v136, v136, v142
	v_add3_u32 v144, v144, v148, s14
	v_add3_u32 v145, v145, v149, s14
	v_add3_u32 v146, v146, v150, s14
	v_add3_u32 v147, v147, v151, s14
	v_add_f32_e32 v136, v136, v143
	v_and_b32_e32 v145, 0xffff0000, v145
	v_and_b32_e32 v147, 0xffff0000, v147
	s_nop 0
	v_or_b32_sdwa v152, v145, v144 dst_sel:DWORD dst_unused:UNUSED_PAD src0_sel:DWORD src1_sel:WORD_1
	v_or_b32_sdwa v153, v147, v146 dst_sel:DWORD dst_unused:UNUSED_PAD src0_sel:DWORD src1_sel:WORD_1
	global_store_dwordx2 v158, v[152:153], s[92:93]
	v_add_u32_e32 v74, 0x68000, v64
	global_store_dwordx4 v74, v[56:59], s[80:81]
	v_pk_mul_f32 v[140:141], v[56:57], v[56:57]
	v_pk_mul_f32 v[142:143], v[58:59], v[58:59]
	v_pk_mul_f32 v[144:145], v[56:57], v[120:121]
	v_pk_mul_f32 v[146:147], v[58:59], v[122:123]
	v_lshrrev_b32_e32 v159, 1, v74
	v_add_f32_e32 v137, v140, v141
	v_and_b32_sdwa v148, v144, v157 dst_sel:DWORD dst_unused:UNUSED_PAD src0_sel:WORD_1 src1_sel:DWORD
	v_and_b32_sdwa v149, v145, v157 dst_sel:DWORD dst_unused:UNUSED_PAD src0_sel:WORD_1 src1_sel:DWORD
	v_and_b32_sdwa v150, v146, v157 dst_sel:DWORD dst_unused:UNUSED_PAD src0_sel:WORD_1 src1_sel:DWORD
	v_and_b32_sdwa v151, v147, v157 dst_sel:DWORD dst_unused:UNUSED_PAD src0_sel:WORD_1 src1_sel:DWORD
	v_add_f32_e32 v137, v137, v142
	v_add3_u32 v144, v144, v148, s14
	v_add3_u32 v145, v145, v149, s14
	v_add3_u32 v146, v146, v150, s14
	v_add3_u32 v147, v147, v151, s14
	v_add_f32_e32 v137, v137, v143
	v_and_b32_e32 v145, 0xffff0000, v145
	v_and_b32_e32 v147, 0xffff0000, v147
	s_nop 0
	v_or_b32_sdwa v154, v145, v144 dst_sel:DWORD dst_unused:UNUSED_PAD src0_sel:DWORD src1_sel:WORD_1
	v_or_b32_sdwa v155, v147, v146 dst_sel:DWORD dst_unused:UNUSED_PAD src0_sel:DWORD src1_sel:WORD_1
	global_store_dwordx2 v159, v[154:155], s[92:93]
	v_add_u32_e32 v65, 0x70000, v64
	global_store_dwordx4 v65, v[60:63], s[80:81]
	v_pk_mul_f32 v[140:141], v[60:61], v[60:61]
	v_pk_mul_f32 v[142:143], v[62:63], v[62:63]
	v_pk_mul_f32 v[144:145], v[60:61], v[120:121]
	v_pk_mul_f32 v[146:147], v[62:63], v[122:123]
	v_lshrrev_b32_e32 v158, 1, v65
	v_add_f32_e32 v138, v140, v141
	v_and_b32_sdwa v148, v144, v157 dst_sel:DWORD dst_unused:UNUSED_PAD src0_sel:WORD_1 src1_sel:DWORD
	v_and_b32_sdwa v149, v145, v157 dst_sel:DWORD dst_unused:UNUSED_PAD src0_sel:WORD_1 src1_sel:DWORD
	v_and_b32_sdwa v150, v146, v157 dst_sel:DWORD dst_unused:UNUSED_PAD src0_sel:WORD_1 src1_sel:DWORD
	v_and_b32_sdwa v151, v147, v157 dst_sel:DWORD dst_unused:UNUSED_PAD src0_sel:WORD_1 src1_sel:DWORD
	v_add_f32_e32 v138, v138, v142
	v_add3_u32 v144, v144, v148, s14
	v_add3_u32 v145, v145, v149, s14
	v_add3_u32 v146, v146, v150, s14
	v_add3_u32 v147, v147, v151, s14
	v_add_f32_e32 v138, v138, v143
	v_and_b32_e32 v145, 0xffff0000, v145
	v_and_b32_e32 v147, 0xffff0000, v147
	s_nop 0
	v_or_b32_sdwa v152, v145, v144 dst_sel:DWORD dst_unused:UNUSED_PAD src0_sel:DWORD src1_sel:WORD_1
	v_or_b32_sdwa v153, v147, v146 dst_sel:DWORD dst_unused:UNUSED_PAD src0_sel:DWORD src1_sel:WORD_1
	global_store_dwordx2 v158, v[152:153], s[92:93]
	v_add_u32_e32 v74, 0x78000, v64
	global_store_dwordx4 v74, v[76:79], s[80:81]
	v_pk_mul_f32 v[140:141], v[76:77], v[76:77]
	v_pk_mul_f32 v[142:143], v[78:79], v[78:79]
	v_pk_mul_f32 v[144:145], v[76:77], v[120:121]
	v_pk_mul_f32 v[146:147], v[78:79], v[122:123]
	v_lshrrev_b32_e32 v159, 1, v74
	v_add_f32_e32 v139, v140, v141
	v_and_b32_sdwa v148, v144, v157 dst_sel:DWORD dst_unused:UNUSED_PAD src0_sel:WORD_1 src1_sel:DWORD
	v_and_b32_sdwa v149, v145, v157 dst_sel:DWORD dst_unused:UNUSED_PAD src0_sel:WORD_1 src1_sel:DWORD
	v_and_b32_sdwa v150, v146, v157 dst_sel:DWORD dst_unused:UNUSED_PAD src0_sel:WORD_1 src1_sel:DWORD
	v_and_b32_sdwa v151, v147, v157 dst_sel:DWORD dst_unused:UNUSED_PAD src0_sel:WORD_1 src1_sel:DWORD
	v_add_f32_e32 v139, v139, v142
	v_add3_u32 v144, v144, v148, s14
	v_add3_u32 v145, v145, v149, s14
	v_add3_u32 v146, v146, v150, s14
	v_add3_u32 v147, v147, v151, s14
	v_add_f32_e32 v139, v139, v143
	v_and_b32_e32 v145, 0xffff0000, v145
	v_and_b32_e32 v147, 0xffff0000, v147
	s_nop 0
	v_or_b32_sdwa v154, v145, v144 dst_sel:DWORD dst_unused:UNUSED_PAD src0_sel:DWORD src1_sel:WORD_1
	v_or_b32_sdwa v155, v147, v146 dst_sel:DWORD dst_unused:UNUSED_PAD src0_sel:DWORD src1_sel:WORD_1
	global_store_dwordx2 v159, v[154:155], s[92:93]
	s_nop 1
	v_add_f32_dpp v136, v136, v136 quad_perm:[1,0,3,2] row_mask:0xf bank_mask:0xf
	v_add_f32_dpp v137, v137, v137 quad_perm:[1,0,3,2] row_mask:0xf bank_mask:0xf
	v_add_f32_dpp v138, v138, v138 quad_perm:[1,0,3,2] row_mask:0xf bank_mask:0xf
	v_add_f32_dpp v139, v139, v139 quad_perm:[1,0,3,2] row_mask:0xf bank_mask:0xf
	v_add_f32_dpp v136, v136, v136 quad_perm:[2,3,0,1] row_mask:0xf bank_mask:0xf
	v_add_f32_dpp v137, v137, v137 quad_perm:[2,3,0,1] row_mask:0xf bank_mask:0xf
	v_add_f32_dpp v138, v138, v138 quad_perm:[2,3,0,1] row_mask:0xf bank_mask:0xf
	v_add_f32_dpp v139, v139, v139 quad_perm:[2,3,0,1] row_mask:0xf bank_mask:0xf
	v_add_f32_dpp v136, v136, v136 row_half_mirror row_mask:0xf bank_mask:0xf
	v_add_f32_dpp v137, v137, v137 row_half_mirror row_mask:0xf bank_mask:0xf
	v_add_f32_dpp v138, v138, v138 row_half_mirror row_mask:0xf bank_mask:0xf
	v_add_f32_dpp v139, v139, v139 row_half_mirror row_mask:0xf bank_mask:0xf
	v_add_f32_dpp v136, v136, v136 row_mirror row_mask:0xf bank_mask:0xf
	v_add_f32_dpp v137, v137, v137 row_mirror row_mask:0xf bank_mask:0xf
	v_add_f32_dpp v138, v138, v138 row_mirror row_mask:0xf bank_mask:0xf
	v_add_f32_dpp v139, v139, v139 row_mirror row_mask:0xf bank_mask:0xf
	v_add_f32_dpp v136, v136, v136 row_bcast:15 row_mask:0xa bank_mask:0xf
	v_add_f32_dpp v137, v137, v137 row_bcast:15 row_mask:0xa bank_mask:0xf
	v_add_f32_dpp v138, v138, v138 row_bcast:15 row_mask:0xa bank_mask:0xf
	v_add_f32_dpp v139, v139, v139 row_bcast:15 row_mask:0xa bank_mask:0xf
	s_nop 1
	s_mov_b32 exec_lo, 0x80000000
	s_mov_b32 exec_hi, 0x80000000
	global_atomic_add_f32 v156, v124, s[10:11]
	global_atomic_add_f32 v156, v125, s[10:11] offset:32
	global_atomic_add_f32 v156, v126, s[10:11] offset:64
	global_atomic_add_f32 v156, v127, s[10:11] offset:96
	global_atomic_add_f32 v156, v128, s[10:11] offset:128
	global_atomic_add_f32 v156, v129, s[10:11] offset:160
	global_atomic_add_f32 v156, v130, s[10:11] offset:192
	global_atomic_add_f32 v156, v131, s[10:11] offset:224
	global_atomic_add_f32 v156, v132, s[10:11] offset:256
	global_atomic_add_f32 v156, v133, s[10:11] offset:288
	global_atomic_add_f32 v156, v134, s[10:11] offset:320
	global_atomic_add_f32 v156, v135, s[10:11] offset:352
	global_atomic_add_f32 v156, v136, s[10:11] offset:384
	global_atomic_add_f32 v156, v137, s[10:11] offset:416
	global_atomic_add_f32 v156, v138, s[10:11] offset:448
	global_atomic_add_f32 v156, v139, s[10:11] offset:480
	s_mov_b64 exec, -1
	s_branch .LBB0_299

.LBB0_563:
	s_and_b32 s4, s15, 0x1ffffc0
	s_lshl_b32 s5, s15, 3
	s_and_b32 s5, s5, 56
	s_or_b32 s4, s4, s3
	s_or_b32 s4, s4, s5
	s_lshl_b32 s12, s4, 7
	s_lshl_b32 s4, s15, 4
	s_and_b32 s23, s4, 0x380
	s_lshl_b64 s[4:5], s[12:13], 11
	v_lshl_add_u64 v[74:75], v[70:71], 0, s[4:5]
	v_add_co_u32_e64 v78, s[4:5], s19, v74
	s_lshl_b32 s12, s23, 11
	s_nop 0
	v_addc_co_u32_e64 v79, s[4:5], 0, v75, s[4:5]
	v_add_co_u32_e64 v80, s[4:5], s20, v74
	v_lshl_add_u64 v[76:77], v[72:73], 0, s[12:13]
	s_nop 0
	v_addc_co_u32_e64 v81, s[4:5], 0, v75, s[4:5]
	v_add_co_u32_e64 v82, s[4:5], s21, v74
	global_load_dwordx4 v[2:5], v[74:75], off
	global_load_dwordx4 v[6:9], v[78:79], off
	v_addc_co_u32_e64 v83, s[4:5], 0, v75, s[4:5]
	global_load_dwordx4 v[10:13], v[80:81], off
	global_load_dwordx4 v[14:17], v[82:83], off
	global_load_dwordx4 v[18:21], v[76:77], off
	v_add_co_u32_e64 v84, s[4:5], s19, v76
	s_nop 1
	v_addc_co_u32_e64 v85, s[4:5], 0, v77, s[4:5]
	v_add_co_u32_e64 v86, s[4:5], s20, v76
	global_load_dwordx4 v[22:25], v[84:85], off
	s_nop 0
	v_addc_co_u32_e64 v87, s[4:5], 0, v77, s[4:5]
	global_load_dwordx4 v[26:29], v[86:87], off
	v_add_co_u32_e64 v88, s[4:5], s21, v76
	s_nop 1
	v_addc_co_u32_e64 v89, s[4:5], 0, v77, s[4:5]
	global_load_dwordx4 v[30:33], v[88:89], off
	global_load_dwordx4 v[118:121], v[74:75], off offset:128
	global_load_dwordx4 v[122:125], v[76:77], off offset:128
	global_load_dwordx4 v[126:129], v[78:79], off offset:128
	global_load_dwordx4 v[130:133], v[80:81], off offset:128
	global_load_dwordx4 v[134:137], v[82:83], off offset:128
	global_load_dwordx4 v[138:141], v[84:85], off offset:128
	global_load_dwordx4 v[142:145], v[86:87], off offset:128
	global_load_dwordx4 v[146:149], v[88:89], off offset:128
	s_lshl_b32 s4, s15, 7
	s_and_b32 s4, s4, 0xffffe000
	s_lshl_b32 s5, s16, 7
	s_or_b32 s4, s4, s18
	s_and_b32 s5, s5, 0x1c00
	s_or_b32 s4, s5, s4
	v_add_u32_e32 v116, s4, v1
	s_waitcnt vmcnt(15)
	ds_write_b128 v90, v[2:5]
	s_waitcnt vmcnt(11)
	ds_write_b128 v90, v[18:21] offset:36864
	ds_write_b128 v90, v[6:9] offset:4608
	ds_write_b128 v90, v[10:13] offset:9216
	ds_write_b128 v90, v[14:17] offset:13824
	s_waitcnt vmcnt(10)
	ds_write_b128 v90, v[22:25] offset:41472
	s_waitcnt vmcnt(9)
	ds_write_b128 v90, v[26:29] offset:46080
	s_waitcnt vmcnt(8)
	ds_write_b128 v90, v[30:33] offset:50688
	s_waitcnt lgkmcnt(0)
	s_barrier
	global_load_dwordx4 v[158:161], v[78:79], off offset:256
	global_load_dwordx4 v[162:165], v[80:81], off offset:256
	global_load_dwordx4 v[150:153], v[74:75], off offset:256
	global_load_dwordx4 v[154:157], v[76:77], off offset:256
	global_load_dwordx4 v[166:169], v[82:83], off offset:256
	global_load_dwordx4 v[170:173], v[84:85], off offset:256
	global_load_dwordx4 v[174:177], v[86:87], off offset:256
	global_load_dwordx4 v[178:181], v[88:89], off offset:256
	global_load_dwordx4 v[218:221], v[78:79], off offset:384
	global_load_dwordx4 v[222:225], v[80:81], off offset:384
	global_load_dwordx4 v[210:213], v[74:75], off offset:384
	global_load_dwordx4 v[214:217], v[76:77], off offset:384
	global_load_dwordx4 v[226:229], v[82:83], off offset:384
	global_load_dwordx4 v[230:233], v[84:85], off offset:384
	global_load_dwordx4 v[234:237], v[86:87], off offset:384
	global_load_dwordx4 v[238:241], v[88:89], off offset:384
	ds_read_b128 v[18:21], v66
	ds_read_b128 v[34:37], v67 offset:36864
	ds_read_b128 v[182:185], v66 offset:32
	ds_read_b128 v[186:189], v67 offset:36896
	ds_read_b128 v[50:53], v67 offset:41472
	ds_read_b128 v[190:193], v67 offset:41504
	ds_read_b128 v[54:57], v66 offset:4608
	ds_read_b128 v[194:197], v66 offset:4640
	s_waitcnt lgkmcnt(6)
	v_mfma_f32_32x32x16_bf16 v[2:17], v[18:21], v[34:37], 0
	s_waitcnt lgkmcnt(3)
	v_mfma_f32_32x32x16_bf16 v[18:33], v[18:21], v[50:53], 0
	s_waitcnt lgkmcnt(1)
	v_mfma_f32_32x32x16_bf16 v[34:49], v[54:57], v[34:37], 0
	v_mfma_f32_32x32x16_bf16 v[50:65], v[54:57], v[50:53], 0
	v_mfma_f32_32x32x16_bf16 v[2:17], v[182:185], v[186:189], v[2:17]
	v_mfma_f32_32x32x16_bf16 v[18:33], v[182:185], v[190:193], v[18:33]
	s_waitcnt lgkmcnt(0)
	v_mfma_f32_32x32x16_bf16 v[34:49], v[194:197], v[186:189], v[34:49]
	v_mfma_f32_32x32x16_bf16 v[50:65], v[194:197], v[190:193], v[50:65]
	ds_read_b128 v[182:185], v66 offset:64
	ds_read_b128 v[186:189], v67 offset:36928
	ds_read_b128 v[190:193], v66 offset:96
	ds_read_b128 v[194:197], v67 offset:36960
	ds_read_b128 v[198:201], v67 offset:41536
	ds_read_b128 v[202:205], v67 offset:41568
	s_waitcnt lgkmcnt(4)
	v_mfma_f32_32x32x16_bf16 v[2:17], v[182:185], v[186:189], v[2:17]
	s_waitcnt lgkmcnt(1)
	v_mfma_f32_32x32x16_bf16 v[18:33], v[182:185], v[198:201], v[18:33]
	ds_read_b128 v[182:185], v66 offset:4672
	ds_read_b128 v[206:209], v66 offset:4704
	s_waitcnt vmcnt(16)
	ds_write_b128 v90, v[118:121] offset:18432
	ds_write_b128 v90, v[126:129] offset:23040
	ds_write_b128 v90, v[130:133] offset:27648
	ds_write_b128 v90, v[134:137] offset:32256
	ds_write_b128 v90, v[122:125] offset:55296
	ds_write_b128 v90, v[138:141] offset:59904
	ds_write_b128 v90, v[142:145] offset:64512
	ds_write_b128 v91, v[146:149] offset:32256
	global_load_dwordx4 v[126:129], v[78:79], off offset:512
	global_load_dwordx4 v[130:133], v[80:81], off offset:512
	global_load_dwordx4 v[118:121], v[74:75], off offset:512
	global_load_dwordx4 v[122:125], v[76:77], off offset:512
	global_load_dwordx4 v[134:137], v[82:83], off offset:512
	global_load_dwordx4 v[138:141], v[84:85], off offset:512
	global_load_dwordx4 v[142:145], v[86:87], off offset:512
	global_load_dwordx4 v[146:149], v[88:89], off offset:512
	s_waitcnt lgkmcnt(0)
	s_barrier
	v_mfma_f32_32x32x16_bf16 v[34:49], v[182:185], v[186:189], v[34:49]
	v_mfma_f32_32x32x16_bf16 v[50:65], v[182:185], v[198:201], v[50:65]
	v_mfma_f32_32x32x16_bf16 v[2:17], v[190:193], v[194:197], v[2:17]
	v_mfma_f32_32x32x16_bf16 v[18:33], v[190:193], v[202:205], v[18:33]
	v_mfma_f32_32x32x16_bf16 v[34:49], v[206:209], v[194:197], v[34:49]
	v_mfma_f32_32x32x16_bf16 v[50:65], v[206:209], v[202:205], v[50:65]
	ds_read_b128 v[182:185], v66 offset:18432
	ds_read_b128 v[186:189], v67 offset:55296
	ds_read_b128 v[190:193], v66 offset:18464
	ds_read_b128 v[194:197], v67 offset:55328
	ds_read_b128 v[198:201], v67 offset:59904
	ds_read_b128 v[202:205], v67 offset:59936
	s_waitcnt lgkmcnt(4)
	v_mfma_f32_32x32x16_bf16 v[2:17], v[182:185], v[186:189], v[2:17]
	s_waitcnt lgkmcnt(1)
	v_mfma_f32_32x32x16_bf16 v[18:33], v[182:185], v[198:201], v[18:33]
	ds_read_b128 v[182:185], v66 offset:23040
	ds_read_b128 v[206:209], v66 offset:23072
	s_waitcnt lgkmcnt(1)
	v_mfma_f32_32x32x16_bf16 v[34:49], v[182:185], v[186:189], v[34:49]
	v_mfma_f32_32x32x16_bf16 v[50:65], v[182:185], v[198:201], v[50:65]
	v_mfma_f32_32x32x16_bf16 v[2:17], v[190:193], v[194:197], v[2:17]
	v_mfma_f32_32x32x16_bf16 v[18:33], v[190:193], v[202:205], v[18:33]
	s_waitcnt lgkmcnt(0)
	v_mfma_f32_32x32x16_bf16 v[34:49], v[206:209], v[194:197], v[34:49]
	ds_read_b128 v[182:185], v66 offset:18496
	ds_read_b128 v[186:189], v67 offset:55360
	ds_read_b128 v[190:193], v66 offset:18528
	ds_read_b128 v[194:197], v67 offset:55392
	v_mfma_f32_32x32x16_bf16 v[50:65], v[206:209], v[202:205], v[50:65]
	ds_read_b128 v[198:201], v67 offset:59968
	ds_read_b128 v[202:205], v67 offset:60000
	s_waitcnt lgkmcnt(4)
	v_mfma_f32_32x32x16_bf16 v[2:17], v[182:185], v[186:189], v[2:17]
	s_waitcnt lgkmcnt(1)
	v_mfma_f32_32x32x16_bf16 v[18:33], v[182:185], v[198:201], v[18:33]
	ds_read_b128 v[182:185], v66 offset:23104
	ds_read_b128 v[206:209], v66 offset:23136
	s_waitcnt vmcnt(16)
	ds_write_b128 v90, v[150:153]
	ds_write_b128 v90, v[158:161] offset:4608
	ds_write_b128 v90, v[162:165] offset:9216
	ds_write_b128 v90, v[166:169] offset:13824
	ds_write_b128 v90, v[154:157] offset:36864
	ds_write_b128 v90, v[170:173] offset:41472
	ds_write_b128 v90, v[174:177] offset:46080
	ds_write_b128 v90, v[178:181] offset:50688
	global_load_dwordx4 v[158:161], v[78:79], off offset:640
	global_load_dwordx4 v[162:165], v[80:81], off offset:640
	global_load_dwordx4 v[150:153], v[74:75], off offset:640
	global_load_dwordx4 v[154:157], v[76:77], off offset:640
	global_load_dwordx4 v[166:169], v[82:83], off offset:640
	global_load_dwordx4 v[170:173], v[84:85], off offset:640
	global_load_dwordx4 v[174:177], v[86:87], off offset:640
	global_load_dwordx4 v[178:181], v[88:89], off offset:640
	s_waitcnt lgkmcnt(0)
	s_barrier
	v_mfma_f32_32x32x16_bf16 v[34:49], v[182:185], v[186:189], v[34:49]
	v_mfma_f32_32x32x16_bf16 v[50:65], v[182:185], v[198:201], v[50:65]
	v_mfma_f32_32x32x16_bf16 v[2:17], v[190:193], v[194:197], v[2:17]
	v_mfma_f32_32x32x16_bf16 v[18:33], v[190:193], v[202:205], v[18:33]
	v_mfma_f32_32x32x16_bf16 v[34:49], v[206:209], v[194:197], v[34:49]
	v_mfma_f32_32x32x16_bf16 v[50:65], v[206:209], v[202:205], v[50:65]
	ds_read_b128 v[182:185], v66
	ds_read_b128 v[186:189], v67 offset:36864
	ds_read_b128 v[190:193], v66 offset:32
	ds_read_b128 v[194:197], v67 offset:36896
	ds_read_b128 v[198:201], v67 offset:41472
	ds_read_b128 v[202:205], v67 offset:41504
	s_waitcnt lgkmcnt(4)
	v_mfma_f32_32x32x16_bf16 v[2:17], v[182:185], v[186:189], v[2:17]
	s_waitcnt lgkmcnt(1)
	v_mfma_f32_32x32x16_bf16 v[18:33], v[182:185], v[198:201], v[18:33]
	ds_read_b128 v[182:185], v66 offset:4608
	ds_read_b128 v[206:209], v66 offset:4640
	s_waitcnt lgkmcnt(1)
	v_mfma_f32_32x32x16_bf16 v[34:49], v[182:185], v[186:189], v[34:49]
	v_mfma_f32_32x32x16_bf16 v[50:65], v[182:185], v[198:201], v[50:65]
	v_mfma_f32_32x32x16_bf16 v[2:17], v[190:193], v[194:197], v[2:17]
	v_mfma_f32_32x32x16_bf16 v[18:33], v[190:193], v[202:205], v[18:33]
	s_waitcnt lgkmcnt(0)
	v_mfma_f32_32x32x16_bf16 v[34:49], v[206:209], v[194:197], v[34:49]
	ds_read_b128 v[182:185], v66 offset:64
	ds_read_b128 v[186:189], v67 offset:36928
	ds_read_b128 v[190:193], v66 offset:96
	ds_read_b128 v[194:197], v67 offset:36960
	v_mfma_f32_32x32x16_bf16 v[50:65], v[206:209], v[202:205], v[50:65]
	ds_read_b128 v[198:201], v67 offset:41536
	ds_read_b128 v[202:205], v67 offset:41568
	s_waitcnt lgkmcnt(4)
	v_mfma_f32_32x32x16_bf16 v[2:17], v[182:185], v[186:189], v[2:17]
	s_waitcnt lgkmcnt(1)
	v_mfma_f32_32x32x16_bf16 v[18:33], v[182:185], v[198:201], v[18:33]
	ds_read_b128 v[182:185], v66 offset:4672
	ds_read_b128 v[206:209], v66 offset:4704
	s_waitcnt vmcnt(16)
	ds_write_b128 v90, v[210:213] offset:18432
	ds_write_b128 v90, v[218:221] offset:23040
	ds_write_b128 v90, v[222:225] offset:27648
	ds_write_b128 v90, v[226:229] offset:32256
	ds_write_b128 v90, v[214:217] offset:55296
	ds_write_b128 v90, v[230:233] offset:59904
	ds_write_b128 v90, v[234:237] offset:64512
	ds_write_b128 v91, v[238:241] offset:32256
	global_load_dwordx4 v[218:221], v[78:79], off offset:768
	global_load_dwordx4 v[222:225], v[80:81], off offset:768
	global_load_dwordx4 v[210:213], v[74:75], off offset:768
	global_load_dwordx4 v[214:217], v[76:77], off offset:768
	global_load_dwordx4 v[226:229], v[82:83], off offset:768
	global_load_dwordx4 v[230:233], v[84:85], off offset:768
	global_load_dwordx4 v[234:237], v[86:87], off offset:768
	global_load_dwordx4 v[238:241], v[88:89], off offset:768
	s_waitcnt lgkmcnt(0)
	s_barrier
	v_mfma_f32_32x32x16_bf16 v[34:49], v[182:185], v[186:189], v[34:49]
	v_mfma_f32_32x32x16_bf16 v[50:65], v[182:185], v[198:201], v[50:65]
	v_mfma_f32_32x32x16_bf16 v[2:17], v[190:193], v[194:197], v[2:17]
	v_mfma_f32_32x32x16_bf16 v[18:33], v[190:193], v[202:205], v[18:33]
	v_mfma_f32_32x32x16_bf16 v[34:49], v[206:209], v[194:197], v[34:49]
	v_mfma_f32_32x32x16_bf16 v[50:65], v[206:209], v[202:205], v[50:65]
	ds_read_b128 v[182:185], v66 offset:18432
	ds_read_b128 v[186:189], v67 offset:55296
	ds_read_b128 v[190:193], v66 offset:18464
	ds_read_b128 v[194:197], v67 offset:55328
	ds_read_b128 v[198:201], v67 offset:59904
	ds_read_b128 v[202:205], v67 offset:59936
	s_waitcnt lgkmcnt(4)
	v_mfma_f32_32x32x16_bf16 v[2:17], v[182:185], v[186:189], v[2:17]
	s_waitcnt lgkmcnt(1)
	v_mfma_f32_32x32x16_bf16 v[18:33], v[182:185], v[198:201], v[18:33]
	ds_read_b128 v[182:185], v66 offset:23040
	ds_read_b128 v[206:209], v66 offset:23072
	s_waitcnt lgkmcnt(1)
	v_mfma_f32_32x32x16_bf16 v[34:49], v[182:185], v[186:189], v[34:49]
	v_mfma_f32_32x32x16_bf16 v[50:65], v[182:185], v[198:201], v[50:65]
	v_mfma_f32_32x32x16_bf16 v[2:17], v[190:193], v[194:197], v[2:17]
	v_mfma_f32_32x32x16_bf16 v[18:33], v[190:193], v[202:205], v[18:33]
	s_waitcnt lgkmcnt(0)
	v_mfma_f32_32x32x16_bf16 v[34:49], v[206:209], v[194:197], v[34:49]
	ds_read_b128 v[182:185], v66 offset:18496
	ds_read_b128 v[186:189], v67 offset:55360
	ds_read_b128 v[190:193], v66 offset:18528
	ds_read_b128 v[194:197], v67 offset:55392
	v_mfma_f32_32x32x16_bf16 v[50:65], v[206:209], v[202:205], v[50:65]
	ds_read_b128 v[198:201], v67 offset:59968
	ds_read_b128 v[202:205], v67 offset:60000
	s_waitcnt lgkmcnt(4)
	v_mfma_f32_32x32x16_bf16 v[2:17], v[182:185], v[186:189], v[2:17]
	s_waitcnt lgkmcnt(1)
	v_mfma_f32_32x32x16_bf16 v[18:33], v[182:185], v[198:201], v[18:33]
	ds_read_b128 v[182:185], v66 offset:23104
	ds_read_b128 v[206:209], v66 offset:23136
	s_waitcnt vmcnt(16)
	ds_write_b128 v90, v[118:121]
	ds_write_b128 v90, v[126:129] offset:4608
	ds_write_b128 v90, v[130:133] offset:9216
	ds_write_b128 v90, v[134:137] offset:13824
	ds_write_b128 v90, v[122:125] offset:36864
	ds_write_b128 v90, v[138:141] offset:41472
	ds_write_b128 v90, v[142:145] offset:46080
	ds_write_b128 v90, v[146:149] offset:50688
	global_load_dwordx4 v[126:129], v[78:79], off offset:896
	global_load_dwordx4 v[130:133], v[80:81], off offset:896
	global_load_dwordx4 v[118:121], v[74:75], off offset:896
	global_load_dwordx4 v[122:125], v[76:77], off offset:896
	global_load_dwordx4 v[134:137], v[82:83], off offset:896
	global_load_dwordx4 v[138:141], v[84:85], off offset:896
	global_load_dwordx4 v[142:145], v[86:87], off offset:896
	global_load_dwordx4 v[146:149], v[88:89], off offset:896
	s_waitcnt lgkmcnt(0)
	s_barrier
	v_mfma_f32_32x32x16_bf16 v[34:49], v[182:185], v[186:189], v[34:49]
	v_mfma_f32_32x32x16_bf16 v[50:65], v[182:185], v[198:201], v[50:65]
	v_mfma_f32_32x32x16_bf16 v[2:17], v[190:193], v[194:197], v[2:17]
	v_mfma_f32_32x32x16_bf16 v[18:33], v[190:193], v[202:205], v[18:33]
	v_mfma_f32_32x32x16_bf16 v[34:49], v[206:209], v[194:197], v[34:49]
	v_mfma_f32_32x32x16_bf16 v[50:65], v[206:209], v[202:205], v[50:65]
	ds_read_b128 v[182:185], v66
	ds_read_b128 v[186:189], v67 offset:36864
	ds_read_b128 v[190:193], v66 offset:32
	ds_read_b128 v[194:197], v67 offset:36896
	ds_read_b128 v[198:201], v67 offset:41472
	ds_read_b128 v[202:205], v67 offset:41504
	s_waitcnt lgkmcnt(4)
	v_mfma_f32_32x32x16_bf16 v[2:17], v[182:185], v[186:189], v[2:17]
	s_waitcnt lgkmcnt(1)
	v_mfma_f32_32x32x16_bf16 v[18:33], v[182:185], v[198:201], v[18:33]
	ds_read_b128 v[182:185], v66 offset:4608
	ds_read_b128 v[206:209], v66 offset:4640
	s_waitcnt lgkmcnt(1)
	v_mfma_f32_32x32x16_bf16 v[34:49], v[182:185], v[186:189], v[34:49]
	v_mfma_f32_32x32x16_bf16 v[50:65], v[182:185], v[198:201], v[50:65]
	v_mfma_f32_32x32x16_bf16 v[2:17], v[190:193], v[194:197], v[2:17]
	v_mfma_f32_32x32x16_bf16 v[18:33], v[190:193], v[202:205], v[18:33]
	s_waitcnt lgkmcnt(0)
	v_mfma_f32_32x32x16_bf16 v[34:49], v[206:209], v[194:197], v[34:49]
	ds_read_b128 v[182:185], v66 offset:64
	ds_read_b128 v[186:189], v67 offset:36928
	ds_read_b128 v[190:193], v66 offset:96
	ds_read_b128 v[194:197], v67 offset:36960
	v_mfma_f32_32x32x16_bf16 v[50:65], v[206:209], v[202:205], v[50:65]
	ds_read_b128 v[198:201], v67 offset:41536
	ds_read_b128 v[202:205], v67 offset:41568
	s_waitcnt lgkmcnt(4)
	v_mfma_f32_32x32x16_bf16 v[2:17], v[182:185], v[186:189], v[2:17]
	s_waitcnt lgkmcnt(1)
	v_mfma_f32_32x32x16_bf16 v[18:33], v[182:185], v[198:201], v[18:33]
	ds_read_b128 v[182:185], v66 offset:4672
	ds_read_b128 v[206:209], v66 offset:4704
	s_waitcnt vmcnt(16)
	ds_write_b128 v90, v[150:153] offset:18432
	ds_write_b128 v90, v[158:161] offset:23040
	ds_write_b128 v90, v[162:165] offset:27648
	ds_write_b128 v90, v[166:169] offset:32256
	ds_write_b128 v90, v[154:157] offset:55296
	ds_write_b128 v90, v[170:173] offset:59904
	ds_write_b128 v90, v[174:177] offset:64512
	ds_write_b128 v91, v[178:181] offset:32256
	global_load_dwordx4 v[158:161], v[78:79], off offset:1024
	global_load_dwordx4 v[162:165], v[80:81], off offset:1024
	global_load_dwordx4 v[150:153], v[74:75], off offset:1024
	global_load_dwordx4 v[154:157], v[76:77], off offset:1024
	global_load_dwordx4 v[166:169], v[82:83], off offset:1024
	global_load_dwordx4 v[170:173], v[84:85], off offset:1024
	global_load_dwordx4 v[174:177], v[86:87], off offset:1024
	global_load_dwordx4 v[178:181], v[88:89], off offset:1024
	s_waitcnt lgkmcnt(0)
	s_barrier
	v_mfma_f32_32x32x16_bf16 v[34:49], v[182:185], v[186:189], v[34:49]
	v_mfma_f32_32x32x16_bf16 v[50:65], v[182:185], v[198:201], v[50:65]
	v_mfma_f32_32x32x16_bf16 v[2:17], v[190:193], v[194:197], v[2:17]
	v_mfma_f32_32x32x16_bf16 v[18:33], v[190:193], v[202:205], v[18:33]
	v_mfma_f32_32x32x16_bf16 v[34:49], v[206:209], v[194:197], v[34:49]
	v_mfma_f32_32x32x16_bf16 v[50:65], v[206:209], v[202:205], v[50:65]
	ds_read_b128 v[182:185], v66 offset:18432
	ds_read_b128 v[186:189], v67 offset:55296
	ds_read_b128 v[190:193], v66 offset:18464
	ds_read_b128 v[194:197], v67 offset:55328
	ds_read_b128 v[198:201], v67 offset:59904
	ds_read_b128 v[202:205], v67 offset:59936
	s_waitcnt lgkmcnt(4)
	v_mfma_f32_32x32x16_bf16 v[2:17], v[182:185], v[186:189], v[2:17]
	s_waitcnt lgkmcnt(1)
	v_mfma_f32_32x32x16_bf16 v[18:33], v[182:185], v[198:201], v[18:33]
	ds_read_b128 v[182:185], v66 offset:23040
	ds_read_b128 v[206:209], v66 offset:23072
	s_waitcnt lgkmcnt(1)
	v_mfma_f32_32x32x16_bf16 v[34:49], v[182:185], v[186:189], v[34:49]
	v_mfma_f32_32x32x16_bf16 v[50:65], v[182:185], v[198:201], v[50:65]
	v_mfma_f32_32x32x16_bf16 v[2:17], v[190:193], v[194:197], v[2:17]
	v_mfma_f32_32x32x16_bf16 v[18:33], v[190:193], v[202:205], v[18:33]
	s_waitcnt lgkmcnt(0)
	v_mfma_f32_32x32x16_bf16 v[34:49], v[206:209], v[194:197], v[34:49]
	ds_read_b128 v[182:185], v66 offset:18496
	ds_read_b128 v[186:189], v67 offset:55360
	ds_read_b128 v[190:193], v66 offset:18528
	ds_read_b128 v[194:197], v67 offset:55392
	v_mfma_f32_32x32x16_bf16 v[50:65], v[206:209], v[202:205], v[50:65]
	ds_read_b128 v[198:201], v67 offset:59968
	ds_read_b128 v[202:205], v67 offset:60000
	s_waitcnt lgkmcnt(4)
	v_mfma_f32_32x32x16_bf16 v[2:17], v[182:185], v[186:189], v[2:17]
	s_waitcnt lgkmcnt(1)
	v_mfma_f32_32x32x16_bf16 v[18:33], v[182:185], v[198:201], v[18:33]
	ds_read_b128 v[182:185], v66 offset:23104
	ds_read_b128 v[206:209], v66 offset:23136
	s_waitcnt vmcnt(16)
	ds_write_b128 v90, v[210:213]
	ds_write_b128 v90, v[218:221] offset:4608
	ds_write_b128 v90, v[222:225] offset:9216
	ds_write_b128 v90, v[226:229] offset:13824
	ds_write_b128 v90, v[214:217] offset:36864
	ds_write_b128 v90, v[230:233] offset:41472
	ds_write_b128 v90, v[234:237] offset:46080
	ds_write_b128 v90, v[238:241] offset:50688
	global_load_dwordx4 v[218:221], v[78:79], off offset:1152
	global_load_dwordx4 v[222:225], v[80:81], off offset:1152
	global_load_dwordx4 v[210:213], v[74:75], off offset:1152
	global_load_dwordx4 v[214:217], v[76:77], off offset:1152
	global_load_dwordx4 v[226:229], v[82:83], off offset:1152
	global_load_dwordx4 v[230:233], v[84:85], off offset:1152
	global_load_dwordx4 v[234:237], v[86:87], off offset:1152
	global_load_dwordx4 v[238:241], v[88:89], off offset:1152
	s_waitcnt lgkmcnt(0)
	s_barrier
	v_mfma_f32_32x32x16_bf16 v[34:49], v[182:185], v[186:189], v[34:49]
	v_mfma_f32_32x32x16_bf16 v[50:65], v[182:185], v[198:201], v[50:65]
	v_mfma_f32_32x32x16_bf16 v[2:17], v[190:193], v[194:197], v[2:17]
	v_mfma_f32_32x32x16_bf16 v[18:33], v[190:193], v[202:205], v[18:33]
	v_mfma_f32_32x32x16_bf16 v[34:49], v[206:209], v[194:197], v[34:49]
	v_mfma_f32_32x32x16_bf16 v[50:65], v[206:209], v[202:205], v[50:65]
	ds_read_b128 v[182:185], v66
	ds_read_b128 v[186:189], v67 offset:36864
	ds_read_b128 v[190:193], v66 offset:32
	ds_read_b128 v[194:197], v67 offset:36896
	ds_read_b128 v[198:201], v67 offset:41472
	ds_read_b128 v[202:205], v67 offset:41504
	s_waitcnt lgkmcnt(4)
	v_mfma_f32_32x32x16_bf16 v[2:17], v[182:185], v[186:189], v[2:17]
	s_waitcnt lgkmcnt(1)
	v_mfma_f32_32x32x16_bf16 v[18:33], v[182:185], v[198:201], v[18:33]
	ds_read_b128 v[182:185], v66 offset:4608
	ds_read_b128 v[206:209], v66 offset:4640
	s_waitcnt lgkmcnt(1)
	v_mfma_f32_32x32x16_bf16 v[34:49], v[182:185], v[186:189], v[34:49]
	v_mfma_f32_32x32x16_bf16 v[50:65], v[182:185], v[198:201], v[50:65]
	v_mfma_f32_32x32x16_bf16 v[2:17], v[190:193], v[194:197], v[2:17]
	v_mfma_f32_32x32x16_bf16 v[18:33], v[190:193], v[202:205], v[18:33]
	s_waitcnt lgkmcnt(0)
	v_mfma_f32_32x32x16_bf16 v[34:49], v[206:209], v[194:197], v[34:49]
	ds_read_b128 v[182:185], v66 offset:64
	ds_read_b128 v[186:189], v67 offset:36928
	ds_read_b128 v[190:193], v66 offset:96
	ds_read_b128 v[194:197], v67 offset:36960
	v_mfma_f32_32x32x16_bf16 v[50:65], v[206:209], v[202:205], v[50:65]
	ds_read_b128 v[198:201], v67 offset:41536
	ds_read_b128 v[202:205], v67 offset:41568
	s_waitcnt lgkmcnt(4)
	v_mfma_f32_32x32x16_bf16 v[2:17], v[182:185], v[186:189], v[2:17]
	s_waitcnt lgkmcnt(1)
	v_mfma_f32_32x32x16_bf16 v[18:33], v[182:185], v[198:201], v[18:33]
	ds_read_b128 v[182:185], v66 offset:4672
	ds_read_b128 v[206:209], v66 offset:4704
	s_waitcnt vmcnt(16)
	ds_write_b128 v90, v[118:121] offset:18432
	ds_write_b128 v90, v[126:129] offset:23040
	ds_write_b128 v90, v[130:133] offset:27648
	ds_write_b128 v90, v[134:137] offset:32256
	ds_write_b128 v90, v[122:125] offset:55296
	ds_write_b128 v90, v[138:141] offset:59904
	ds_write_b128 v90, v[142:145] offset:64512
	ds_write_b128 v91, v[146:149] offset:32256
	global_load_dwordx4 v[126:129], v[78:79], off offset:1280
	global_load_dwordx4 v[130:133], v[80:81], off offset:1280
	global_load_dwordx4 v[118:121], v[74:75], off offset:1280
	global_load_dwordx4 v[122:125], v[76:77], off offset:1280
	global_load_dwordx4 v[134:137], v[82:83], off offset:1280
	global_load_dwordx4 v[138:141], v[84:85], off offset:1280
	global_load_dwordx4 v[142:145], v[86:87], off offset:1280
	global_load_dwordx4 v[146:149], v[88:89], off offset:1280
	s_waitcnt lgkmcnt(0)
	s_barrier
	v_mfma_f32_32x32x16_bf16 v[34:49], v[182:185], v[186:189], v[34:49]
	v_mfma_f32_32x32x16_bf16 v[50:65], v[182:185], v[198:201], v[50:65]
	v_mfma_f32_32x32x16_bf16 v[2:17], v[190:193], v[194:197], v[2:17]
	v_mfma_f32_32x32x16_bf16 v[18:33], v[190:193], v[202:205], v[18:33]
	v_mfma_f32_32x32x16_bf16 v[34:49], v[206:209], v[194:197], v[34:49]
	v_mfma_f32_32x32x16_bf16 v[50:65], v[206:209], v[202:205], v[50:65]
	ds_read_b128 v[182:185], v66 offset:18432
	ds_read_b128 v[186:189], v67 offset:55296
	ds_read_b128 v[190:193], v66 offset:18464
	ds_read_b128 v[194:197], v67 offset:55328
	ds_read_b128 v[198:201], v67 offset:59904
	ds_read_b128 v[202:205], v67 offset:59936
	s_waitcnt lgkmcnt(4)
	v_mfma_f32_32x32x16_bf16 v[2:17], v[182:185], v[186:189], v[2:17]
	s_waitcnt lgkmcnt(1)
	v_mfma_f32_32x32x16_bf16 v[18:33], v[182:185], v[198:201], v[18:33]
	ds_read_b128 v[182:185], v66 offset:23040
	ds_read_b128 v[206:209], v66 offset:23072
	s_waitcnt lgkmcnt(1)
	v_mfma_f32_32x32x16_bf16 v[34:49], v[182:185], v[186:189], v[34:49]
	v_mfma_f32_32x32x16_bf16 v[50:65], v[182:185], v[198:201], v[50:65]
	v_mfma_f32_32x32x16_bf16 v[2:17], v[190:193], v[194:197], v[2:17]
	v_mfma_f32_32x32x16_bf16 v[18:33], v[190:193], v[202:205], v[18:33]
	s_waitcnt lgkmcnt(0)
	v_mfma_f32_32x32x16_bf16 v[34:49], v[206:209], v[194:197], v[34:49]
	ds_read_b128 v[182:185], v66 offset:18496
	ds_read_b128 v[186:189], v67 offset:55360
	ds_read_b128 v[190:193], v66 offset:18528
	ds_read_b128 v[194:197], v67 offset:55392
	v_mfma_f32_32x32x16_bf16 v[50:65], v[206:209], v[202:205], v[50:65]
	ds_read_b128 v[198:201], v67 offset:59968
	ds_read_b128 v[202:205], v67 offset:60000
	s_waitcnt lgkmcnt(4)
	v_mfma_f32_32x32x16_bf16 v[2:17], v[182:185], v[186:189], v[2:17]
	s_waitcnt lgkmcnt(1)
	v_mfma_f32_32x32x16_bf16 v[18:33], v[182:185], v[198:201], v[18:33]
	ds_read_b128 v[182:185], v66 offset:23104
	ds_read_b128 v[206:209], v66 offset:23136
	s_waitcnt vmcnt(16)
	ds_write_b128 v90, v[150:153]
	ds_write_b128 v90, v[158:161] offset:4608
	ds_write_b128 v90, v[162:165] offset:9216
	ds_write_b128 v90, v[166:169] offset:13824
	ds_write_b128 v90, v[154:157] offset:36864
	ds_write_b128 v90, v[170:173] offset:41472
	ds_write_b128 v90, v[174:177] offset:46080
	ds_write_b128 v90, v[178:181] offset:50688
	global_load_dwordx4 v[158:161], v[78:79], off offset:1408
	global_load_dwordx4 v[162:165], v[80:81], off offset:1408
	global_load_dwordx4 v[150:153], v[74:75], off offset:1408
	global_load_dwordx4 v[154:157], v[76:77], off offset:1408
	global_load_dwordx4 v[166:169], v[82:83], off offset:1408
	global_load_dwordx4 v[170:173], v[84:85], off offset:1408
	global_load_dwordx4 v[174:177], v[86:87], off offset:1408
	global_load_dwordx4 v[178:181], v[88:89], off offset:1408
	s_waitcnt lgkmcnt(0)
	s_barrier
	v_mfma_f32_32x32x16_bf16 v[34:49], v[182:185], v[186:189], v[34:49]
	v_mfma_f32_32x32x16_bf16 v[50:65], v[182:185], v[198:201], v[50:65]
	v_mfma_f32_32x32x16_bf16 v[2:17], v[190:193], v[194:197], v[2:17]
	v_mfma_f32_32x32x16_bf16 v[18:33], v[190:193], v[202:205], v[18:33]
	v_mfma_f32_32x32x16_bf16 v[34:49], v[206:209], v[194:197], v[34:49]
	v_mfma_f32_32x32x16_bf16 v[50:65], v[206:209], v[202:205], v[50:65]
	ds_read_b128 v[182:185], v66
	ds_read_b128 v[186:189], v67 offset:36864
	ds_read_b128 v[190:193], v66 offset:32
	ds_read_b128 v[194:197], v67 offset:36896
	ds_read_b128 v[198:201], v67 offset:41472
	ds_read_b128 v[202:205], v67 offset:41504
	s_waitcnt lgkmcnt(4)
	v_mfma_f32_32x32x16_bf16 v[2:17], v[182:185], v[186:189], v[2:17]
	s_waitcnt lgkmcnt(1)
	v_mfma_f32_32x32x16_bf16 v[18:33], v[182:185], v[198:201], v[18:33]
	ds_read_b128 v[182:185], v66 offset:4608
	ds_read_b128 v[206:209], v66 offset:4640
	s_waitcnt lgkmcnt(1)
	v_mfma_f32_32x32x16_bf16 v[34:49], v[182:185], v[186:189], v[34:49]
	v_mfma_f32_32x32x16_bf16 v[50:65], v[182:185], v[198:201], v[50:65]
	v_mfma_f32_32x32x16_bf16 v[2:17], v[190:193], v[194:197], v[2:17]
	v_mfma_f32_32x32x16_bf16 v[18:33], v[190:193], v[202:205], v[18:33]
	s_waitcnt lgkmcnt(0)
	v_mfma_f32_32x32x16_bf16 v[34:49], v[206:209], v[194:197], v[34:49]
	ds_read_b128 v[182:185], v66 offset:64
	ds_read_b128 v[186:189], v67 offset:36928
	ds_read_b128 v[190:193], v66 offset:96
	ds_read_b128 v[194:197], v67 offset:36960
	v_mfma_f32_32x32x16_bf16 v[50:65], v[206:209], v[202:205], v[50:65]
	ds_read_b128 v[198:201], v67 offset:41536
	ds_read_b128 v[202:205], v67 offset:41568
	s_waitcnt lgkmcnt(4)
	v_mfma_f32_32x32x16_bf16 v[2:17], v[182:185], v[186:189], v[2:17]
	s_waitcnt lgkmcnt(1)
	v_mfma_f32_32x32x16_bf16 v[18:33], v[182:185], v[198:201], v[18:33]
	ds_read_b128 v[182:185], v66 offset:4672
	ds_read_b128 v[206:209], v66 offset:4704
	s_waitcnt vmcnt(16)
	ds_write_b128 v90, v[210:213] offset:18432
	ds_write_b128 v90, v[218:221] offset:23040
	ds_write_b128 v90, v[222:225] offset:27648
	ds_write_b128 v90, v[226:229] offset:32256
	ds_write_b128 v90, v[214:217] offset:55296
	ds_write_b128 v90, v[230:233] offset:59904
	ds_write_b128 v90, v[234:237] offset:64512
	ds_write_b128 v91, v[238:241] offset:32256
	global_load_dwordx4 v[218:221], v[78:79], off offset:1536
	global_load_dwordx4 v[222:225], v[80:81], off offset:1536
	global_load_dwordx4 v[210:213], v[74:75], off offset:1536
	global_load_dwordx4 v[214:217], v[76:77], off offset:1536
	global_load_dwordx4 v[226:229], v[82:83], off offset:1536
	global_load_dwordx4 v[230:233], v[84:85], off offset:1536
	global_load_dwordx4 v[234:237], v[86:87], off offset:1536
	global_load_dwordx4 v[238:241], v[88:89], off offset:1536
	s_waitcnt lgkmcnt(0)
	s_barrier
	v_mfma_f32_32x32x16_bf16 v[34:49], v[182:185], v[186:189], v[34:49]
	v_mfma_f32_32x32x16_bf16 v[50:65], v[182:185], v[198:201], v[50:65]
	v_mfma_f32_32x32x16_bf16 v[2:17], v[190:193], v[194:197], v[2:17]
	v_mfma_f32_32x32x16_bf16 v[18:33], v[190:193], v[202:205], v[18:33]
	v_mfma_f32_32x32x16_bf16 v[34:49], v[206:209], v[194:197], v[34:49]
	v_mfma_f32_32x32x16_bf16 v[50:65], v[206:209], v[202:205], v[50:65]
	ds_read_b128 v[182:185], v66 offset:18432
	ds_read_b128 v[186:189], v67 offset:55296
	ds_read_b128 v[190:193], v66 offset:18464
	ds_read_b128 v[194:197], v67 offset:55328
	ds_read_b128 v[198:201], v67 offset:59904
	ds_read_b128 v[202:205], v67 offset:59936
	s_waitcnt lgkmcnt(4)
	v_mfma_f32_32x32x16_bf16 v[2:17], v[182:185], v[186:189], v[2:17]
	s_waitcnt lgkmcnt(1)
	v_mfma_f32_32x32x16_bf16 v[18:33], v[182:185], v[198:201], v[18:33]
	ds_read_b128 v[182:185], v66 offset:23040
	ds_read_b128 v[206:209], v66 offset:23072
	s_waitcnt lgkmcnt(1)
	v_mfma_f32_32x32x16_bf16 v[34:49], v[182:185], v[186:189], v[34:49]
	v_mfma_f32_32x32x16_bf16 v[50:65], v[182:185], v[198:201], v[50:65]
	v_mfma_f32_32x32x16_bf16 v[2:17], v[190:193], v[194:197], v[2:17]
	v_mfma_f32_32x32x16_bf16 v[18:33], v[190:193], v[202:205], v[18:33]
	s_waitcnt lgkmcnt(0)
	v_mfma_f32_32x32x16_bf16 v[34:49], v[206:209], v[194:197], v[34:49]
	ds_read_b128 v[182:185], v66 offset:18496
	ds_read_b128 v[186:189], v67 offset:55360
	ds_read_b128 v[190:193], v66 offset:18528
	ds_read_b128 v[194:197], v67 offset:55392
	v_mfma_f32_32x32x16_bf16 v[50:65], v[206:209], v[202:205], v[50:65]
	ds_read_b128 v[198:201], v67 offset:59968
	ds_read_b128 v[202:205], v67 offset:60000
	s_waitcnt lgkmcnt(4)
	v_mfma_f32_32x32x16_bf16 v[2:17], v[182:185], v[186:189], v[2:17]
	s_waitcnt lgkmcnt(1)
	v_mfma_f32_32x32x16_bf16 v[18:33], v[182:185], v[198:201], v[18:33]
	ds_read_b128 v[182:185], v66 offset:23104
	ds_read_b128 v[206:209], v66 offset:23136
	s_waitcnt vmcnt(16)
	ds_write_b128 v90, v[118:121]
	ds_write_b128 v90, v[126:129] offset:4608
	ds_write_b128 v90, v[130:133] offset:9216
	ds_write_b128 v90, v[134:137] offset:13824
	ds_write_b128 v90, v[122:125] offset:36864
	ds_write_b128 v90, v[138:141] offset:41472
	ds_write_b128 v90, v[142:145] offset:46080
	ds_write_b128 v90, v[146:149] offset:50688
	global_load_dwordx4 v[126:129], v[78:79], off offset:1664
	global_load_dwordx4 v[130:133], v[80:81], off offset:1664
	global_load_dwordx4 v[118:121], v[74:75], off offset:1664
	global_load_dwordx4 v[122:125], v[76:77], off offset:1664
	global_load_dwordx4 v[134:137], v[82:83], off offset:1664
	global_load_dwordx4 v[138:141], v[84:85], off offset:1664
	global_load_dwordx4 v[142:145], v[86:87], off offset:1664
	global_load_dwordx4 v[146:149], v[88:89], off offset:1664
	s_waitcnt lgkmcnt(0)
	s_barrier
	v_mfma_f32_32x32x16_bf16 v[34:49], v[182:185], v[186:189], v[34:49]
	v_mfma_f32_32x32x16_bf16 v[50:65], v[182:185], v[198:201], v[50:65]
	v_mfma_f32_32x32x16_bf16 v[2:17], v[190:193], v[194:197], v[2:17]
	v_mfma_f32_32x32x16_bf16 v[18:33], v[190:193], v[202:205], v[18:33]
	v_mfma_f32_32x32x16_bf16 v[34:49], v[206:209], v[194:197], v[34:49]
	v_mfma_f32_32x32x16_bf16 v[50:65], v[206:209], v[202:205], v[50:65]
	ds_read_b128 v[182:185], v66
	ds_read_b128 v[186:189], v67 offset:36864
	ds_read_b128 v[190:193], v66 offset:32
	ds_read_b128 v[194:197], v67 offset:36896
	ds_read_b128 v[198:201], v67 offset:41472
	ds_read_b128 v[202:205], v67 offset:41504
	s_waitcnt lgkmcnt(4)
	v_mfma_f32_32x32x16_bf16 v[2:17], v[182:185], v[186:189], v[2:17]
	s_waitcnt lgkmcnt(1)
	v_mfma_f32_32x32x16_bf16 v[18:33], v[182:185], v[198:201], v[18:33]
	ds_read_b128 v[182:185], v66 offset:4608
	ds_read_b128 v[206:209], v66 offset:4640
	s_waitcnt lgkmcnt(1)
	v_mfma_f32_32x32x16_bf16 v[34:49], v[182:185], v[186:189], v[34:49]
	v_mfma_f32_32x32x16_bf16 v[50:65], v[182:185], v[198:201], v[50:65]
	v_mfma_f32_32x32x16_bf16 v[2:17], v[190:193], v[194:197], v[2:17]
	v_mfma_f32_32x32x16_bf16 v[18:33], v[190:193], v[202:205], v[18:33]
	s_waitcnt lgkmcnt(0)
	v_mfma_f32_32x32x16_bf16 v[34:49], v[206:209], v[194:197], v[34:49]
	ds_read_b128 v[182:185], v66 offset:64
	ds_read_b128 v[186:189], v67 offset:36928
	ds_read_b128 v[190:193], v66 offset:96
	ds_read_b128 v[194:197], v67 offset:36960
	v_mfma_f32_32x32x16_bf16 v[50:65], v[206:209], v[202:205], v[50:65]
	ds_read_b128 v[198:201], v67 offset:41536
	ds_read_b128 v[202:205], v67 offset:41568
	s_waitcnt lgkmcnt(4)
	v_mfma_f32_32x32x16_bf16 v[2:17], v[182:185], v[186:189], v[2:17]
	s_waitcnt lgkmcnt(1)
	v_mfma_f32_32x32x16_bf16 v[18:33], v[182:185], v[198:201], v[18:33]
	ds_read_b128 v[182:185], v66 offset:4672
	ds_read_b128 v[206:209], v66 offset:4704
	s_waitcnt vmcnt(16)
	ds_write_b128 v90, v[150:153] offset:18432
	ds_write_b128 v90, v[158:161] offset:23040
	ds_write_b128 v90, v[162:165] offset:27648
	ds_write_b128 v90, v[166:169] offset:32256
	ds_write_b128 v90, v[154:157] offset:55296
	ds_write_b128 v90, v[170:173] offset:59904
	ds_write_b128 v90, v[174:177] offset:64512
	ds_write_b128 v91, v[178:181] offset:32256
	global_load_dwordx4 v[158:161], v[78:79], off offset:1792
	global_load_dwordx4 v[162:165], v[80:81], off offset:1792
	global_load_dwordx4 v[150:153], v[74:75], off offset:1792
	global_load_dwordx4 v[154:157], v[76:77], off offset:1792
	global_load_dwordx4 v[166:169], v[82:83], off offset:1792
	global_load_dwordx4 v[170:173], v[84:85], off offset:1792
	global_load_dwordx4 v[174:177], v[86:87], off offset:1792
	global_load_dwordx4 v[178:181], v[88:89], off offset:1792
	s_waitcnt lgkmcnt(0)
	s_barrier
	v_mfma_f32_32x32x16_bf16 v[34:49], v[182:185], v[186:189], v[34:49]
	v_mfma_f32_32x32x16_bf16 v[50:65], v[182:185], v[198:201], v[50:65]
	v_mfma_f32_32x32x16_bf16 v[2:17], v[190:193], v[194:197], v[2:17]
	v_mfma_f32_32x32x16_bf16 v[18:33], v[190:193], v[202:205], v[18:33]
	v_mfma_f32_32x32x16_bf16 v[34:49], v[206:209], v[194:197], v[34:49]
	v_mfma_f32_32x32x16_bf16 v[50:65], v[206:209], v[202:205], v[50:65]
	ds_read_b128 v[182:185], v66 offset:18432
	ds_read_b128 v[186:189], v67 offset:55296
	ds_read_b128 v[190:193], v66 offset:18464
	ds_read_b128 v[194:197], v67 offset:55328
	ds_read_b128 v[198:201], v67 offset:59904
	ds_read_b128 v[202:205], v67 offset:59936
	s_waitcnt lgkmcnt(4)
	v_mfma_f32_32x32x16_bf16 v[2:17], v[182:185], v[186:189], v[2:17]
	s_waitcnt lgkmcnt(1)
	v_mfma_f32_32x32x16_bf16 v[18:33], v[182:185], v[198:201], v[18:33]
	ds_read_b128 v[182:185], v66 offset:23040
	ds_read_b128 v[206:209], v66 offset:23072
	s_waitcnt lgkmcnt(1)
	v_mfma_f32_32x32x16_bf16 v[34:49], v[182:185], v[186:189], v[34:49]
	v_mfma_f32_32x32x16_bf16 v[50:65], v[182:185], v[198:201], v[50:65]
	v_mfma_f32_32x32x16_bf16 v[2:17], v[190:193], v[194:197], v[2:17]
	v_mfma_f32_32x32x16_bf16 v[18:33], v[190:193], v[202:205], v[18:33]
	s_waitcnt lgkmcnt(0)
	v_mfma_f32_32x32x16_bf16 v[34:49], v[206:209], v[194:197], v[34:49]
	ds_read_b128 v[182:185], v66 offset:18496
	ds_read_b128 v[186:189], v67 offset:55360
	ds_read_b128 v[190:193], v66 offset:18528
	ds_read_b128 v[194:197], v67 offset:55392
	v_mfma_f32_32x32x16_bf16 v[50:65], v[206:209], v[202:205], v[50:65]
	ds_read_b128 v[198:201], v67 offset:59968
	ds_read_b128 v[202:205], v67 offset:60000
	s_waitcnt lgkmcnt(4)
	v_mfma_f32_32x32x16_bf16 v[2:17], v[182:185], v[186:189], v[2:17]
	s_waitcnt lgkmcnt(1)
	v_mfma_f32_32x32x16_bf16 v[18:33], v[182:185], v[198:201], v[18:33]
	ds_read_b128 v[182:185], v66 offset:23104
	ds_read_b128 v[206:209], v66 offset:23136
	s_waitcnt vmcnt(16)
	ds_write_b128 v90, v[210:213]
	ds_write_b128 v90, v[218:221] offset:4608
	ds_write_b128 v90, v[222:225] offset:9216
	ds_write_b128 v90, v[226:229] offset:13824
	ds_write_b128 v90, v[214:217] offset:36864
	ds_write_b128 v90, v[230:233] offset:41472
	ds_write_b128 v90, v[234:237] offset:46080
	ds_write_b128 v90, v[238:241] offset:50688
	global_load_dwordx4 v[218:221], v[78:79], off offset:1920
	global_load_dwordx4 v[222:225], v[80:81], off offset:1920
	global_load_dwordx4 v[210:213], v[74:75], off offset:1920
	global_load_dwordx4 v[214:217], v[76:77], off offset:1920
	global_load_dwordx4 v[226:229], v[82:83], off offset:1920
	global_load_dwordx4 v[230:233], v[84:85], off offset:1920
	global_load_dwordx4 v[234:237], v[86:87], off offset:1920
	global_load_dwordx4 v[238:241], v[88:89], off offset:1920
	s_waitcnt lgkmcnt(0)
	s_barrier
	v_mfma_f32_32x32x16_bf16 v[34:49], v[182:185], v[186:189], v[34:49]
	v_mfma_f32_32x32x16_bf16 v[50:65], v[182:185], v[198:201], v[50:65]
	v_mfma_f32_32x32x16_bf16 v[2:17], v[190:193], v[194:197], v[2:17]
	v_mfma_f32_32x32x16_bf16 v[18:33], v[190:193], v[202:205], v[18:33]
	v_mfma_f32_32x32x16_bf16 v[34:49], v[206:209], v[194:197], v[34:49]
	v_mfma_f32_32x32x16_bf16 v[50:65], v[206:209], v[202:205], v[50:65]
	ds_read_b128 v[182:185], v66
	ds_read_b128 v[186:189], v67 offset:36864
	ds_read_b128 v[190:193], v66 offset:32
	ds_read_b128 v[194:197], v67 offset:36896
	ds_read_b128 v[198:201], v67 offset:41472
	ds_read_b128 v[202:205], v67 offset:41504
	s_waitcnt lgkmcnt(4)
	v_mfma_f32_32x32x16_bf16 v[2:17], v[182:185], v[186:189], v[2:17]
	s_waitcnt lgkmcnt(1)
	v_mfma_f32_32x32x16_bf16 v[18:33], v[182:185], v[198:201], v[18:33]
	ds_read_b128 v[182:185], v66 offset:4608
	ds_read_b128 v[206:209], v66 offset:4640
	s_waitcnt lgkmcnt(1)
	v_mfma_f32_32x32x16_bf16 v[34:49], v[182:185], v[186:189], v[34:49]
	v_mfma_f32_32x32x16_bf16 v[50:65], v[182:185], v[198:201], v[50:65]
	v_mfma_f32_32x32x16_bf16 v[2:17], v[190:193], v[194:197], v[2:17]
	v_mfma_f32_32x32x16_bf16 v[18:33], v[190:193], v[202:205], v[18:33]
	s_waitcnt lgkmcnt(0)
	v_mfma_f32_32x32x16_bf16 v[34:49], v[206:209], v[194:197], v[34:49]
	ds_read_b128 v[182:185], v66 offset:64
	ds_read_b128 v[186:189], v67 offset:36928
	ds_read_b128 v[190:193], v66 offset:96
	ds_read_b128 v[194:197], v67 offset:36960
	v_mfma_f32_32x32x16_bf16 v[50:65], v[206:209], v[202:205], v[50:65]
	ds_read_b128 v[198:201], v67 offset:41536
	ds_read_b128 v[202:205], v67 offset:41568
	s_waitcnt lgkmcnt(4)
	v_mfma_f32_32x32x16_bf16 v[2:17], v[182:185], v[186:189], v[2:17]
	s_waitcnt lgkmcnt(1)
	v_mfma_f32_32x32x16_bf16 v[18:33], v[182:185], v[198:201], v[18:33]
	ds_read_b128 v[182:185], v66 offset:4672
	ds_read_b128 v[206:209], v66 offset:4704
	s_waitcnt vmcnt(16)
	ds_write_b128 v90, v[118:121] offset:18432
	ds_write_b128 v90, v[126:129] offset:23040
	ds_write_b128 v90, v[130:133] offset:27648
	ds_write_b128 v90, v[134:137] offset:32256
	ds_write_b128 v90, v[122:125] offset:55296
	ds_write_b128 v90, v[138:141] offset:59904
	ds_write_b128 v90, v[142:145] offset:64512
	ds_write_b128 v91, v[146:149] offset:32256
	s_waitcnt lgkmcnt(0)
	s_barrier
	v_mfma_f32_32x32x16_bf16 v[34:49], v[182:185], v[186:189], v[34:49]
	v_mfma_f32_32x32x16_bf16 v[50:65], v[182:185], v[198:201], v[50:65]
	v_mfma_f32_32x32x16_bf16 v[2:17], v[190:193], v[194:197], v[2:17]
	v_mfma_f32_32x32x16_bf16 v[18:33], v[190:193], v[202:205], v[18:33]
	v_mfma_f32_32x32x16_bf16 v[34:49], v[206:209], v[194:197], v[34:49]
	v_mfma_f32_32x32x16_bf16 v[50:65], v[206:209], v[202:205], v[50:65]
	ds_read_b128 v[134:137], v66 offset:18432
	ds_read_b128 v[138:141], v67 offset:55296
	ds_read_b128 v[142:145], v66 offset:18464
	ds_read_b128 v[146:149], v67 offset:55328
	ds_read_b128 v[182:185], v67 offset:59904
	ds_read_b128 v[186:189], v67 offset:59936
	s_waitcnt lgkmcnt(4)
	v_mfma_f32_32x32x16_bf16 v[2:17], v[134:137], v[138:141], v[2:17]
	s_waitcnt lgkmcnt(1)
	v_mfma_f32_32x32x16_bf16 v[18:33], v[134:137], v[182:185], v[18:33]
	ds_read_b128 v[134:137], v66 offset:23040
	ds_read_b128 v[190:193], v66 offset:23072
	s_waitcnt lgkmcnt(1)
	v_mfma_f32_32x32x16_bf16 v[34:49], v[134:137], v[138:141], v[34:49]
	v_mfma_f32_32x32x16_bf16 v[50:65], v[134:137], v[182:185], v[50:65]
	v_mfma_f32_32x32x16_bf16 v[2:17], v[142:145], v[146:149], v[2:17]
	v_mfma_f32_32x32x16_bf16 v[18:33], v[142:145], v[186:189], v[18:33]
	s_waitcnt lgkmcnt(0)
	v_mfma_f32_32x32x16_bf16 v[34:49], v[190:193], v[146:149], v[34:49]
	ds_read_b128 v[134:137], v66 offset:18496
	ds_read_b128 v[138:141], v67 offset:55360
	ds_read_b128 v[142:145], v66 offset:18528
	ds_read_b128 v[146:149], v67 offset:55392
	v_mfma_f32_32x32x16_bf16 v[50:65], v[190:193], v[186:189], v[50:65]
	ds_read_b128 v[182:185], v67 offset:59968
	ds_read_b128 v[186:189], v67 offset:60000
	s_waitcnt lgkmcnt(4)
	v_mfma_f32_32x32x16_bf16 v[2:17], v[134:137], v[138:141], v[2:17]
	s_waitcnt lgkmcnt(1)
	v_mfma_f32_32x32x16_bf16 v[18:33], v[134:137], v[182:185], v[18:33]
	ds_read_b128 v[134:137], v66 offset:23104
	ds_read_b128 v[190:193], v66 offset:23136
	s_waitcnt vmcnt(8)
	ds_write_b128 v90, v[150:153]
	ds_write_b128 v90, v[158:161] offset:4608
	ds_write_b128 v90, v[162:165] offset:9216
	ds_write_b128 v90, v[166:169] offset:13824
	ds_write_b128 v90, v[154:157] offset:36864
	ds_write_b128 v90, v[170:173] offset:41472
	ds_write_b128 v90, v[174:177] offset:46080
	ds_write_b128 v90, v[178:181] offset:50688
	s_waitcnt lgkmcnt(0)
	s_barrier
	v_mfma_f32_32x32x16_bf16 v[34:49], v[134:137], v[138:141], v[34:49]
	v_mfma_f32_32x32x16_bf16 v[50:65], v[134:137], v[182:185], v[50:65]
	v_mfma_f32_32x32x16_bf16 v[2:17], v[142:145], v[146:149], v[2:17]
	v_mfma_f32_32x32x16_bf16 v[18:33], v[142:145], v[186:189], v[18:33]
	v_mfma_f32_32x32x16_bf16 v[34:49], v[190:193], v[146:149], v[34:49]
	v_mfma_f32_32x32x16_bf16 v[50:65], v[190:193], v[186:189], v[50:65]
	ds_read_b128 v[134:137], v66
	ds_read_b128 v[138:141], v67 offset:36864
	ds_read_b128 v[142:145], v66 offset:32
	ds_read_b128 v[146:149], v67 offset:36896
	ds_read_b128 v[150:153], v67 offset:41472
	ds_read_b128 v[154:157], v67 offset:41504
	s_waitcnt lgkmcnt(4)
	v_mfma_f32_32x32x16_bf16 v[2:17], v[134:137], v[138:141], v[2:17]
	s_waitcnt lgkmcnt(1)
	v_mfma_f32_32x32x16_bf16 v[18:33], v[134:137], v[150:153], v[18:33]
	ds_read_b128 v[134:137], v66 offset:4608
	ds_read_b128 v[158:161], v66 offset:4640
	s_waitcnt lgkmcnt(1)
	v_mfma_f32_32x32x16_bf16 v[34:49], v[134:137], v[138:141], v[34:49]
	v_mfma_f32_32x32x16_bf16 v[50:65], v[134:137], v[150:153], v[50:65]
	v_mfma_f32_32x32x16_bf16 v[2:17], v[142:145], v[146:149], v[2:17]
	v_mfma_f32_32x32x16_bf16 v[18:33], v[142:145], v[154:157], v[18:33]
	s_waitcnt lgkmcnt(0)
	v_mfma_f32_32x32x16_bf16 v[34:49], v[158:161], v[146:149], v[34:49]
	ds_read_b128 v[134:137], v66 offset:64
	ds_read_b128 v[138:141], v67 offset:36928
	ds_read_b128 v[142:145], v66 offset:96
	ds_read_b128 v[146:149], v67 offset:36960
	v_mfma_f32_32x32x16_bf16 v[50:65], v[158:161], v[154:157], v[50:65]
	ds_read_b128 v[150:153], v67 offset:41536
	ds_read_b128 v[154:157], v67 offset:41568
	s_waitcnt lgkmcnt(4)
	v_mfma_f32_32x32x16_bf16 v[2:17], v[134:137], v[138:141], v[2:17]
	s_waitcnt lgkmcnt(1)
	v_mfma_f32_32x32x16_bf16 v[18:33], v[134:137], v[150:153], v[18:33]
	ds_read_b128 v[134:137], v66 offset:4672
	ds_read_b128 v[158:161], v66 offset:4704
	s_waitcnt vmcnt(0)
	ds_write_b128 v90, v[210:213] offset:18432
	ds_write_b128 v90, v[218:221] offset:23040
	ds_write_b128 v90, v[222:225] offset:27648
	ds_write_b128 v90, v[226:229] offset:32256
	ds_write_b128 v90, v[214:217] offset:55296
	ds_write_b128 v90, v[230:233] offset:59904
	ds_write_b128 v90, v[234:237] offset:64512
	ds_write_b128 v91, v[238:241] offset:32256
	s_waitcnt lgkmcnt(0)
	s_barrier
	v_mfma_f32_32x32x16_bf16 v[34:49], v[134:137], v[138:141], v[34:49]
	v_mfma_f32_32x32x16_bf16 v[50:65], v[134:137], v[150:153], v[50:65]
	v_mfma_f32_32x32x16_bf16 v[2:17], v[142:145], v[146:149], v[2:17]
	v_mfma_f32_32x32x16_bf16 v[18:33], v[142:145], v[154:157], v[18:33]
	v_mfma_f32_32x32x16_bf16 v[34:49], v[158:161], v[146:149], v[34:49]
	v_mfma_f32_32x32x16_bf16 v[50:65], v[158:161], v[154:157], v[50:65]
	ds_read_b128 v[74:77], v66 offset:18432
	ds_read_b128 v[78:81], v67 offset:55296
	ds_read_b128 v[82:85], v66 offset:18464
	ds_read_b128 v[86:89], v67 offset:55328
	ds_read_b128 v[118:121], v67 offset:59904
	ds_read_b128 v[122:125], v67 offset:59936
	s_mov_b32 s12, 0
	s_waitcnt lgkmcnt(4)
	v_mfma_f32_32x32x16_bf16 v[2:17], v[74:77], v[78:81], v[2:17]
	s_waitcnt lgkmcnt(1)
	v_mfma_f32_32x32x16_bf16 v[18:33], v[74:77], v[118:121], v[18:33]
	ds_read_b128 v[74:77], v66 offset:23040
	ds_read_b128 v[126:129], v66 offset:23072
	s_waitcnt lgkmcnt(1)
	v_mfma_f32_32x32x16_bf16 v[34:49], v[74:77], v[78:81], v[34:49]
	v_mfma_f32_32x32x16_bf16 v[50:65], v[74:77], v[118:121], v[50:65]
	v_mfma_f32_32x32x16_bf16 v[2:17], v[82:85], v[86:89], v[2:17]
	v_mfma_f32_32x32x16_bf16 v[18:33], v[82:85], v[122:125], v[18:33]
	s_waitcnt lgkmcnt(0)
	v_mfma_f32_32x32x16_bf16 v[34:49], v[126:129], v[86:89], v[34:49]
	ds_read_b128 v[74:77], v66 offset:18496
	ds_read_b128 v[78:81], v67 offset:55360
	ds_read_b128 v[82:85], v66 offset:18528
	ds_read_b128 v[86:89], v67 offset:55392
	v_mfma_f32_32x32x16_bf16 v[50:65], v[126:129], v[122:125], v[50:65]
	ds_read_b128 v[118:121], v67 offset:59968
	ds_read_b128 v[122:125], v67 offset:60000
	s_waitcnt lgkmcnt(4)
	v_mfma_f32_32x32x16_bf16 v[2:17], v[74:77], v[78:81], v[2:17]
	s_waitcnt lgkmcnt(1)
	v_mfma_f32_32x32x16_bf16 v[18:33], v[74:77], v[118:121], v[18:33]
	ds_read_b128 v[74:77], v66 offset:23104
	ds_read_b128 v[126:129], v66 offset:23136
	s_waitcnt lgkmcnt(0)
	s_barrier
	v_mfma_f32_32x32x16_bf16 v[34:49], v[74:77], v[78:81], v[34:49]
	v_mfma_f32_32x32x16_bf16 v[50:65], v[74:77], v[118:121], v[50:65]
	v_mfma_f32_32x32x16_bf16 v[2:17], v[82:85], v[86:89], v[2:17]
	v_mfma_f32_32x32x16_bf16 v[18:33], v[82:85], v[122:125], v[18:33]
	v_mfma_f32_32x32x16_bf16 v[34:49], v[126:129], v[86:89], v[34:49]
	s_nop 10
	ds_write2_b32 v93, v2, v18 offset1:32
	v_mfma_f32_32x32x16_bf16 v[50:65], v[126:129], v[122:125], v[50:65]
	s_nop 11
	ds_write2_b32 v100, v34, v50 offset0:32 offset1:64
	ds_write2_b32 v93, v3, v19 offset0:129 offset1:161
	ds_write2_b32 v100, v35, v51 offset0:161 offset1:193
	ds_write2_b32 v101, v4, v20 offset0:2 offset1:34
	ds_write2_b32 v102, v36, v52 offset0:34 offset1:66
	ds_write2_b32 v101, v5, v21 offset0:131 offset1:163
	ds_write2_b32 v102, v37, v53 offset0:163 offset1:195
	ds_write2_b32 v103, v6, v22 offset0:8 offset1:40
	ds_write2_b32 v104, v38, v54 offset0:40 offset1:72
	ds_write2_b32 v103, v7, v23 offset0:137 offset1:169
	ds_write2_b32 v104, v39, v55 offset0:169 offset1:201
	ds_write2_b32 v105, v8, v24 offset0:10 offset1:42
	ds_write2_b32 v106, v40, v56 offset0:42 offset1:74
	ds_write2_b32 v105, v9, v25 offset0:139 offset1:171
	ds_write2_b32 v106, v41, v57 offset0:171 offset1:203
	ds_write2_b32 v107, v10, v26 offset0:16 offset1:48
	ds_write2_b32 v108, v42, v58 offset0:48 offset1:80
	ds_write2_b32 v107, v11, v27 offset0:145 offset1:177
	ds_write2_b32 v108, v43, v59 offset0:177 offset1:209
	ds_write2_b32 v109, v12, v28 offset0:18 offset1:50
	ds_write2_b32 v110, v44, v60 offset0:50 offset1:82
	ds_write2_b32 v109, v13, v29 offset0:147 offset1:179
	ds_write2_b32 v110, v45, v61 offset0:179 offset1:211
	ds_write2_b32 v111, v14, v30 offset0:24 offset1:56
	ds_write2_b32 v112, v46, v62 offset0:56 offset1:88
	ds_write2_b32 v111, v15, v31 offset0:153 offset1:185
	ds_write2_b32 v112, v47, v63 offset0:185 offset1:217
	ds_write2_b32 v113, v16, v32 offset0:26 offset1:58
	ds_write2_b32 v114, v48, v64 offset0:58 offset1:90
	ds_write2_b32 v113, v17, v33 offset0:155 offset1:187
	ds_write2_b32 v114, v49, v65 offset0:187 offset1:219
	v_or_b32_e32 v8, s23, v92
	v_lshlrev_b32_e32 v68, 2, v8
	s_waitcnt lgkmcnt(0)
	s_barrier
	v_mov_b32_e32 v2, v8
	v_mov_b32_e32 v3, v116
	v_lshlrev_b32_e32 v64, 12, v3
	v_lshl_add_u32 v64, v2, 2, v64
	v_lshlrev_b32_e32 v74, 2, v2
	global_load_dwordx4 v[128:131], v74, s[8:9]
	global_load_dwordx4 v[4:7], v64, s[80:81]
	v_add_u32_e32 v74, 0x8000, v64
	global_load_dwordx4 v[8:11], v74, s[80:81]
	v_add_u32_e32 v65, 0x10000, v64
	global_load_dwordx4 v[12:15], v65, s[80:81]
	v_add_u32_e32 v74, 0x18000, v64
	global_load_dwordx4 v[16:19], v74, s[80:81]
	v_add_u32_e32 v65, 0x20000, v64
	global_load_dwordx4 v[20:23], v65, s[80:81]
	v_add_u32_e32 v74, 0x28000, v64
	global_load_dwordx4 v[24:27], v74, s[80:81]
	v_add_u32_e32 v65, 0x30000, v64
	global_load_dwordx4 v[28:31], v65, s[80:81]
	v_add_u32_e32 v74, 0x38000, v64
	global_load_dwordx4 v[32:35], v74, s[80:81]
	v_add_u32_e32 v65, 0x40000, v64
	global_load_dwordx4 v[36:39], v65, s[80:81]
	v_add_u32_e32 v74, 0x48000, v64
	global_load_dwordx4 v[40:43], v74, s[80:81]
	v_add_u32_e32 v65, 0x50000, v64
	global_load_dwordx4 v[44:47], v65, s[80:81]
	v_add_u32_e32 v74, 0x58000, v64
	global_load_dwordx4 v[48:51], v74, s[80:81]
	v_add_u32_e32 v65, 0x60000, v64
	global_load_dwordx4 v[52:55], v65, s[80:81]
	v_add_u32_e32 v74, 0x68000, v64
	global_load_dwordx4 v[56:59], v74, s[80:81]
	v_add_u32_e32 v65, 0x70000, v64
	global_load_dwordx4 v[60:63], v65, s[80:81]
	v_add_u32_e32 v74, 0x78000, v64
	global_load_dwordx4 v[76:79], v74, s[80:81]
	v_and_b32_e32 v75, 7, v3
	v_mul_u32_u24_e32 v75, 0x204, v75
	v_and_b32_e32 v88, 0x7f, v2
	v_lshl_add_u32 v75, v88, 2, v75
	v_lshlrev_b32_e32 v162, 2, v3
	s_movk_i32 s12, 0x7fff
	v_mov_b32_e32 v163, 1
	ds_read2_b32 v[80:81], v75 offset1:1
	ds_read2_b32 v[82:83], v75 offset0:2 offset1:3
	v_add_u32_e32 v89, 0x1020, v75
	ds_read2_b32 v[84:85], v89 offset1:1
	ds_read2_b32 v[86:87], v89 offset0:2 offset1:3
	v_add_u32_e32 v88, 0x2040, v75
	ds_read2_b32 v[118:119], v88 offset1:1
	ds_read2_b32 v[120:121], v88 offset0:2 offset1:3
	v_add_u32_e32 v89, 0x3060, v75
	ds_read2_b32 v[122:123], v89 offset1:1
	ds_read2_b32 v[124:125], v89 offset0:2 offset1:3
	s_waitcnt vmcnt(15) lgkmcnt(6)
	v_pk_add_f32 v[4:5], v[4:5], v[80:81]
	v_pk_add_f32 v[6:7], v[6:7], v[82:83]
	s_waitcnt vmcnt(14) lgkmcnt(4)
	v_pk_add_f32 v[8:9], v[8:9], v[84:85]
	v_pk_add_f32 v[10:11], v[10:11], v[86:87]
	s_waitcnt vmcnt(13) lgkmcnt(2)
	v_pk_add_f32 v[12:13], v[12:13], v[118:119]
	v_pk_add_f32 v[14:15], v[14:15], v[120:121]
	s_waitcnt vmcnt(12) lgkmcnt(0)
	v_pk_add_f32 v[16:17], v[16:17], v[122:123]
	v_pk_add_f32 v[18:19], v[18:19], v[124:125]
	v_add_u32_e32 v88, 0x4080, v75
	ds_read2_b32 v[80:81], v88 offset1:1
	ds_read2_b32 v[82:83], v88 offset0:2 offset1:3
	v_add_u32_e32 v89, 0x50a0, v75
	ds_read2_b32 v[84:85], v89 offset1:1
	ds_read2_b32 v[86:87], v89 offset0:2 offset1:3
	v_add_u32_e32 v88, 0x60c0, v75
	ds_read2_b32 v[118:119], v88 offset1:1
	ds_read2_b32 v[120:121], v88 offset0:2 offset1:3
	v_add_u32_e32 v89, 0x70e0, v75
	ds_read2_b32 v[122:123], v89 offset1:1
	ds_read2_b32 v[124:125], v89 offset0:2 offset1:3
	global_store_dwordx4 v64, v[4:7], s[80:81]
	v_pk_mul_f32 v[146:147], v[4:5], v[4:5]
	v_pk_mul_f32 v[148:149], v[6:7], v[6:7]
	v_pk_mul_f32 v[150:151], v[4:5], v[128:129]
	v_pk_mul_f32 v[152:153], v[6:7], v[130:131]
	v_lshrrev_b32_e32 v164, 1, v64
	v_add_f32_e32 v126, v146, v147
	v_and_b32_sdwa v154, v150, v163 dst_sel:DWORD dst_unused:UNUSED_PAD src0_sel:WORD_1 src1_sel:DWORD
	v_and_b32_sdwa v155, v151, v163 dst_sel:DWORD dst_unused:UNUSED_PAD src0_sel:WORD_1 src1_sel:DWORD
	v_and_b32_sdwa v156, v152, v163 dst_sel:DWORD dst_unused:UNUSED_PAD src0_sel:WORD_1 src1_sel:DWORD
	v_and_b32_sdwa v157, v153, v163 dst_sel:DWORD dst_unused:UNUSED_PAD src0_sel:WORD_1 src1_sel:DWORD
	v_add_f32_e32 v126, v126, v148
	v_add3_u32 v150, v150, v154, s12
	v_add3_u32 v151, v151, v155, s12
	v_add3_u32 v152, v152, v156, s12
	v_add3_u32 v153, v153, v157, s12
	v_add_f32_e32 v126, v126, v149
	v_and_b32_e32 v151, 0xffff0000, v151
	v_and_b32_e32 v153, 0xffff0000, v153
	s_nop 0
	v_or_b32_sdwa v158, v151, v150 dst_sel:DWORD dst_unused:UNUSED_PAD src0_sel:DWORD src1_sel:WORD_1
	v_or_b32_sdwa v159, v153, v152 dst_sel:DWORD dst_unused:UNUSED_PAD src0_sel:DWORD src1_sel:WORD_1
	global_store_dwordx2 v164, v[158:159], s[92:93]
	v_add_u32_e32 v74, 0x8000, v64
	global_store_dwordx4 v74, v[8:11], s[80:81]
	v_pk_mul_f32 v[146:147], v[8:9], v[8:9]
	v_pk_mul_f32 v[148:149], v[10:11], v[10:11]
	v_pk_mul_f32 v[150:151], v[8:9], v[128:129]
	v_pk_mul_f32 v[152:153], v[10:11], v[130:131]
	v_lshrrev_b32_e32 v165, 1, v74
	v_add_f32_e32 v127, v146, v147
	v_and_b32_sdwa v154, v150, v163 dst_sel:DWORD dst_unused:UNUSED_PAD src0_sel:WORD_1 src1_sel:DWORD
	v_and_b32_sdwa v155, v151, v163 dst_sel:DWORD dst_unused:UNUSED_PAD src0_sel:WORD_1 src1_sel:DWORD
	v_and_b32_sdwa v156, v152, v163 dst_sel:DWORD dst_unused:UNUSED_PAD src0_sel:WORD_1 src1_sel:DWORD
	v_and_b32_sdwa v157, v153, v163 dst_sel:DWORD dst_unused:UNUSED_PAD src0_sel:WORD_1 src1_sel:DWORD
	v_add_f32_e32 v127, v127, v148
	v_add3_u32 v150, v150, v154, s12
	v_add3_u32 v151, v151, v155, s12
	v_add3_u32 v152, v152, v156, s12
	v_add3_u32 v153, v153, v157, s12
	v_add_f32_e32 v127, v127, v149
	v_and_b32_e32 v151, 0xffff0000, v151
	v_and_b32_e32 v153, 0xffff0000, v153
	s_nop 0
	v_or_b32_sdwa v160, v151, v150 dst_sel:DWORD dst_unused:UNUSED_PAD src0_sel:DWORD src1_sel:WORD_1
	v_or_b32_sdwa v161, v153, v152 dst_sel:DWORD dst_unused:UNUSED_PAD src0_sel:DWORD src1_sel:WORD_1
	global_store_dwordx2 v165, v[160:161], s[92:93]
	v_add_u32_e32 v65, 0x10000, v64
	global_store_dwordx4 v65, v[12:15], s[80:81]
	v_pk_mul_f32 v[146:147], v[12:13], v[12:13]
	v_pk_mul_f32 v[148:149], v[14:15], v[14:15]
	v_pk_mul_f32 v[150:151], v[12:13], v[128:129]
	v_pk_mul_f32 v[152:153], v[14:15], v[130:131]
	v_lshrrev_b32_e32 v164, 1, v65
	v_add_f32_e32 v132, v146, v147
	v_and_b32_sdwa v154, v150, v163 dst_sel:DWORD dst_unused:UNUSED_PAD src0_sel:WORD_1 src1_sel:DWORD
	v_and_b32_sdwa v155, v151, v163 dst_sel:DWORD dst_unused:UNUSED_PAD src0_sel:WORD_1 src1_sel:DWORD
	v_and_b32_sdwa v156, v152, v163 dst_sel:DWORD dst_unused:UNUSED_PAD src0_sel:WORD_1 src1_sel:DWORD
	v_and_b32_sdwa v157, v153, v163 dst_sel:DWORD dst_unused:UNUSED_PAD src0_sel:WORD_1 src1_sel:DWORD
	v_add_f32_e32 v132, v132, v148
	v_add3_u32 v150, v150, v154, s12
	v_add3_u32 v151, v151, v155, s12
	v_add3_u32 v152, v152, v156, s12
	v_add3_u32 v153, v153, v157, s12
	v_add_f32_e32 v132, v132, v149
	v_and_b32_e32 v151, 0xffff0000, v151
	v_and_b32_e32 v153, 0xffff0000, v153
	s_nop 0
	v_or_b32_sdwa v158, v151, v150 dst_sel:DWORD dst_unused:UNUSED_PAD src0_sel:DWORD src1_sel:WORD_1
	v_or_b32_sdwa v159, v153, v152 dst_sel:DWORD dst_unused:UNUSED_PAD src0_sel:DWORD src1_sel:WORD_1
	global_store_dwordx2 v164, v[158:159], s[92:93]
	v_add_u32_e32 v74, 0x18000, v64
	global_store_dwordx4 v74, v[16:19], s[80:81]
	v_pk_mul_f32 v[146:147], v[16:17], v[16:17]
	v_pk_mul_f32 v[148:149], v[18:19], v[18:19]
	v_pk_mul_f32 v[150:151], v[16:17], v[128:129]
	v_pk_mul_f32 v[152:153], v[18:19], v[130:131]
	v_lshrrev_b32_e32 v165, 1, v74
	v_add_f32_e32 v133, v146, v147
	v_and_b32_sdwa v154, v150, v163 dst_sel:DWORD dst_unused:UNUSED_PAD src0_sel:WORD_1 src1_sel:DWORD
	v_and_b32_sdwa v155, v151, v163 dst_sel:DWORD dst_unused:UNUSED_PAD src0_sel:WORD_1 src1_sel:DWORD
	v_and_b32_sdwa v156, v152, v163 dst_sel:DWORD dst_unused:UNUSED_PAD src0_sel:WORD_1 src1_sel:DWORD
	v_and_b32_sdwa v157, v153, v163 dst_sel:DWORD dst_unused:UNUSED_PAD src0_sel:WORD_1 src1_sel:DWORD
	v_add_f32_e32 v133, v133, v148
	v_add3_u32 v150, v150, v154, s12
	v_add3_u32 v151, v151, v155, s12
	v_add3_u32 v152, v152, v156, s12
	v_add3_u32 v153, v153, v157, s12
	v_add_f32_e32 v133, v133, v149
	v_and_b32_e32 v151, 0xffff0000, v151
	v_and_b32_e32 v153, 0xffff0000, v153
	s_nop 0
	v_or_b32_sdwa v160, v151, v150 dst_sel:DWORD dst_unused:UNUSED_PAD src0_sel:DWORD src1_sel:WORD_1
	v_or_b32_sdwa v161, v153, v152 dst_sel:DWORD dst_unused:UNUSED_PAD src0_sel:DWORD src1_sel:WORD_1
	global_store_dwordx2 v165, v[160:161], s[92:93]
	s_nop 1
	v_add_f32_dpp v126, v126, v126 quad_perm:[1,0,3,2] row_mask:0xf bank_mask:0xf
	v_add_f32_dpp v127, v127, v127 quad_perm:[1,0,3,2] row_mask:0xf bank_mask:0xf
	v_add_f32_dpp v132, v132, v132 quad_perm:[1,0,3,2] row_mask:0xf bank_mask:0xf
	v_add_f32_dpp v133, v133, v133 quad_perm:[1,0,3,2] row_mask:0xf bank_mask:0xf
	v_add_f32_dpp v126, v126, v126 quad_perm:[2,3,0,1] row_mask:0xf bank_mask:0xf
	v_add_f32_dpp v127, v127, v127 quad_perm:[2,3,0,1] row_mask:0xf bank_mask:0xf
	v_add_f32_dpp v132, v132, v132 quad_perm:[2,3,0,1] row_mask:0xf bank_mask:0xf
	v_add_f32_dpp v133, v133, v133 quad_perm:[2,3,0,1] row_mask:0xf bank_mask:0xf
	v_add_f32_dpp v126, v126, v126 row_half_mirror row_mask:0xf bank_mask:0xf
	v_add_f32_dpp v127, v127, v127 row_half_mirror row_mask:0xf bank_mask:0xf
	v_add_f32_dpp v132, v132, v132 row_half_mirror row_mask:0xf bank_mask:0xf
	v_add_f32_dpp v133, v133, v133 row_half_mirror row_mask:0xf bank_mask:0xf
	v_add_f32_dpp v126, v126, v126 row_mirror row_mask:0xf bank_mask:0xf
	v_add_f32_dpp v127, v127, v127 row_mirror row_mask:0xf bank_mask:0xf
	v_add_f32_dpp v132, v132, v132 row_mirror row_mask:0xf bank_mask:0xf
	v_add_f32_dpp v133, v133, v133 row_mirror row_mask:0xf bank_mask:0xf
	v_add_f32_dpp v126, v126, v126 row_bcast:15 row_mask:0xa bank_mask:0xf
	v_add_f32_dpp v127, v127, v127 row_bcast:15 row_mask:0xa bank_mask:0xf
	v_add_f32_dpp v132, v132, v132 row_bcast:15 row_mask:0xa bank_mask:0xf
	v_add_f32_dpp v133, v133, v133 row_bcast:15 row_mask:0xa bank_mask:0xf
	s_waitcnt vmcnt(19) lgkmcnt(6)
	v_pk_add_f32 v[20:21], v[20:21], v[80:81]
	v_pk_add_f32 v[22:23], v[22:23], v[82:83]
	s_waitcnt vmcnt(18) lgkmcnt(4)
	v_pk_add_f32 v[24:25], v[24:25], v[84:85]
	v_pk_add_f32 v[26:27], v[26:27], v[86:87]
	s_waitcnt vmcnt(17) lgkmcnt(2)
	v_pk_add_f32 v[28:29], v[28:29], v[118:119]
	v_pk_add_f32 v[30:31], v[30:31], v[120:121]
	s_waitcnt vmcnt(16) lgkmcnt(0)
	v_pk_add_f32 v[32:33], v[32:33], v[122:123]
	v_pk_add_f32 v[34:35], v[34:35], v[124:125]
	v_add_u32_e32 v88, 0x8100, v75
	ds_read2_b32 v[80:81], v88 offset1:1
	ds_read2_b32 v[82:83], v88 offset0:2 offset1:3
	v_add_u32_e32 v89, 0x9120, v75
	ds_read2_b32 v[84:85], v89 offset1:1
	ds_read2_b32 v[86:87], v89 offset0:2 offset1:3
	v_add_u32_e32 v88, 0xa140, v75
	ds_read2_b32 v[118:119], v88 offset1:1
	ds_read2_b32 v[120:121], v88 offset0:2 offset1:3
	v_add_u32_e32 v89, 0xb160, v75
	ds_read2_b32 v[122:123], v89 offset1:1
	ds_read2_b32 v[124:125], v89 offset0:2 offset1:3
	v_add_u32_e32 v65, 0x20000, v64
	global_store_dwordx4 v65, v[20:23], s[80:81]
	v_pk_mul_f32 v[146:147], v[20:21], v[20:21]
	v_pk_mul_f32 v[148:149], v[22:23], v[22:23]
	v_pk_mul_f32 v[150:151], v[20:21], v[128:129]
	v_pk_mul_f32 v[152:153], v[22:23], v[130:131]
	v_lshrrev_b32_e32 v164, 1, v65
	v_add_f32_e32 v134, v146, v147
	v_and_b32_sdwa v154, v150, v163 dst_sel:DWORD dst_unused:UNUSED_PAD src0_sel:WORD_1 src1_sel:DWORD
	v_and_b32_sdwa v155, v151, v163 dst_sel:DWORD dst_unused:UNUSED_PAD src0_sel:WORD_1 src1_sel:DWORD
	v_and_b32_sdwa v156, v152, v163 dst_sel:DWORD dst_unused:UNUSED_PAD src0_sel:WORD_1 src1_sel:DWORD
	v_and_b32_sdwa v157, v153, v163 dst_sel:DWORD dst_unused:UNUSED_PAD src0_sel:WORD_1 src1_sel:DWORD
	v_add_f32_e32 v134, v134, v148
	v_add3_u32 v150, v150, v154, s12
	v_add3_u32 v151, v151, v155, s12
	v_add3_u32 v152, v152, v156, s12
	v_add3_u32 v153, v153, v157, s12
	v_add_f32_e32 v134, v134, v149
	v_and_b32_e32 v151, 0xffff0000, v151
	v_and_b32_e32 v153, 0xffff0000, v153
	s_nop 0
	v_or_b32_sdwa v158, v151, v150 dst_sel:DWORD dst_unused:UNUSED_PAD src0_sel:DWORD src1_sel:WORD_1
	v_or_b32_sdwa v159, v153, v152 dst_sel:DWORD dst_unused:UNUSED_PAD src0_sel:DWORD src1_sel:WORD_1
	global_store_dwordx2 v164, v[158:159], s[92:93]
	v_add_u32_e32 v74, 0x28000, v64
	global_store_dwordx4 v74, v[24:27], s[80:81]
	v_pk_mul_f32 v[146:147], v[24:25], v[24:25]
	v_pk_mul_f32 v[148:149], v[26:27], v[26:27]
	v_pk_mul_f32 v[150:151], v[24:25], v[128:129]
	v_pk_mul_f32 v[152:153], v[26:27], v[130:131]
	v_lshrrev_b32_e32 v165, 1, v74
	v_add_f32_e32 v135, v146, v147
	v_and_b32_sdwa v154, v150, v163 dst_sel:DWORD dst_unused:UNUSED_PAD src0_sel:WORD_1 src1_sel:DWORD
	v_and_b32_sdwa v155, v151, v163 dst_sel:DWORD dst_unused:UNUSED_PAD src0_sel:WORD_1 src1_sel:DWORD
	v_and_b32_sdwa v156, v152, v163 dst_sel:DWORD dst_unused:UNUSED_PAD src0_sel:WORD_1 src1_sel:DWORD
	v_and_b32_sdwa v157, v153, v163 dst_sel:DWORD dst_unused:UNUSED_PAD src0_sel:WORD_1 src1_sel:DWORD
	v_add_f32_e32 v135, v135, v148
	v_add3_u32 v150, v150, v154, s12
	v_add3_u32 v151, v151, v155, s12
	v_add3_u32 v152, v152, v156, s12
	v_add3_u32 v153, v153, v157, s12
	v_add_f32_e32 v135, v135, v149
	v_and_b32_e32 v151, 0xffff0000, v151
	v_and_b32_e32 v153, 0xffff0000, v153
	s_nop 0
	v_or_b32_sdwa v160, v151, v150 dst_sel:DWORD dst_unused:UNUSED_PAD src0_sel:DWORD src1_sel:WORD_1
	v_or_b32_sdwa v161, v153, v152 dst_sel:DWORD dst_unused:UNUSED_PAD src0_sel:DWORD src1_sel:WORD_1
	global_store_dwordx2 v165, v[160:161], s[92:93]
	v_add_u32_e32 v65, 0x30000, v64
	global_store_dwordx4 v65, v[28:31], s[80:81]
	v_pk_mul_f32 v[146:147], v[28:29], v[28:29]
	v_pk_mul_f32 v[148:149], v[30:31], v[30:31]
	v_pk_mul_f32 v[150:151], v[28:29], v[128:129]
	v_pk_mul_f32 v[152:153], v[30:31], v[130:131]
	v_lshrrev_b32_e32 v164, 1, v65
	v_add_f32_e32 v136, v146, v147
	v_and_b32_sdwa v154, v150, v163 dst_sel:DWORD dst_unused:UNUSED_PAD src0_sel:WORD_1 src1_sel:DWORD
	v_and_b32_sdwa v155, v151, v163 dst_sel:DWORD dst_unused:UNUSED_PAD src0_sel:WORD_1 src1_sel:DWORD
	v_and_b32_sdwa v156, v152, v163 dst_sel:DWORD dst_unused:UNUSED_PAD src0_sel:WORD_1 src1_sel:DWORD
	v_and_b32_sdwa v157, v153, v163 dst_sel:DWORD dst_unused:UNUSED_PAD src0_sel:WORD_1 src1_sel:DWORD
	v_add_f32_e32 v136, v136, v148
	v_add3_u32 v150, v150, v154, s12
	v_add3_u32 v151, v151, v155, s12
	v_add3_u32 v152, v152, v156, s12
	v_add3_u32 v153, v153, v157, s12
	v_add_f32_e32 v136, v136, v149
	v_and_b32_e32 v151, 0xffff0000, v151
	v_and_b32_e32 v153, 0xffff0000, v153
	s_nop 0
	v_or_b32_sdwa v158, v151, v150 dst_sel:DWORD dst_unused:UNUSED_PAD src0_sel:DWORD src1_sel:WORD_1
	v_or_b32_sdwa v159, v153, v152 dst_sel:DWORD dst_unused:UNUSED_PAD src0_sel:DWORD src1_sel:WORD_1
	global_store_dwordx2 v164, v[158:159], s[92:93]
	v_add_u32_e32 v74, 0x38000, v64
	global_store_dwordx4 v74, v[32:35], s[80:81]
	v_pk_mul_f32 v[146:147], v[32:33], v[32:33]
	v_pk_mul_f32 v[148:149], v[34:35], v[34:35]
	v_pk_mul_f32 v[150:151], v[32:33], v[128:129]
	v_pk_mul_f32 v[152:153], v[34:35], v[130:131]
	v_lshrrev_b32_e32 v165, 1, v74
	v_add_f32_e32 v137, v146, v147
	v_and_b32_sdwa v154, v150, v163 dst_sel:DWORD dst_unused:UNUSED_PAD src0_sel:WORD_1 src1_sel:DWORD
	v_and_b32_sdwa v155, v151, v163 dst_sel:DWORD dst_unused:UNUSED_PAD src0_sel:WORD_1 src1_sel:DWORD
	v_and_b32_sdwa v156, v152, v163 dst_sel:DWORD dst_unused:UNUSED_PAD src0_sel:WORD_1 src1_sel:DWORD
	v_and_b32_sdwa v157, v153, v163 dst_sel:DWORD dst_unused:UNUSED_PAD src0_sel:WORD_1 src1_sel:DWORD
	v_add_f32_e32 v137, v137, v148
	v_add3_u32 v150, v150, v154, s12
	v_add3_u32 v151, v151, v155, s12
	v_add3_u32 v152, v152, v156, s12
	v_add3_u32 v153, v153, v157, s12
	v_add_f32_e32 v137, v137, v149
	v_and_b32_e32 v151, 0xffff0000, v151
	v_and_b32_e32 v153, 0xffff0000, v153
	s_nop 0
	v_or_b32_sdwa v160, v151, v150 dst_sel:DWORD dst_unused:UNUSED_PAD src0_sel:DWORD src1_sel:WORD_1
	v_or_b32_sdwa v161, v153, v152 dst_sel:DWORD dst_unused:UNUSED_PAD src0_sel:DWORD src1_sel:WORD_1
	global_store_dwordx2 v165, v[160:161], s[92:93]
	s_nop 1
	v_add_f32_dpp v134, v134, v134 quad_perm:[1,0,3,2] row_mask:0xf bank_mask:0xf
	v_add_f32_dpp v135, v135, v135 quad_perm:[1,0,3,2] row_mask:0xf bank_mask:0xf
	v_add_f32_dpp v136, v136, v136 quad_perm:[1,0,3,2] row_mask:0xf bank_mask:0xf
	v_add_f32_dpp v137, v137, v137 quad_perm:[1,0,3,2] row_mask:0xf bank_mask:0xf
	v_add_f32_dpp v134, v134, v134 quad_perm:[2,3,0,1] row_mask:0xf bank_mask:0xf
	v_add_f32_dpp v135, v135, v135 quad_perm:[2,3,0,1] row_mask:0xf bank_mask:0xf
	v_add_f32_dpp v136, v136, v136 quad_perm:[2,3,0,1] row_mask:0xf bank_mask:0xf
	v_add_f32_dpp v137, v137, v137 quad_perm:[2,3,0,1] row_mask:0xf bank_mask:0xf
	v_add_f32_dpp v134, v134, v134 row_half_mirror row_mask:0xf bank_mask:0xf
	v_add_f32_dpp v135, v135, v135 row_half_mirror row_mask:0xf bank_mask:0xf
	v_add_f32_dpp v136, v136, v136 row_half_mirror row_mask:0xf bank_mask:0xf
	v_add_f32_dpp v137, v137, v137 row_half_mirror row_mask:0xf bank_mask:0xf
	v_add_f32_dpp v134, v134, v134 row_mirror row_mask:0xf bank_mask:0xf
	v_add_f32_dpp v135, v135, v135 row_mirror row_mask:0xf bank_mask:0xf
	v_add_f32_dpp v136, v136, v136 row_mirror row_mask:0xf bank_mask:0xf
	v_add_f32_dpp v137, v137, v137 row_mirror row_mask:0xf bank_mask:0xf
	v_add_f32_dpp v134, v134, v134 row_bcast:15 row_mask:0xa bank_mask:0xf
	v_add_f32_dpp v135, v135, v135 row_bcast:15 row_mask:0xa bank_mask:0xf
	v_add_f32_dpp v136, v136, v136 row_bcast:15 row_mask:0xa bank_mask:0xf
	v_add_f32_dpp v137, v137, v137 row_bcast:15 row_mask:0xa bank_mask:0xf
	s_waitcnt vmcnt(23) lgkmcnt(6)
	v_pk_add_f32 v[36:37], v[36:37], v[80:81]
	v_pk_add_f32 v[38:39], v[38:39], v[82:83]
	s_waitcnt vmcnt(22) lgkmcnt(4)
	v_pk_add_f32 v[40:41], v[40:41], v[84:85]
	v_pk_add_f32 v[42:43], v[42:43], v[86:87]
	s_waitcnt vmcnt(21) lgkmcnt(2)
	v_pk_add_f32 v[44:45], v[44:45], v[118:119]
	v_pk_add_f32 v[46:47], v[46:47], v[120:121]
	s_waitcnt vmcnt(20) lgkmcnt(0)
	v_pk_add_f32 v[48:49], v[48:49], v[122:123]
	v_pk_add_f32 v[50:51], v[50:51], v[124:125]
	v_add_u32_e32 v88, 0xc180, v75
	ds_read2_b32 v[80:81], v88 offset1:1
	ds_read2_b32 v[82:83], v88 offset0:2 offset1:3
	v_add_u32_e32 v89, 0xd1a0, v75
	ds_read2_b32 v[84:85], v89 offset1:1
	ds_read2_b32 v[86:87], v89 offset0:2 offset1:3
	v_add_u32_e32 v88, 0xe1c0, v75
	ds_read2_b32 v[118:119], v88 offset1:1
	ds_read2_b32 v[120:121], v88 offset0:2 offset1:3
	v_add_u32_e32 v89, 0xf1e0, v75
	ds_read2_b32 v[122:123], v89 offset1:1
	ds_read2_b32 v[124:125], v89 offset0:2 offset1:3
	v_add_u32_e32 v65, 0x40000, v64
	global_store_dwordx4 v65, v[36:39], s[80:81]
	v_pk_mul_f32 v[146:147], v[36:37], v[36:37]
	v_pk_mul_f32 v[148:149], v[38:39], v[38:39]
	v_pk_mul_f32 v[150:151], v[36:37], v[128:129]
	v_pk_mul_f32 v[152:153], v[38:39], v[130:131]
	v_lshrrev_b32_e32 v164, 1, v65
	v_add_f32_e32 v138, v146, v147
	v_and_b32_sdwa v154, v150, v163 dst_sel:DWORD dst_unused:UNUSED_PAD src0_sel:WORD_1 src1_sel:DWORD
	v_and_b32_sdwa v155, v151, v163 dst_sel:DWORD dst_unused:UNUSED_PAD src0_sel:WORD_1 src1_sel:DWORD
	v_and_b32_sdwa v156, v152, v163 dst_sel:DWORD dst_unused:UNUSED_PAD src0_sel:WORD_1 src1_sel:DWORD
	v_and_b32_sdwa v157, v153, v163 dst_sel:DWORD dst_unused:UNUSED_PAD src0_sel:WORD_1 src1_sel:DWORD
	v_add_f32_e32 v138, v138, v148
	v_add3_u32 v150, v150, v154, s12
	v_add3_u32 v151, v151, v155, s12
	v_add3_u32 v152, v152, v156, s12
	v_add3_u32 v153, v153, v157, s12
	v_add_f32_e32 v138, v138, v149
	v_and_b32_e32 v151, 0xffff0000, v151
	v_and_b32_e32 v153, 0xffff0000, v153
	s_nop 0
	v_or_b32_sdwa v158, v151, v150 dst_sel:DWORD dst_unused:UNUSED_PAD src0_sel:DWORD src1_sel:WORD_1
	v_or_b32_sdwa v159, v153, v152 dst_sel:DWORD dst_unused:UNUSED_PAD src0_sel:DWORD src1_sel:WORD_1
	global_store_dwordx2 v164, v[158:159], s[92:93]
	v_add_u32_e32 v74, 0x48000, v64
	global_store_dwordx4 v74, v[40:43], s[80:81]
	v_pk_mul_f32 v[146:147], v[40:41], v[40:41]
	v_pk_mul_f32 v[148:149], v[42:43], v[42:43]
	v_pk_mul_f32 v[150:151], v[40:41], v[128:129]
	v_pk_mul_f32 v[152:153], v[42:43], v[130:131]
	v_lshrrev_b32_e32 v165, 1, v74
	v_add_f32_e32 v139, v146, v147
	v_and_b32_sdwa v154, v150, v163 dst_sel:DWORD dst_unused:UNUSED_PAD src0_sel:WORD_1 src1_sel:DWORD
	v_and_b32_sdwa v155, v151, v163 dst_sel:DWORD dst_unused:UNUSED_PAD src0_sel:WORD_1 src1_sel:DWORD
	v_and_b32_sdwa v156, v152, v163 dst_sel:DWORD dst_unused:UNUSED_PAD src0_sel:WORD_1 src1_sel:DWORD
	v_and_b32_sdwa v157, v153, v163 dst_sel:DWORD dst_unused:UNUSED_PAD src0_sel:WORD_1 src1_sel:DWORD
	v_add_f32_e32 v139, v139, v148
	v_add3_u32 v150, v150, v154, s12
	v_add3_u32 v151, v151, v155, s12
	v_add3_u32 v152, v152, v156, s12
	v_add3_u32 v153, v153, v157, s12
	v_add_f32_e32 v139, v139, v149
	v_and_b32_e32 v151, 0xffff0000, v151
	v_and_b32_e32 v153, 0xffff0000, v153
	s_nop 0
	v_or_b32_sdwa v160, v151, v150 dst_sel:DWORD dst_unused:UNUSED_PAD src0_sel:DWORD src1_sel:WORD_1
	v_or_b32_sdwa v161, v153, v152 dst_sel:DWORD dst_unused:UNUSED_PAD src0_sel:DWORD src1_sel:WORD_1
	global_store_dwordx2 v165, v[160:161], s[92:93]
	v_add_u32_e32 v65, 0x50000, v64
	global_store_dwordx4 v65, v[44:47], s[80:81]
	v_pk_mul_f32 v[146:147], v[44:45], v[44:45]
	v_pk_mul_f32 v[148:149], v[46:47], v[46:47]
	v_pk_mul_f32 v[150:151], v[44:45], v[128:129]
	v_pk_mul_f32 v[152:153], v[46:47], v[130:131]
	v_lshrrev_b32_e32 v164, 1, v65
	v_add_f32_e32 v140, v146, v147
	v_and_b32_sdwa v154, v150, v163 dst_sel:DWORD dst_unused:UNUSED_PAD src0_sel:WORD_1 src1_sel:DWORD
	v_and_b32_sdwa v155, v151, v163 dst_sel:DWORD dst_unused:UNUSED_PAD src0_sel:WORD_1 src1_sel:DWORD
	v_and_b32_sdwa v156, v152, v163 dst_sel:DWORD dst_unused:UNUSED_PAD src0_sel:WORD_1 src1_sel:DWORD
	v_and_b32_sdwa v157, v153, v163 dst_sel:DWORD dst_unused:UNUSED_PAD src0_sel:WORD_1 src1_sel:DWORD
	v_add_f32_e32 v140, v140, v148
	v_add3_u32 v150, v150, v154, s12
	v_add3_u32 v151, v151, v155, s12
	v_add3_u32 v152, v152, v156, s12
	v_add3_u32 v153, v153, v157, s12
	v_add_f32_e32 v140, v140, v149
	v_and_b32_e32 v151, 0xffff0000, v151
	v_and_b32_e32 v153, 0xffff0000, v153
	s_nop 0
	v_or_b32_sdwa v158, v151, v150 dst_sel:DWORD dst_unused:UNUSED_PAD src0_sel:DWORD src1_sel:WORD_1
	v_or_b32_sdwa v159, v153, v152 dst_sel:DWORD dst_unused:UNUSED_PAD src0_sel:DWORD src1_sel:WORD_1
	global_store_dwordx2 v164, v[158:159], s[92:93]
	v_add_u32_e32 v74, 0x58000, v64
	global_store_dwordx4 v74, v[48:51], s[80:81]
	v_pk_mul_f32 v[146:147], v[48:49], v[48:49]
	v_pk_mul_f32 v[148:149], v[50:51], v[50:51]
	v_pk_mul_f32 v[150:151], v[48:49], v[128:129]
	v_pk_mul_f32 v[152:153], v[50:51], v[130:131]
	v_lshrrev_b32_e32 v165, 1, v74
	v_add_f32_e32 v141, v146, v147
	v_and_b32_sdwa v154, v150, v163 dst_sel:DWORD dst_unused:UNUSED_PAD src0_sel:WORD_1 src1_sel:DWORD
	v_and_b32_sdwa v155, v151, v163 dst_sel:DWORD dst_unused:UNUSED_PAD src0_sel:WORD_1 src1_sel:DWORD
	v_and_b32_sdwa v156, v152, v163 dst_sel:DWORD dst_unused:UNUSED_PAD src0_sel:WORD_1 src1_sel:DWORD
	v_and_b32_sdwa v157, v153, v163 dst_sel:DWORD dst_unused:UNUSED_PAD src0_sel:WORD_1 src1_sel:DWORD
	v_add_f32_e32 v141, v141, v148
	v_add3_u32 v150, v150, v154, s12
	v_add3_u32 v151, v151, v155, s12
	v_add3_u32 v152, v152, v156, s12
	v_add3_u32 v153, v153, v157, s12
	v_add_f32_e32 v141, v141, v149
	v_and_b32_e32 v151, 0xffff0000, v151
	v_and_b32_e32 v153, 0xffff0000, v153
	s_nop 0
	v_or_b32_sdwa v160, v151, v150 dst_sel:DWORD dst_unused:UNUSED_PAD src0_sel:DWORD src1_sel:WORD_1
	v_or_b32_sdwa v161, v153, v152 dst_sel:DWORD dst_unused:UNUSED_PAD src0_sel:DWORD src1_sel:WORD_1
	global_store_dwordx2 v165, v[160:161], s[92:93]
	s_nop 1
	v_add_f32_dpp v138, v138, v138 quad_perm:[1,0,3,2] row_mask:0xf bank_mask:0xf
	v_add_f32_dpp v139, v139, v139 quad_perm:[1,0,3,2] row_mask:0xf bank_mask:0xf
	v_add_f32_dpp v140, v140, v140 quad_perm:[1,0,3,2] row_mask:0xf bank_mask:0xf
	v_add_f32_dpp v141, v141, v141 quad_perm:[1,0,3,2] row_mask:0xf bank_mask:0xf
	v_add_f32_dpp v138, v138, v138 quad_perm:[2,3,0,1] row_mask:0xf bank_mask:0xf
	v_add_f32_dpp v139, v139, v139 quad_perm:[2,3,0,1] row_mask:0xf bank_mask:0xf
	v_add_f32_dpp v140, v140, v140 quad_perm:[2,3,0,1] row_mask:0xf bank_mask:0xf
	v_add_f32_dpp v141, v141, v141 quad_perm:[2,3,0,1] row_mask:0xf bank_mask:0xf
	v_add_f32_dpp v138, v138, v138 row_half_mirror row_mask:0xf bank_mask:0xf
	v_add_f32_dpp v139, v139, v139 row_half_mirror row_mask:0xf bank_mask:0xf
	v_add_f32_dpp v140, v140, v140 row_half_mirror row_mask:0xf bank_mask:0xf
	v_add_f32_dpp v141, v141, v141 row_half_mirror row_mask:0xf bank_mask:0xf
	v_add_f32_dpp v138, v138, v138 row_mirror row_mask:0xf bank_mask:0xf
	v_add_f32_dpp v139, v139, v139 row_mirror row_mask:0xf bank_mask:0xf
	v_add_f32_dpp v140, v140, v140 row_mirror row_mask:0xf bank_mask:0xf
	v_add_f32_dpp v141, v141, v141 row_mirror row_mask:0xf bank_mask:0xf
	v_add_f32_dpp v138, v138, v138 row_bcast:15 row_mask:0xa bank_mask:0xf
	v_add_f32_dpp v139, v139, v139 row_bcast:15 row_mask:0xa bank_mask:0xf
	v_add_f32_dpp v140, v140, v140 row_bcast:15 row_mask:0xa bank_mask:0xf
	v_add_f32_dpp v141, v141, v141 row_bcast:15 row_mask:0xa bank_mask:0xf
	s_waitcnt vmcnt(27) lgkmcnt(6)
	v_pk_add_f32 v[52:53], v[52:53], v[80:81]
	v_pk_add_f32 v[54:55], v[54:55], v[82:83]
	s_waitcnt vmcnt(26) lgkmcnt(4)
	v_pk_add_f32 v[56:57], v[56:57], v[84:85]
	v_pk_add_f32 v[58:59], v[58:59], v[86:87]
	s_waitcnt vmcnt(25) lgkmcnt(2)
	v_pk_add_f32 v[60:61], v[60:61], v[118:119]
	v_pk_add_f32 v[62:63], v[62:63], v[120:121]
	s_waitcnt vmcnt(24) lgkmcnt(0)
	v_pk_add_f32 v[76:77], v[76:77], v[122:123]
	v_pk_add_f32 v[78:79], v[78:79], v[124:125]
	v_add_u32_e32 v65, 0x60000, v64
	global_store_dwordx4 v65, v[52:55], s[80:81]
	v_pk_mul_f32 v[146:147], v[52:53], v[52:53]
	v_pk_mul_f32 v[148:149], v[54:55], v[54:55]
	v_pk_mul_f32 v[150:151], v[52:53], v[128:129]
	v_pk_mul_f32 v[152:153], v[54:55], v[130:131]
	v_lshrrev_b32_e32 v164, 1, v65
	v_add_f32_e32 v142, v146, v147
	v_and_b32_sdwa v154, v150, v163 dst_sel:DWORD dst_unused:UNUSED_PAD src0_sel:WORD_1 src1_sel:DWORD
	v_and_b32_sdwa v155, v151, v163 dst_sel:DWORD dst_unused:UNUSED_PAD src0_sel:WORD_1 src1_sel:DWORD
	v_and_b32_sdwa v156, v152, v163 dst_sel:DWORD dst_unused:UNUSED_PAD src0_sel:WORD_1 src1_sel:DWORD
	v_and_b32_sdwa v157, v153, v163 dst_sel:DWORD dst_unused:UNUSED_PAD src0_sel:WORD_1 src1_sel:DWORD
	v_add_f32_e32 v142, v142, v148
	v_add3_u32 v150, v150, v154, s12
	v_add3_u32 v151, v151, v155, s12
	v_add3_u32 v152, v152, v156, s12
	v_add3_u32 v153, v153, v157, s12
	v_add_f32_e32 v142, v142, v149
	v_and_b32_e32 v151, 0xffff0000, v151
	v_and_b32_e32 v153, 0xffff0000, v153
	s_nop 0
	v_or_b32_sdwa v158, v151, v150 dst_sel:DWORD dst_unused:UNUSED_PAD src0_sel:DWORD src1_sel:WORD_1
	v_or_b32_sdwa v159, v153, v152 dst_sel:DWORD dst_unused:UNUSED_PAD src0_sel:DWORD src1_sel:WORD_1
	global_store_dwordx2 v164, v[158:159], s[92:93]
	v_add_u32_e32 v74, 0x68000, v64
	global_store_dwordx4 v74, v[56:59], s[80:81]
	v_pk_mul_f32 v[146:147], v[56:57], v[56:57]
	v_pk_mul_f32 v[148:149], v[58:59], v[58:59]
	v_pk_mul_f32 v[150:151], v[56:57], v[128:129]
	v_pk_mul_f32 v[152:153], v[58:59], v[130:131]
	v_lshrrev_b32_e32 v165, 1, v74
	v_add_f32_e32 v143, v146, v147
	v_and_b32_sdwa v154, v150, v163 dst_sel:DWORD dst_unused:UNUSED_PAD src0_sel:WORD_1 src1_sel:DWORD
	v_and_b32_sdwa v155, v151, v163 dst_sel:DWORD dst_unused:UNUSED_PAD src0_sel:WORD_1 src1_sel:DWORD
	v_and_b32_sdwa v156, v152, v163 dst_sel:DWORD dst_unused:UNUSED_PAD src0_sel:WORD_1 src1_sel:DWORD
	v_and_b32_sdwa v157, v153, v163 dst_sel:DWORD dst_unused:UNUSED_PAD src0_sel:WORD_1 src1_sel:DWORD
	v_add_f32_e32 v143, v143, v148
	v_add3_u32 v150, v150, v154, s12
	v_add3_u32 v151, v151, v155, s12
	v_add3_u32 v152, v152, v156, s12
	v_add3_u32 v153, v153, v157, s12
	v_add_f32_e32 v143, v143, v149
	v_and_b32_e32 v151, 0xffff0000, v151
	v_and_b32_e32 v153, 0xffff0000, v153
	s_nop 0
	v_or_b32_sdwa v160, v151, v150 dst_sel:DWORD dst_unused:UNUSED_PAD src0_sel:DWORD src1_sel:WORD_1
	v_or_b32_sdwa v161, v153, v152 dst_sel:DWORD dst_unused:UNUSED_PAD src0_sel:DWORD src1_sel:WORD_1
	global_store_dwordx2 v165, v[160:161], s[92:93]
	v_add_u32_e32 v65, 0x70000, v64
	global_store_dwordx4 v65, v[60:63], s[80:81]
	v_pk_mul_f32 v[146:147], v[60:61], v[60:61]
	v_pk_mul_f32 v[148:149], v[62:63], v[62:63]
	v_pk_mul_f32 v[150:151], v[60:61], v[128:129]
	v_pk_mul_f32 v[152:153], v[62:63], v[130:131]
	v_lshrrev_b32_e32 v164, 1, v65
	v_add_f32_e32 v144, v146, v147
	v_and_b32_sdwa v154, v150, v163 dst_sel:DWORD dst_unused:UNUSED_PAD src0_sel:WORD_1 src1_sel:DWORD
	v_and_b32_sdwa v155, v151, v163 dst_sel:DWORD dst_unused:UNUSED_PAD src0_sel:WORD_1 src1_sel:DWORD
	v_and_b32_sdwa v156, v152, v163 dst_sel:DWORD dst_unused:UNUSED_PAD src0_sel:WORD_1 src1_sel:DWORD
	v_and_b32_sdwa v157, v153, v163 dst_sel:DWORD dst_unused:UNUSED_PAD src0_sel:WORD_1 src1_sel:DWORD
	v_add_f32_e32 v144, v144, v148
	v_add3_u32 v150, v150, v154, s12
	v_add3_u32 v151, v151, v155, s12
	v_add3_u32 v152, v152, v156, s12
	v_add3_u32 v153, v153, v157, s12
	v_add_f32_e32 v144, v144, v149
	v_and_b32_e32 v151, 0xffff0000, v151
	v_and_b32_e32 v153, 0xffff0000, v153
	s_nop 0
	v_or_b32_sdwa v158, v151, v150 dst_sel:DWORD dst_unused:UNUSED_PAD src0_sel:DWORD src1_sel:WORD_1
	v_or_b32_sdwa v159, v153, v152 dst_sel:DWORD dst_unused:UNUSED_PAD src0_sel:DWORD src1_sel:WORD_1
	global_store_dwordx2 v164, v[158:159], s[92:93]
	v_add_u32_e32 v74, 0x78000, v64
	global_store_dwordx4 v74, v[76:79], s[80:81]
	v_pk_mul_f32 v[146:147], v[76:77], v[76:77]
	v_pk_mul_f32 v[148:149], v[78:79], v[78:79]
	v_pk_mul_f32 v[150:151], v[76:77], v[128:129]
	v_pk_mul_f32 v[152:153], v[78:79], v[130:131]
	v_lshrrev_b32_e32 v165, 1, v74
	v_add_f32_e32 v145, v146, v147
	v_and_b32_sdwa v154, v150, v163 dst_sel:DWORD dst_unused:UNUSED_PAD src0_sel:WORD_1 src1_sel:DWORD
	v_and_b32_sdwa v155, v151, v163 dst_sel:DWORD dst_unused:UNUSED_PAD src0_sel:WORD_1 src1_sel:DWORD
	v_and_b32_sdwa v156, v152, v163 dst_sel:DWORD dst_unused:UNUSED_PAD src0_sel:WORD_1 src1_sel:DWORD
	v_and_b32_sdwa v157, v153, v163 dst_sel:DWORD dst_unused:UNUSED_PAD src0_sel:WORD_1 src1_sel:DWORD
	v_add_f32_e32 v145, v145, v148
	v_add3_u32 v150, v150, v154, s12
	v_add3_u32 v151, v151, v155, s12
	v_add3_u32 v152, v152, v156, s12
	v_add3_u32 v153, v153, v157, s12
	v_add_f32_e32 v145, v145, v149
	v_and_b32_e32 v151, 0xffff0000, v151
	v_and_b32_e32 v153, 0xffff0000, v153
	s_nop 0
	v_or_b32_sdwa v160, v151, v150 dst_sel:DWORD dst_unused:UNUSED_PAD src0_sel:DWORD src1_sel:WORD_1
	v_or_b32_sdwa v161, v153, v152 dst_sel:DWORD dst_unused:UNUSED_PAD src0_sel:DWORD src1_sel:WORD_1
	global_store_dwordx2 v165, v[160:161], s[92:93]
	s_nop 1
	v_add_f32_dpp v142, v142, v142 quad_perm:[1,0,3,2] row_mask:0xf bank_mask:0xf
	v_add_f32_dpp v143, v143, v143 quad_perm:[1,0,3,2] row_mask:0xf bank_mask:0xf
	v_add_f32_dpp v144, v144, v144 quad_perm:[1,0,3,2] row_mask:0xf bank_mask:0xf
	v_add_f32_dpp v145, v145, v145 quad_perm:[1,0,3,2] row_mask:0xf bank_mask:0xf
	v_add_f32_dpp v142, v142, v142 quad_perm:[2,3,0,1] row_mask:0xf bank_mask:0xf
	v_add_f32_dpp v143, v143, v143 quad_perm:[2,3,0,1] row_mask:0xf bank_mask:0xf
	v_add_f32_dpp v144, v144, v144 quad_perm:[2,3,0,1] row_mask:0xf bank_mask:0xf
	v_add_f32_dpp v145, v145, v145 quad_perm:[2,3,0,1] row_mask:0xf bank_mask:0xf
	v_add_f32_dpp v142, v142, v142 row_half_mirror row_mask:0xf bank_mask:0xf
	v_add_f32_dpp v143, v143, v143 row_half_mirror row_mask:0xf bank_mask:0xf
	v_add_f32_dpp v144, v144, v144 row_half_mirror row_mask:0xf bank_mask:0xf
	v_add_f32_dpp v145, v145, v145 row_half_mirror row_mask:0xf bank_mask:0xf
	v_add_f32_dpp v142, v142, v142 row_mirror row_mask:0xf bank_mask:0xf
	v_add_f32_dpp v143, v143, v143 row_mirror row_mask:0xf bank_mask:0xf
	v_add_f32_dpp v144, v144, v144 row_mirror row_mask:0xf bank_mask:0xf
	v_add_f32_dpp v145, v145, v145 row_mirror row_mask:0xf bank_mask:0xf
	v_add_f32_dpp v142, v142, v142 row_bcast:15 row_mask:0xa bank_mask:0xf
	v_add_f32_dpp v143, v143, v143 row_bcast:15 row_mask:0xa bank_mask:0xf
	v_add_f32_dpp v144, v144, v144 row_bcast:15 row_mask:0xa bank_mask:0xf
	v_add_f32_dpp v145, v145, v145 row_bcast:15 row_mask:0xa bank_mask:0xf
	s_nop 1
	s_mov_b32 exec_lo, 0x80000000
	s_mov_b32 exec_hi, 0x80000000
	global_atomic_add_f32 v162, v126, s[10:11]
	global_atomic_add_f32 v162, v127, s[10:11] offset:32
	global_atomic_add_f32 v162, v132, s[10:11] offset:64
	global_atomic_add_f32 v162, v133, s[10:11] offset:96
	global_atomic_add_f32 v162, v134, s[10:11] offset:128
	global_atomic_add_f32 v162, v135, s[10:11] offset:160
	global_atomic_add_f32 v162, v136, s[10:11] offset:192
	global_atomic_add_f32 v162, v137, s[10:11] offset:224
	global_atomic_add_f32 v162, v138, s[10:11] offset:256
	global_atomic_add_f32 v162, v139, s[10:11] offset:288
	global_atomic_add_f32 v162, v140, s[10:11] offset:320
	global_atomic_add_f32 v162, v141, s[10:11] offset:352
	global_atomic_add_f32 v162, v142, s[10:11] offset:384
	global_atomic_add_f32 v162, v143, s[10:11] offset:416
	global_atomic_add_f32 v162, v144, s[10:11] offset:448
	global_atomic_add_f32 v162, v145, s[10:11] offset:480
	s_mov_b64 exec, -1
	s_branch .LBB0_562
